# GU GEMM sum-of-squares dedup across the 4 waves sharing token rows (LDS exchange); EPI_RES epilogue: 8 xb row loads per round issued together with counted vmcnt instead of load-wait-store chain
# speedup vs baseline: 1.0269x; 1.0269x over previous
; DI float bflo(unsigned u) { return __uint_as_float(u << 16); }
; DI float bfhi(unsigned u) { return __uint_as_float(u & 0xffff0000u); }
; template <int EPI, bool RS>
; DI void gemm_epilogue(unsigned char* smem, f32x16 (&acc)[2][4], const float (&ssq)[4], int K, int m0, int nt256, const EpiArgs& ea, int wt, int wf, int r, int h) {
;     ...
;       __syncthreads();
; #pragma unroll
;       for (int i = 0; i < 8; ++i) {
;         const int c = tid + NTHR * i, row = c >> 5, kc = c & 31;
;         const u32x4 d = *(const u32x4*)(es + row * EP + kc * 16);
;         const size_t off = (size_t)(m0 + hf * 128 + row) * 1024 + nt256 * 256 + kc * 8;
;         const u32x4 xo = *(const u32x4*)(ea.XB + off);
;         float xn[8];
; #pragma unroll
;         for (int j = 0; j < 4; ++j) { xn[2 * j] = bflo(xo[j]) + bflo(d[j]); xn[2 * j + 1] = bfhi(xo[j]) + bfhi(d[j]); }
;         if (ea.X) {
;           f32x4 o0 = {xn[0], xn[1], xn[2], xn[3]}, o1 = {xn[4], xn[5], xn[6], xn[7]};
;           __builtin_nontemporal_store(o0, (f32x4*)(ea.X + off)); __builtin_nontemporal_store(o1, (f32x4*)(ea.X + off + 4));
;         } else {
;           u32x4 w;
; #pragma unroll
;           for (int j = 0; j < 4; ++j) w[j] = pk2(xn[2 * j], xn[2 * j + 1]);
;           *(u32x4*)(ea.XB + off) = w;
.LBB0_186:
	s_or_b64 exec, exec, s[6:7]
	v_add_u32_e32 v0, v223, v234
	v_lshl_add_u32 v60, v0, 5, v233
	v_and_b32_e32 v0, 31, v233
	s_lshl_b32 s0, s33, 8
	v_ashrrev_i32_e32 v30, 5, v60
	v_lshl_add_u32 v61, v0, 4, s35
	v_lshl_or_b32 v8, v0, 3, s0
	v_mul_lo_u32 v0, v30, s29
	v_add_u32_e32 v31, v61, v0
	v_add_u32_e32 v0, s59, v30
	s_ashr_i32 s1, s0, 31
	v_ashrrev_i32_e32 v1, 31, v0
	v_mov_b32_e32 v9, s1
	v_lshlrev_b64 v[0:1], 10, v[0:1]
	v_lshl_add_u64 v[14:15], v[0:1], 0, v[8:9]
	v_lshl_add_u64 v[12:13], v[14:15], 1, s[62:63]
	s_mov_b64 s[100:101], 0x8000
	global_load_dwordx4 v[84:87], v[12:13], off
	v_lshl_add_u64 v[236:237], v[12:13], 0, s[100:101]
	global_load_dwordx4 v[88:91], v[236:237], off
	v_lshl_add_u64 v[236:237], v[236:237], 0, s[100:101]
	global_load_dwordx4 v[92:95], v[236:237], off
	v_lshl_add_u64 v[236:237], v[236:237], 0, s[100:101]
	global_load_dwordx4 v[96:99], v[236:237], off
	v_lshl_add_u64 v[236:237], v[236:237], 0, s[100:101]
	global_load_dwordx4 v[100:103], v[236:237], off
	v_lshl_add_u64 v[236:237], v[236:237], 0, s[100:101]
	global_load_dwordx4 v[104:107], v[236:237], off
	v_lshl_add_u64 v[236:237], v[236:237], 0, s[100:101]
	global_load_dwordx4 v[108:111], v[236:237], off
	v_lshl_add_u64 v[236:237], v[236:237], 0, s[100:101]
	global_load_dwordx4 v[124:127], v[236:237], off
	s_waitcnt lgkmcnt(0)
	s_barrier
	ds_read_b128 v[4:7], v31
	s_and_b64 vcc, exec, s[10:11]
	s_waitcnt lgkmcnt(0)
	v_lshlrev_b32_e32 v2, 16, v4
	v_and_b32_e32 v3, 0xffff0000, v4
	v_lshlrev_b32_e32 v4, 16, v5
	v_and_b32_e32 v5, 0xffff0000, v5
	s_waitcnt vmcnt(7)
	v_mov_b32_e32 v48, v84
	v_mov_b32_e32 v49, v85
	v_mov_b32_e32 v50, v86
	v_mov_b32_e32 v51, v87
	v_lshlrev_b32_e32 v0, 16, v48
	v_and_b32_e32 v1, 0xffff0000, v48
	v_pk_add_f32 v[0:1], v[2:3], v[0:1]
	v_lshlrev_b32_e32 v2, 16, v49
	v_and_b32_e32 v3, 0xffff0000, v49
	v_pk_add_f32 v[2:3], v[4:5], v[2:3]
	v_lshlrev_b32_e32 v4, 16, v50
	v_and_b32_e32 v5, 0xffff0000, v50
	v_lshlrev_b32_e32 v48, 16, v6
	v_and_b32_e32 v49, 0xffff0000, v6
	v_pk_add_f32 v[4:5], v[48:49], v[4:5]
	v_lshlrev_b32_e32 v48, 16, v51
	v_and_b32_e32 v49, 0xffff0000, v51
	v_lshlrev_b32_e32 v6, 16, v7
	v_and_b32_e32 v7, 0xffff0000, v7
	v_pk_add_f32 v[6:7], v[6:7], v[48:49]
	s_cbranch_vccz .LBB0_235
	v_lshl_add_u64 v[14:15], v[14:15], 2, s[8:9]
	global_store_dwordx4 v[14:15], v[0:3], off nt
	global_store_dwordx4 v[14:15], v[4:7], off offset:16 nt
	s_cbranch_execnz .LBB0_189

; DI float bflo(unsigned u) { return __uint_as_float(u << 16); }
; DI float bfhi(unsigned u) { return __uint_as_float(u & 0xffff0000u); }
; template <int EPI, bool RS>
; DI void gemm_epilogue(unsigned char* smem, f32x16 (&acc)[2][4], const float (&ssq)[4], int K, int m0, int nt256, const EpiArgs& ea, int wt, int wf, int r, int h) {
;     ...
; #pragma unroll
;       for (int i = 0; i < 8; ++i) {
;         const int c = tid + NTHR * i, row = c >> 5, kc = c & 31;
;         const u32x4 d = *(const u32x4*)(es + row * EP + kc * 16);
;         const size_t off = (size_t)(m0 + hf * 128 + row) * 1024 + nt256 * 256 + kc * 8;
;         const u32x4 xo = *(const u32x4*)(ea.XB + off);
;         float xn[8];
; #pragma unroll
;         for (int j = 0; j < 4; ++j) { xn[2 * j] = bflo(xo[j]) + bflo(d[j]); xn[2 * j + 1] = bfhi(xo[j]) + bfhi(d[j]); }
;         if (ea.X) {
;           f32x4 o0 = {xn[0], xn[1], xn[2], xn[3]}, o1 = {xn[4], xn[5], xn[6], xn[7]};
;           __builtin_nontemporal_store(o0, (f32x4*)(ea.X + off)); __builtin_nontemporal_store(o1, (f32x4*)(ea.X + off + 4));
;         } else {
;           u32x4 w;
; #pragma unroll
;           for (int j = 0; j < 4; ++j) w[j] = pk2(xn[2 * j], xn[2 * j + 1]);
;           *(u32x4*)(ea.XB + off) = w;
.LBB0_189:
	s_nop 1
	v_add_u32_e32 v0, 0x200, v60
	v_ashrrev_i32_e32 v48, 5, v0
	v_mul_lo_u32 v0, v48, s29
	v_add_u32_e32 v49, v61, v0
	v_add_u32_e32 v0, s59, v48
	v_ashrrev_i32_e32 v1, 31, v0
	v_lshlrev_b64 v[0:1], 10, v[0:1]
	v_lshl_add_u64 v[14:15], v[0:1], 0, v[8:9]
	v_lshl_add_u64 v[12:13], v[14:15], 1, s[62:63]
	ds_read_b128 v[4:7], v49
	s_andn2_b64 vcc, exec, s[10:11]
	s_waitcnt lgkmcnt(0)
	v_lshlrev_b32_e32 v2, 16, v4
	v_and_b32_e32 v3, 0xffff0000, v4
	v_lshlrev_b32_e32 v4, 16, v5
	v_and_b32_e32 v5, 0xffff0000, v5
	s_waitcnt vmcnt(7)
	v_mov_b32_e32 v50, v88
	v_mov_b32_e32 v51, v89
	v_mov_b32_e32 v52, v90
	v_mov_b32_e32 v53, v91
	v_lshlrev_b32_e32 v0, 16, v50
	v_and_b32_e32 v1, 0xffff0000, v50
	v_pk_add_f32 v[0:1], v[2:3], v[0:1]
	v_lshlrev_b32_e32 v2, 16, v51
	v_and_b32_e32 v3, 0xffff0000, v51
	v_pk_add_f32 v[2:3], v[4:5], v[2:3]
	v_lshlrev_b32_e32 v4, 16, v52
	v_and_b32_e32 v5, 0xffff0000, v52
	v_lshlrev_b32_e32 v50, 16, v6
	v_and_b32_e32 v51, 0xffff0000, v6
	v_pk_add_f32 v[4:5], v[50:51], v[4:5]
	v_lshlrev_b32_e32 v50, 16, v53
	v_and_b32_e32 v51, 0xffff0000, v53
	v_lshlrev_b32_e32 v6, 16, v7
	v_and_b32_e32 v7, 0xffff0000, v7
	v_pk_add_f32 v[6:7], v[6:7], v[50:51]
	v_cndmask_b32_e64 v50, 0, 1, s[10:11]
	v_cmp_ne_u32_e64 s[6:7], 1, v50
	s_cbranch_vccnz .LBB0_236
	v_lshl_add_u64 v[14:15], v[14:15], 2, s[8:9]
	global_store_dwordx4 v[14:15], v[0:3], off nt
	global_store_dwordx4 v[14:15], v[4:7], off offset:16 nt
	s_cbranch_execnz .LBB0_192

; DI float bflo(unsigned u) { return __uint_as_float(u << 16); }
; DI float bfhi(unsigned u) { return __uint_as_float(u & 0xffff0000u); }
; template <int EPI, bool RS>
; DI void gemm_epilogue(unsigned char* smem, f32x16 (&acc)[2][4], const float (&ssq)[4], int K, int m0, int nt256, const EpiArgs& ea, int wt, int wf, int r, int h) {
;     ...
; #pragma unroll
;       for (int i = 0; i < 8; ++i) {
;         const int c = tid + NTHR * i, row = c >> 5, kc = c & 31;
;         const u32x4 d = *(const u32x4*)(es + row * EP + kc * 16);
;         const size_t off = (size_t)(m0 + hf * 128 + row) * 1024 + nt256 * 256 + kc * 8;
;         const u32x4 xo = *(const u32x4*)(ea.XB + off);
;         float xn[8];
; #pragma unroll
;         for (int j = 0; j < 4; ++j) { xn[2 * j] = bflo(xo[j]) + bflo(d[j]); xn[2 * j + 1] = bfhi(xo[j]) + bfhi(d[j]); }
;         if (ea.X) {
;           f32x4 o0 = {xn[0], xn[1], xn[2], xn[3]}, o1 = {xn[4], xn[5], xn[6], xn[7]};
;           __builtin_nontemporal_store(o0, (f32x4*)(ea.X + off)); __builtin_nontemporal_store(o1, (f32x4*)(ea.X + off + 4));
;         } else {
;           u32x4 w;
; #pragma unroll
;           for (int j = 0; j < 4; ++j) w[j] = pk2(xn[2 * j], xn[2 * j + 1]);
;           *(u32x4*)(ea.XB + off) = w;
.LBB0_192:
	s_nop 1
	v_add_u32_e32 v0, 0x400, v60
	v_ashrrev_i32_e32 v50, 5, v0
	v_mul_lo_u32 v0, v50, s29
	v_add_u32_e32 v51, v61, v0
	v_add_u32_e32 v0, s59, v50
	v_ashrrev_i32_e32 v1, 31, v0
	v_lshlrev_b64 v[0:1], 10, v[0:1]
	v_lshl_add_u64 v[14:15], v[0:1], 0, v[8:9]
	v_lshl_add_u64 v[12:13], v[14:15], 1, s[62:63]
	ds_read_b128 v[4:7], v51
	s_and_b64 vcc, exec, s[6:7]
	s_waitcnt lgkmcnt(0)
	v_lshlrev_b32_e32 v2, 16, v4
	v_and_b32_e32 v3, 0xffff0000, v4
	v_lshlrev_b32_e32 v4, 16, v5
	v_and_b32_e32 v5, 0xffff0000, v5
	s_waitcnt vmcnt(7)
	v_mov_b32_e32 v52, v92
	v_mov_b32_e32 v53, v93
	v_mov_b32_e32 v54, v94
	v_mov_b32_e32 v55, v95
	v_lshlrev_b32_e32 v0, 16, v52
	v_and_b32_e32 v1, 0xffff0000, v52
	v_pk_add_f32 v[0:1], v[2:3], v[0:1]
	v_lshlrev_b32_e32 v2, 16, v53
	v_and_b32_e32 v3, 0xffff0000, v53
	v_pk_add_f32 v[2:3], v[4:5], v[2:3]
	v_lshlrev_b32_e32 v4, 16, v54
	v_and_b32_e32 v5, 0xffff0000, v54
	v_lshlrev_b32_e32 v52, 16, v6
	v_and_b32_e32 v53, 0xffff0000, v6
	v_pk_add_f32 v[4:5], v[52:53], v[4:5]
	v_lshlrev_b32_e32 v52, 16, v55
	v_and_b32_e32 v53, 0xffff0000, v55
	v_lshlrev_b32_e32 v6, 16, v7
	v_and_b32_e32 v7, 0xffff0000, v7
	v_pk_add_f32 v[6:7], v[6:7], v[52:53]
	s_cbranch_vccnz .LBB0_237
	v_lshl_add_u64 v[14:15], v[14:15], 2, s[8:9]
	global_store_dwordx4 v[14:15], v[0:3], off nt
	global_store_dwordx4 v[14:15], v[4:7], off offset:16 nt
	s_cbranch_execnz .LBB0_195

; DI float bflo(unsigned u) { return __uint_as_float(u << 16); }
; DI float bfhi(unsigned u) { return __uint_as_float(u & 0xffff0000u); }
; template <int EPI, bool RS>
; DI void gemm_epilogue(unsigned char* smem, f32x16 (&acc)[2][4], const float (&ssq)[4], int K, int m0, int nt256, const EpiArgs& ea, int wt, int wf, int r, int h) {
;     ...
; #pragma unroll
;       for (int i = 0; i < 8; ++i) {
;         const int c = tid + NTHR * i, row = c >> 5, kc = c & 31;
;         const u32x4 d = *(const u32x4*)(es + row * EP + kc * 16);
;         const size_t off = (size_t)(m0 + hf * 128 + row) * 1024 + nt256 * 256 + kc * 8;
;         const u32x4 xo = *(const u32x4*)(ea.XB + off);
;         float xn[8];
; #pragma unroll
;         for (int j = 0; j < 4; ++j) { xn[2 * j] = bflo(xo[j]) + bflo(d[j]); xn[2 * j + 1] = bfhi(xo[j]) + bfhi(d[j]); }
;         if (ea.X) {
;           f32x4 o0 = {xn[0], xn[1], xn[2], xn[3]}, o1 = {xn[4], xn[5], xn[6], xn[7]};
;           __builtin_nontemporal_store(o0, (f32x4*)(ea.X + off)); __builtin_nontemporal_store(o1, (f32x4*)(ea.X + off + 4));
;         } else {
;           u32x4 w;
; #pragma unroll
;           for (int j = 0; j < 4; ++j) w[j] = pk2(xn[2 * j], xn[2 * j + 1]);
;           *(u32x4*)(ea.XB + off) = w;
.LBB0_195:
	s_nop 1
	v_add_u32_e32 v0, 0x600, v60
	v_ashrrev_i32_e32 v52, 5, v0
	v_mul_lo_u32 v0, v52, s29
	v_add_u32_e32 v53, v61, v0
	v_add_u32_e32 v0, s59, v52
	v_ashrrev_i32_e32 v1, 31, v0
	v_lshlrev_b64 v[0:1], 10, v[0:1]
	v_lshl_add_u64 v[14:15], v[0:1], 0, v[8:9]
	v_lshl_add_u64 v[12:13], v[14:15], 1, s[62:63]
	ds_read_b128 v[4:7], v53
	s_and_b64 vcc, exec, s[6:7]
	s_waitcnt lgkmcnt(0)
	v_lshlrev_b32_e32 v2, 16, v4
	v_and_b32_e32 v3, 0xffff0000, v4
	v_lshlrev_b32_e32 v4, 16, v5
	v_and_b32_e32 v5, 0xffff0000, v5
	s_waitcnt vmcnt(7)
	v_mov_b32_e32 v54, v96
	v_mov_b32_e32 v55, v97
	v_mov_b32_e32 v56, v98
	v_mov_b32_e32 v57, v99
	v_lshlrev_b32_e32 v0, 16, v54
	v_and_b32_e32 v1, 0xffff0000, v54
	v_pk_add_f32 v[0:1], v[2:3], v[0:1]
	v_lshlrev_b32_e32 v2, 16, v55
	v_and_b32_e32 v3, 0xffff0000, v55
	v_pk_add_f32 v[2:3], v[4:5], v[2:3]
	v_lshlrev_b32_e32 v4, 16, v56
	v_and_b32_e32 v5, 0xffff0000, v56
	v_lshlrev_b32_e32 v54, 16, v6
	v_and_b32_e32 v55, 0xffff0000, v6
	v_pk_add_f32 v[4:5], v[54:55], v[4:5]
	v_lshlrev_b32_e32 v54, 16, v57
	v_and_b32_e32 v55, 0xffff0000, v57
	v_lshlrev_b32_e32 v6, 16, v7
	v_and_b32_e32 v7, 0xffff0000, v7
	v_pk_add_f32 v[6:7], v[6:7], v[54:55]
	s_cbranch_vccnz .LBB0_238
	v_lshl_add_u64 v[14:15], v[14:15], 2, s[8:9]
	global_store_dwordx4 v[14:15], v[0:3], off nt
	global_store_dwordx4 v[14:15], v[4:7], off offset:16 nt
	s_cbranch_execnz .LBB0_198

; DI float bflo(unsigned u) { return __uint_as_float(u << 16); }
; DI float bfhi(unsigned u) { return __uint_as_float(u & 0xffff0000u); }
; template <int EPI, bool RS>
; DI void gemm_epilogue(unsigned char* smem, f32x16 (&acc)[2][4], const float (&ssq)[4], int K, int m0, int nt256, const EpiArgs& ea, int wt, int wf, int r, int h) {
;     ...
; #pragma unroll
;       for (int i = 0; i < 8; ++i) {
;         const int c = tid + NTHR * i, row = c >> 5, kc = c & 31;
;         const u32x4 d = *(const u32x4*)(es + row * EP + kc * 16);
;         const size_t off = (size_t)(m0 + hf * 128 + row) * 1024 + nt256 * 256 + kc * 8;
;         const u32x4 xo = *(const u32x4*)(ea.XB + off);
;         float xn[8];
; #pragma unroll
;         for (int j = 0; j < 4; ++j) { xn[2 * j] = bflo(xo[j]) + bflo(d[j]); xn[2 * j + 1] = bfhi(xo[j]) + bfhi(d[j]); }
;         if (ea.X) {
;           f32x4 o0 = {xn[0], xn[1], xn[2], xn[3]}, o1 = {xn[4], xn[5], xn[6], xn[7]};
;           __builtin_nontemporal_store(o0, (f32x4*)(ea.X + off)); __builtin_nontemporal_store(o1, (f32x4*)(ea.X + off + 4));
;         } else {
;           u32x4 w;
; #pragma unroll
;           for (int j = 0; j < 4; ++j) w[j] = pk2(xn[2 * j], xn[2 * j + 1]);
;           *(u32x4*)(ea.XB + off) = w;
.LBB0_198:
	s_nop 1
	v_add_u32_e32 v0, 0x800, v60
	v_ashrrev_i32_e32 v54, 5, v0
	v_mul_lo_u32 v0, v54, s29
	v_add_u32_e32 v55, v61, v0
	v_add_u32_e32 v0, s59, v54
	v_ashrrev_i32_e32 v1, 31, v0
	v_lshlrev_b64 v[0:1], 10, v[0:1]
	v_lshl_add_u64 v[14:15], v[0:1], 0, v[8:9]
	v_lshl_add_u64 v[12:13], v[14:15], 1, s[62:63]
	ds_read_b128 v[4:7], v55
	s_and_b64 vcc, exec, s[6:7]
	s_waitcnt lgkmcnt(0)
	v_lshlrev_b32_e32 v2, 16, v4
	v_and_b32_e32 v3, 0xffff0000, v4
	v_lshlrev_b32_e32 v4, 16, v5
	v_and_b32_e32 v5, 0xffff0000, v5
	s_waitcnt vmcnt(7)
	v_mov_b32_e32 v56, v100
	v_mov_b32_e32 v57, v101
	v_mov_b32_e32 v58, v102
	v_mov_b32_e32 v59, v103
	v_lshlrev_b32_e32 v0, 16, v56
	v_and_b32_e32 v1, 0xffff0000, v56
	v_pk_add_f32 v[0:1], v[2:3], v[0:1]
	v_lshlrev_b32_e32 v2, 16, v57
	v_and_b32_e32 v3, 0xffff0000, v57
	v_pk_add_f32 v[2:3], v[4:5], v[2:3]
	v_lshlrev_b32_e32 v4, 16, v58
	v_and_b32_e32 v5, 0xffff0000, v58
	v_lshlrev_b32_e32 v56, 16, v6
	v_and_b32_e32 v57, 0xffff0000, v6
	v_pk_add_f32 v[4:5], v[56:57], v[4:5]
	v_lshlrev_b32_e32 v56, 16, v59
	v_and_b32_e32 v57, 0xffff0000, v59
	v_lshlrev_b32_e32 v6, 16, v7
	v_and_b32_e32 v7, 0xffff0000, v7
	v_pk_add_f32 v[6:7], v[6:7], v[56:57]
	s_cbranch_vccnz .LBB0_239
	v_lshl_add_u64 v[14:15], v[14:15], 2, s[8:9]
	global_store_dwordx4 v[14:15], v[0:3], off nt
	global_store_dwordx4 v[14:15], v[4:7], off offset:16 nt
	s_cbranch_execnz .LBB0_201

; DI float bflo(unsigned u) { return __uint_as_float(u << 16); }
; DI float bfhi(unsigned u) { return __uint_as_float(u & 0xffff0000u); }
; template <int EPI, bool RS>
; DI void gemm_epilogue(unsigned char* smem, f32x16 (&acc)[2][4], const float (&ssq)[4], int K, int m0, int nt256, const EpiArgs& ea, int wt, int wf, int r, int h) {
;     ...
; #pragma unroll
;       for (int i = 0; i < 8; ++i) {
;         const int c = tid + NTHR * i, row = c >> 5, kc = c & 31;
;         const u32x4 d = *(const u32x4*)(es + row * EP + kc * 16);
;         const size_t off = (size_t)(m0 + hf * 128 + row) * 1024 + nt256 * 256 + kc * 8;
;         const u32x4 xo = *(const u32x4*)(ea.XB + off);
;         float xn[8];
; #pragma unroll
;         for (int j = 0; j < 4; ++j) { xn[2 * j] = bflo(xo[j]) + bflo(d[j]); xn[2 * j + 1] = bfhi(xo[j]) + bfhi(d[j]); }
;         if (ea.X) {
;           f32x4 o0 = {xn[0], xn[1], xn[2], xn[3]}, o1 = {xn[4], xn[5], xn[6], xn[7]};
;           __builtin_nontemporal_store(o0, (f32x4*)(ea.X + off)); __builtin_nontemporal_store(o1, (f32x4*)(ea.X + off + 4));
;         } else {
;           u32x4 w;
; #pragma unroll
;           for (int j = 0; j < 4; ++j) w[j] = pk2(xn[2 * j], xn[2 * j + 1]);
;           *(u32x4*)(ea.XB + off) = w;
.LBB0_201:
	s_nop 1
	v_add_u32_e32 v0, 0xa00, v60
	v_ashrrev_i32_e32 v56, 5, v0
	v_mul_lo_u32 v0, v56, s29
	v_add_u32_e32 v57, v61, v0
	v_add_u32_e32 v0, s59, v56
	v_ashrrev_i32_e32 v1, 31, v0
	v_lshlrev_b64 v[0:1], 10, v[0:1]
	v_lshl_add_u64 v[14:15], v[0:1], 0, v[8:9]
	v_lshl_add_u64 v[12:13], v[14:15], 1, s[62:63]
	ds_read_b128 v[4:7], v57
	s_and_b64 vcc, exec, s[6:7]
	s_waitcnt lgkmcnt(0)
	v_lshlrev_b32_e32 v2, 16, v4
	v_and_b32_e32 v3, 0xffff0000, v4
	v_lshlrev_b32_e32 v4, 16, v5
	v_and_b32_e32 v5, 0xffff0000, v5
	v_lshlrev_b32_e32 v58, 16, v6
	v_and_b32_e32 v59, 0xffff0000, v6
	v_lshlrev_b32_e32 v6, 16, v7
	v_and_b32_e32 v7, 0xffff0000, v7
	s_waitcnt vmcnt(7)
	v_mov_b32_e32 v80, v104
	v_mov_b32_e32 v81, v105
	v_mov_b32_e32 v82, v106
	v_mov_b32_e32 v83, v107
	v_lshlrev_b32_e32 v0, 16, v80
	v_and_b32_e32 v1, 0xffff0000, v80
	v_pk_add_f32 v[0:1], v[2:3], v[0:1]
	v_lshlrev_b32_e32 v2, 16, v81
	v_and_b32_e32 v3, 0xffff0000, v81
	v_pk_add_f32 v[2:3], v[4:5], v[2:3]
	v_lshlrev_b32_e32 v4, 16, v82
	v_and_b32_e32 v5, 0xffff0000, v82
	v_pk_add_f32 v[4:5], v[58:59], v[4:5]
	v_lshlrev_b32_e32 v58, 16, v83
	v_and_b32_e32 v59, 0xffff0000, v83
	v_pk_add_f32 v[6:7], v[6:7], v[58:59]
	s_cbranch_vccnz .LBB0_240
	v_lshl_add_u64 v[14:15], v[14:15], 2, s[8:9]
	global_store_dwordx4 v[14:15], v[0:3], off nt
	global_store_dwordx4 v[14:15], v[4:7], off offset:16 nt
	s_cbranch_execnz .LBB0_204

; DI float bflo(unsigned u) { return __uint_as_float(u << 16); }
; DI float bfhi(unsigned u) { return __uint_as_float(u & 0xffff0000u); }
; template <int EPI, bool RS>
; DI void gemm_epilogue(unsigned char* smem, f32x16 (&acc)[2][4], const float (&ssq)[4], int K, int m0, int nt256, const EpiArgs& ea, int wt, int wf, int r, int h) {
;     ...
; #pragma unroll
;       for (int i = 0; i < 8; ++i) {
;         const int c = tid + NTHR * i, row = c >> 5, kc = c & 31;
;         const u32x4 d = *(const u32x4*)(es + row * EP + kc * 16);
;         const size_t off = (size_t)(m0 + hf * 128 + row) * 1024 + nt256 * 256 + kc * 8;
;         const u32x4 xo = *(const u32x4*)(ea.XB + off);
;         float xn[8];
; #pragma unroll
;         for (int j = 0; j < 4; ++j) { xn[2 * j] = bflo(xo[j]) + bflo(d[j]); xn[2 * j + 1] = bfhi(xo[j]) + bfhi(d[j]); }
;         if (ea.X) {
;           f32x4 o0 = {xn[0], xn[1], xn[2], xn[3]}, o1 = {xn[4], xn[5], xn[6], xn[7]};
;           __builtin_nontemporal_store(o0, (f32x4*)(ea.X + off)); __builtin_nontemporal_store(o1, (f32x4*)(ea.X + off + 4));
;         } else {
;           u32x4 w;
; #pragma unroll
;           for (int j = 0; j < 4; ++j) w[j] = pk2(xn[2 * j], xn[2 * j + 1]);
;           *(u32x4*)(ea.XB + off) = w;
.LBB0_204:
	s_nop 1
	v_add_u32_e32 v0, 0xc00, v60
	v_ashrrev_i32_e32 v58, 5, v0
	v_mul_lo_u32 v0, v58, s29
	v_add_u32_e32 v59, v61, v0
	v_add_u32_e32 v0, s59, v58
	v_ashrrev_i32_e32 v1, 31, v0
	v_lshlrev_b64 v[0:1], 10, v[0:1]
	v_lshl_add_u64 v[14:15], v[0:1], 0, v[8:9]
	v_lshl_add_u64 v[12:13], v[14:15], 1, s[62:63]
	ds_read_b128 v[4:7], v59
	s_and_b64 vcc, exec, s[6:7]
	s_waitcnt lgkmcnt(0)
	v_lshlrev_b32_e32 v2, 16, v4
	v_and_b32_e32 v3, 0xffff0000, v4
	v_lshlrev_b32_e32 v4, 16, v5
	v_and_b32_e32 v5, 0xffff0000, v5
	v_lshlrev_b32_e32 v62, 16, v6
	v_and_b32_e32 v63, 0xffff0000, v6
	v_lshlrev_b32_e32 v6, 16, v7
	v_and_b32_e32 v7, 0xffff0000, v7
	s_waitcnt vmcnt(7)
	v_mov_b32_e32 v80, v108
	v_mov_b32_e32 v81, v109
	v_mov_b32_e32 v82, v110
	v_mov_b32_e32 v83, v111
	v_lshlrev_b32_e32 v0, 16, v80
	v_and_b32_e32 v1, 0xffff0000, v80
	v_pk_add_f32 v[0:1], v[2:3], v[0:1]
	v_lshlrev_b32_e32 v2, 16, v81
	v_and_b32_e32 v3, 0xffff0000, v81
	v_pk_add_f32 v[2:3], v[4:5], v[2:3]
	v_lshlrev_b32_e32 v4, 16, v82
	v_and_b32_e32 v5, 0xffff0000, v82
	v_pk_add_f32 v[4:5], v[62:63], v[4:5]
	v_lshlrev_b32_e32 v62, 16, v83
	v_and_b32_e32 v63, 0xffff0000, v83
	v_pk_add_f32 v[6:7], v[6:7], v[62:63]
	s_cbranch_vccnz .LBB0_241
	v_lshl_add_u64 v[14:15], v[14:15], 2, s[8:9]
	global_store_dwordx4 v[14:15], v[0:3], off nt
	global_store_dwordx4 v[14:15], v[4:7], off offset:16 nt
	s_cbranch_execnz .LBB0_207

; DI float bflo(unsigned u) { return __uint_as_float(u << 16); }
; DI float bfhi(unsigned u) { return __uint_as_float(u & 0xffff0000u); }
; template <int EPI, bool RS>
; DI void gemm_epilogue(unsigned char* smem, f32x16 (&acc)[2][4], const float (&ssq)[4], int K, int m0, int nt256, const EpiArgs& ea, int wt, int wf, int r, int h) {
;     ...
; #pragma unroll
;       for (int i = 0; i < 8; ++i) {
;         const int c = tid + NTHR * i, row = c >> 5, kc = c & 31;
;         const u32x4 d = *(const u32x4*)(es + row * EP + kc * 16);
;         const size_t off = (size_t)(m0 + hf * 128 + row) * 1024 + nt256 * 256 + kc * 8;
;         const u32x4 xo = *(const u32x4*)(ea.XB + off);
;         float xn[8];
; #pragma unroll
;         for (int j = 0; j < 4; ++j) { xn[2 * j] = bflo(xo[j]) + bflo(d[j]); xn[2 * j + 1] = bfhi(xo[j]) + bfhi(d[j]); }
;         if (ea.X) {
;           f32x4 o0 = {xn[0], xn[1], xn[2], xn[3]}, o1 = {xn[4], xn[5], xn[6], xn[7]};
;           __builtin_nontemporal_store(o0, (f32x4*)(ea.X + off)); __builtin_nontemporal_store(o1, (f32x4*)(ea.X + off + 4));
;         } else {
;           u32x4 w;
; #pragma unroll
;           for (int j = 0; j < 4; ++j) w[j] = pk2(xn[2 * j], xn[2 * j + 1]);
;           *(u32x4*)(ea.XB + off) = w;
.LBB0_207:
	s_nop 1
	v_add_u32_e32 v0, 0xe00, v60
	v_ashrrev_i32_e32 v60, 5, v0
	v_mul_lo_u32 v0, v60, s29
	v_add_u32_e32 v61, v61, v0
	v_add_u32_e32 v0, s59, v60
	v_ashrrev_i32_e32 v1, 31, v0
	v_lshlrev_b64 v[0:1], 10, v[0:1]
	v_lshl_add_u64 v[14:15], v[0:1], 0, v[8:9]
	v_lshl_add_u64 v[12:13], v[14:15], 1, s[62:63]
	ds_read_b128 v[4:7], v61
	s_and_b64 vcc, exec, s[6:7]
	s_waitcnt lgkmcnt(0)
	v_lshlrev_b32_e32 v2, 16, v4
	v_and_b32_e32 v3, 0xffff0000, v4
	v_lshlrev_b32_e32 v4, 16, v5
	v_and_b32_e32 v5, 0xffff0000, v5
	v_lshlrev_b32_e32 v62, 16, v6
	v_and_b32_e32 v63, 0xffff0000, v6
	v_lshlrev_b32_e32 v6, 16, v7
	v_and_b32_e32 v7, 0xffff0000, v7
	s_waitcnt vmcnt(7)
	v_mov_b32_e32 v80, v124
	v_mov_b32_e32 v81, v125
	v_mov_b32_e32 v82, v126
	v_mov_b32_e32 v83, v127
	v_lshlrev_b32_e32 v0, 16, v80
	v_and_b32_e32 v1, 0xffff0000, v80
	v_pk_add_f32 v[0:1], v[2:3], v[0:1]
	v_lshlrev_b32_e32 v2, 16, v81
	v_and_b32_e32 v3, 0xffff0000, v81
	v_pk_add_f32 v[2:3], v[4:5], v[2:3]
	v_lshlrev_b32_e32 v4, 16, v82
	v_and_b32_e32 v5, 0xffff0000, v82
	v_pk_add_f32 v[4:5], v[62:63], v[4:5]
	v_lshlrev_b32_e32 v62, 16, v83
	v_and_b32_e32 v63, 0xffff0000, v83
	v_pk_add_f32 v[6:7], v[6:7], v[62:63]
	s_cbranch_vccnz .LBB0_242
	v_lshl_add_u64 v[14:15], v[14:15], 2, s[8:9]
	global_store_dwordx4 v[14:15], v[0:3], off nt
	global_store_dwordx4 v[14:15], v[4:7], off offset:16 nt
	s_cbranch_execnz .LBB0_210

; DI float bflo(unsigned u) { return __uint_as_float(u << 16); }
; DI float bfhi(unsigned u) { return __uint_as_float(u & 0xffff0000u); }
; template <int EPI, bool RS>
; DI void gemm_epilogue(unsigned char* smem, f32x16 (&acc)[2][4], const float (&ssq)[4], int K, int m0, int nt256, const EpiArgs& ea, int wt, int wf, int r, int h) {
;     ...
;       __syncthreads();
; #pragma unroll
;       for (int i = 0; i < 8; ++i) {
;         const int c = tid + NTHR * i, row = c >> 5, kc = c & 31;
;         const u32x4 d = *(const u32x4*)(es + row * EP + kc * 16);
;         const size_t off = (size_t)(m0 + hf * 128 + row) * 1024 + nt256 * 256 + kc * 8;
;         const u32x4 xo = *(const u32x4*)(ea.XB + off);
;         float xn[8];
; #pragma unroll
;         for (int j = 0; j < 4; ++j) { xn[2 * j] = bflo(xo[j]) + bflo(d[j]); xn[2 * j + 1] = bfhi(xo[j]) + bfhi(d[j]); }
;         if (ea.X) {
;           f32x4 o0 = {xn[0], xn[1], xn[2], xn[3]}, o1 = {xn[4], xn[5], xn[6], xn[7]};
;           __builtin_nontemporal_store(o0, (f32x4*)(ea.X + off)); __builtin_nontemporal_store(o1, (f32x4*)(ea.X + off + 4));
;         } else {
;           u32x4 w;
; #pragma unroll
;           for (int j = 0; j < 4; ++j) w[j] = pk2(xn[2 * j], xn[2 * j + 1]);
;           *(u32x4*)(ea.XB + off) = w;
.LBB0_212:
	s_or_b64 exec, exec, s[20:21]
	s_add_i32 s33, s59, 0x80
	v_add_u32_e32 v0, s33, v30
	v_ashrrev_i32_e32 v1, 31, v0
	v_lshlrev_b64 v[0:1], 10, v[0:1]
	v_lshl_add_u64 v[12:13], v[0:1], 0, v[8:9]
	v_lshl_add_u64 v[10:11], v[12:13], 1, s[62:63]
	s_mov_b64 s[100:101], 0x8000
	global_load_dwordx4 v[20:23], v[10:11], off
	v_lshl_add_u64 v[28:29], v[10:11], 0, s[100:101]
	global_load_dwordx4 v[24:27], v[28:29], off
	v_lshl_add_u64 v[28:29], v[28:29], 0, s[100:101]
	global_load_dwordx4 v[32:35], v[28:29], off
	v_lshl_add_u64 v[28:29], v[28:29], 0, s[100:101]
	global_load_dwordx4 v[36:39], v[28:29], off
	v_lshl_add_u64 v[28:29], v[28:29], 0, s[100:101]
	global_load_dwordx4 v[40:43], v[28:29], off
	v_lshl_add_u64 v[28:29], v[28:29], 0, s[100:101]
	global_load_dwordx4 v[44:47], v[28:29], off
	v_lshl_add_u64 v[28:29], v[28:29], 0, s[100:101]
	global_load_dwordx4 v[62:65], v[28:29], off
	v_lshl_add_u64 v[28:29], v[28:29], 0, s[100:101]
	global_load_dwordx4 v[66:69], v[28:29], off
	s_waitcnt lgkmcnt(0)
	s_barrier
	ds_read_b128 v[4:7], v31
	s_and_b64 vcc, exec, s[6:7]
	s_waitcnt lgkmcnt(0)
	v_lshlrev_b32_e32 v2, 16, v4
	v_and_b32_e32 v3, 0xffff0000, v4
	v_lshlrev_b32_e32 v4, 16, v5
	v_and_b32_e32 v5, 0xffff0000, v5
	s_waitcnt vmcnt(7)
	v_mov_b32_e32 v14, v20
	v_mov_b32_e32 v15, v21
	v_mov_b32_e32 v16, v22
	v_mov_b32_e32 v17, v23
	v_lshlrev_b32_e32 v0, 16, v14
	v_and_b32_e32 v1, 0xffff0000, v14
	v_pk_add_f32 v[0:1], v[2:3], v[0:1]
	v_lshlrev_b32_e32 v2, 16, v15
	v_and_b32_e32 v3, 0xffff0000, v15
	v_pk_add_f32 v[2:3], v[4:5], v[2:3]
	v_lshlrev_b32_e32 v4, 16, v16
	v_and_b32_e32 v5, 0xffff0000, v16
	v_lshlrev_b32_e32 v14, 16, v6
	v_and_b32_e32 v15, 0xffff0000, v6
	v_pk_add_f32 v[4:5], v[14:15], v[4:5]
	v_lshlrev_b32_e32 v14, 16, v17
	v_and_b32_e32 v15, 0xffff0000, v17
	v_lshlrev_b32_e32 v6, 16, v7
	v_and_b32_e32 v7, 0xffff0000, v7
	v_pk_add_f32 v[6:7], v[6:7], v[14:15]
	s_cbranch_vccnz .LBB0_243
	v_lshl_add_u64 v[12:13], v[12:13], 2, s[8:9]
	global_store_dwordx4 v[12:13], v[0:3], off nt
	global_store_dwordx4 v[12:13], v[4:7], off offset:16 nt
	s_cbranch_execnz .LBB0_215

; DI float bflo(unsigned u) { return __uint_as_float(u << 16); }
; DI float bfhi(unsigned u) { return __uint_as_float(u & 0xffff0000u); }
; template <int EPI, bool RS>
; DI void gemm_epilogue(unsigned char* smem, f32x16 (&acc)[2][4], const float (&ssq)[4], int K, int m0, int nt256, const EpiArgs& ea, int wt, int wf, int r, int h) {
;     ...
; #pragma unroll
;       for (int i = 0; i < 8; ++i) {
;         const int c = tid + NTHR * i, row = c >> 5, kc = c & 31;
;         const u32x4 d = *(const u32x4*)(es + row * EP + kc * 16);
;         const size_t off = (size_t)(m0 + hf * 128 + row) * 1024 + nt256 * 256 + kc * 8;
;         const u32x4 xo = *(const u32x4*)(ea.XB + off);
;         float xn[8];
; #pragma unroll
;         for (int j = 0; j < 4; ++j) { xn[2 * j] = bflo(xo[j]) + bflo(d[j]); xn[2 * j + 1] = bfhi(xo[j]) + bfhi(d[j]); }
;         if (ea.X) {
;           f32x4 o0 = {xn[0], xn[1], xn[2], xn[3]}, o1 = {xn[4], xn[5], xn[6], xn[7]};
;           __builtin_nontemporal_store(o0, (f32x4*)(ea.X + off)); __builtin_nontemporal_store(o1, (f32x4*)(ea.X + off + 4));
;         } else {
;           u32x4 w;
; #pragma unroll
;           for (int j = 0; j < 4; ++j) w[j] = pk2(xn[2 * j], xn[2 * j + 1]);
;           *(u32x4*)(ea.XB + off) = w;
.LBB0_215:
	s_nop 1
	v_add_u32_e32 v0, s33, v48
	v_ashrrev_i32_e32 v1, 31, v0
	v_lshlrev_b64 v[0:1], 10, v[0:1]
	v_lshl_add_u64 v[12:13], v[0:1], 0, v[8:9]
	v_lshl_add_u64 v[10:11], v[12:13], 1, s[62:63]
	ds_read_b128 v[4:7], v49
	s_and_b64 vcc, exec, s[6:7]
	s_waitcnt lgkmcnt(0)
	v_lshlrev_b32_e32 v2, 16, v4
	v_and_b32_e32 v3, 0xffff0000, v4
	v_lshlrev_b32_e32 v4, 16, v5
	v_and_b32_e32 v5, 0xffff0000, v5
	s_waitcnt vmcnt(7)
	v_mov_b32_e32 v14, v24
	v_mov_b32_e32 v15, v25
	v_mov_b32_e32 v16, v26
	v_mov_b32_e32 v17, v27
	v_lshlrev_b32_e32 v0, 16, v14
	v_and_b32_e32 v1, 0xffff0000, v14
	v_pk_add_f32 v[0:1], v[2:3], v[0:1]
	v_lshlrev_b32_e32 v2, 16, v15
	v_and_b32_e32 v3, 0xffff0000, v15
	v_pk_add_f32 v[2:3], v[4:5], v[2:3]
	v_lshlrev_b32_e32 v4, 16, v16
	v_and_b32_e32 v5, 0xffff0000, v16
	v_lshlrev_b32_e32 v14, 16, v6
	v_and_b32_e32 v15, 0xffff0000, v6
	v_pk_add_f32 v[4:5], v[14:15], v[4:5]
	v_lshlrev_b32_e32 v14, 16, v17
	v_and_b32_e32 v15, 0xffff0000, v17
	v_lshlrev_b32_e32 v6, 16, v7
	v_and_b32_e32 v7, 0xffff0000, v7
	v_pk_add_f32 v[6:7], v[6:7], v[14:15]
	s_cbranch_vccnz .LBB0_244
	v_lshl_add_u64 v[12:13], v[12:13], 2, s[8:9]
	global_store_dwordx4 v[12:13], v[0:3], off nt
	global_store_dwordx4 v[12:13], v[4:7], off offset:16 nt
	s_cbranch_execnz .LBB0_218

; DI float bflo(unsigned u) { return __uint_as_float(u << 16); }
; DI float bfhi(unsigned u) { return __uint_as_float(u & 0xffff0000u); }
; template <int EPI, bool RS>
; DI void gemm_epilogue(unsigned char* smem, f32x16 (&acc)[2][4], const float (&ssq)[4], int K, int m0, int nt256, const EpiArgs& ea, int wt, int wf, int r, int h) {
;     ...
; #pragma unroll
;       for (int i = 0; i < 8; ++i) {
;         const int c = tid + NTHR * i, row = c >> 5, kc = c & 31;
;         const u32x4 d = *(const u32x4*)(es + row * EP + kc * 16);
;         const size_t off = (size_t)(m0 + hf * 128 + row) * 1024 + nt256 * 256 + kc * 8;
;         const u32x4 xo = *(const u32x4*)(ea.XB + off);
;         float xn[8];
; #pragma unroll
;         for (int j = 0; j < 4; ++j) { xn[2 * j] = bflo(xo[j]) + bflo(d[j]); xn[2 * j + 1] = bfhi(xo[j]) + bfhi(d[j]); }
;         if (ea.X) {
;           f32x4 o0 = {xn[0], xn[1], xn[2], xn[3]}, o1 = {xn[4], xn[5], xn[6], xn[7]};
;           __builtin_nontemporal_store(o0, (f32x4*)(ea.X + off)); __builtin_nontemporal_store(o1, (f32x4*)(ea.X + off + 4));
;         } else {
;           u32x4 w;
; #pragma unroll
;           for (int j = 0; j < 4; ++j) w[j] = pk2(xn[2 * j], xn[2 * j + 1]);
;           *(u32x4*)(ea.XB + off) = w;
.LBB0_218:
	s_nop 1
	v_add_u32_e32 v0, s33, v50
	v_ashrrev_i32_e32 v1, 31, v0
	v_lshlrev_b64 v[0:1], 10, v[0:1]
	v_lshl_add_u64 v[12:13], v[0:1], 0, v[8:9]
	v_lshl_add_u64 v[10:11], v[12:13], 1, s[62:63]
	ds_read_b128 v[4:7], v51
	s_and_b64 vcc, exec, s[6:7]
	s_waitcnt lgkmcnt(0)
	v_lshlrev_b32_e32 v2, 16, v4
	v_and_b32_e32 v3, 0xffff0000, v4
	v_lshlrev_b32_e32 v4, 16, v5
	v_and_b32_e32 v5, 0xffff0000, v5
	s_waitcnt vmcnt(7)
	v_mov_b32_e32 v14, v32
	v_mov_b32_e32 v15, v33
	v_mov_b32_e32 v16, v34
	v_mov_b32_e32 v17, v35
	v_lshlrev_b32_e32 v0, 16, v14
	v_and_b32_e32 v1, 0xffff0000, v14
	v_pk_add_f32 v[0:1], v[2:3], v[0:1]
	v_lshlrev_b32_e32 v2, 16, v15
	v_and_b32_e32 v3, 0xffff0000, v15
	v_pk_add_f32 v[2:3], v[4:5], v[2:3]
	v_lshlrev_b32_e32 v4, 16, v16
	v_and_b32_e32 v5, 0xffff0000, v16
	v_lshlrev_b32_e32 v14, 16, v6
	v_and_b32_e32 v15, 0xffff0000, v6
	v_pk_add_f32 v[4:5], v[14:15], v[4:5]
	v_lshlrev_b32_e32 v14, 16, v17
	v_and_b32_e32 v15, 0xffff0000, v17
	v_lshlrev_b32_e32 v6, 16, v7
	v_and_b32_e32 v7, 0xffff0000, v7
	v_pk_add_f32 v[6:7], v[6:7], v[14:15]
	s_cbranch_vccnz .LBB0_245
	v_lshl_add_u64 v[12:13], v[12:13], 2, s[8:9]
	global_store_dwordx4 v[12:13], v[0:3], off nt
	global_store_dwordx4 v[12:13], v[4:7], off offset:16 nt
	s_cbranch_execnz .LBB0_221

; DI float bflo(unsigned u) { return __uint_as_float(u << 16); }
; DI float bfhi(unsigned u) { return __uint_as_float(u & 0xffff0000u); }
; template <int EPI, bool RS>
; DI void gemm_epilogue(unsigned char* smem, f32x16 (&acc)[2][4], const float (&ssq)[4], int K, int m0, int nt256, const EpiArgs& ea, int wt, int wf, int r, int h) {
;     ...
; #pragma unroll
;       for (int i = 0; i < 8; ++i) {
;         const int c = tid + NTHR * i, row = c >> 5, kc = c & 31;
;         const u32x4 d = *(const u32x4*)(es + row * EP + kc * 16);
;         const size_t off = (size_t)(m0 + hf * 128 + row) * 1024 + nt256 * 256 + kc * 8;
;         const u32x4 xo = *(const u32x4*)(ea.XB + off);
;         float xn[8];
; #pragma unroll
;         for (int j = 0; j < 4; ++j) { xn[2 * j] = bflo(xo[j]) + bflo(d[j]); xn[2 * j + 1] = bfhi(xo[j]) + bfhi(d[j]); }
;         if (ea.X) {
;           f32x4 o0 = {xn[0], xn[1], xn[2], xn[3]}, o1 = {xn[4], xn[5], xn[6], xn[7]};
;           __builtin_nontemporal_store(o0, (f32x4*)(ea.X + off)); __builtin_nontemporal_store(o1, (f32x4*)(ea.X + off + 4));
;         } else {
;           u32x4 w;
; #pragma unroll
;           for (int j = 0; j < 4; ++j) w[j] = pk2(xn[2 * j], xn[2 * j + 1]);
;           *(u32x4*)(ea.XB + off) = w;
.LBB0_221:
	s_nop 1
	v_add_u32_e32 v0, s33, v52
	v_ashrrev_i32_e32 v1, 31, v0
	v_lshlrev_b64 v[0:1], 10, v[0:1]
	v_lshl_add_u64 v[12:13], v[0:1], 0, v[8:9]
	v_lshl_add_u64 v[10:11], v[12:13], 1, s[62:63]
	ds_read_b128 v[4:7], v53
	s_and_b64 vcc, exec, s[6:7]
	s_waitcnt lgkmcnt(0)
	v_lshlrev_b32_e32 v2, 16, v4
	v_and_b32_e32 v3, 0xffff0000, v4
	v_lshlrev_b32_e32 v4, 16, v5
	v_and_b32_e32 v5, 0xffff0000, v5
	s_waitcnt vmcnt(7)
	v_mov_b32_e32 v14, v36
	v_mov_b32_e32 v15, v37
	v_mov_b32_e32 v16, v38
	v_mov_b32_e32 v17, v39
	v_lshlrev_b32_e32 v0, 16, v14
	v_and_b32_e32 v1, 0xffff0000, v14
	v_pk_add_f32 v[0:1], v[2:3], v[0:1]
	v_lshlrev_b32_e32 v2, 16, v15
	v_and_b32_e32 v3, 0xffff0000, v15
	v_pk_add_f32 v[2:3], v[4:5], v[2:3]
	v_lshlrev_b32_e32 v4, 16, v16
	v_and_b32_e32 v5, 0xffff0000, v16
	v_lshlrev_b32_e32 v14, 16, v6
	v_and_b32_e32 v15, 0xffff0000, v6
	v_pk_add_f32 v[4:5], v[14:15], v[4:5]
	v_lshlrev_b32_e32 v14, 16, v17
	v_and_b32_e32 v15, 0xffff0000, v17
	v_lshlrev_b32_e32 v6, 16, v7
	v_and_b32_e32 v7, 0xffff0000, v7
	v_pk_add_f32 v[6:7], v[6:7], v[14:15]
	s_cbranch_vccnz .LBB0_246
	v_lshl_add_u64 v[12:13], v[12:13], 2, s[8:9]
	global_store_dwordx4 v[12:13], v[0:3], off nt
	global_store_dwordx4 v[12:13], v[4:7], off offset:16 nt
	s_cbranch_execnz .LBB0_224

; DI float bflo(unsigned u) { return __uint_as_float(u << 16); }
; DI float bfhi(unsigned u) { return __uint_as_float(u & 0xffff0000u); }
; template <int EPI, bool RS>
; DI void gemm_epilogue(unsigned char* smem, f32x16 (&acc)[2][4], const float (&ssq)[4], int K, int m0, int nt256, const EpiArgs& ea, int wt, int wf, int r, int h) {
;     ...
; #pragma unroll
;       for (int i = 0; i < 8; ++i) {
;         const int c = tid + NTHR * i, row = c >> 5, kc = c & 31;
;         const u32x4 d = *(const u32x4*)(es + row * EP + kc * 16);
;         const size_t off = (size_t)(m0 + hf * 128 + row) * 1024 + nt256 * 256 + kc * 8;
;         const u32x4 xo = *(const u32x4*)(ea.XB + off);
;         float xn[8];
; #pragma unroll
;         for (int j = 0; j < 4; ++j) { xn[2 * j] = bflo(xo[j]) + bflo(d[j]); xn[2 * j + 1] = bfhi(xo[j]) + bfhi(d[j]); }
;         if (ea.X) {
;           f32x4 o0 = {xn[0], xn[1], xn[2], xn[3]}, o1 = {xn[4], xn[5], xn[6], xn[7]};
;           __builtin_nontemporal_store(o0, (f32x4*)(ea.X + off)); __builtin_nontemporal_store(o1, (f32x4*)(ea.X + off + 4));
;         } else {
;           u32x4 w;
; #pragma unroll
;           for (int j = 0; j < 4; ++j) w[j] = pk2(xn[2 * j], xn[2 * j + 1]);
;           *(u32x4*)(ea.XB + off) = w;
.LBB0_224:
	s_nop 1
	v_add_u32_e32 v0, s33, v54
	v_ashrrev_i32_e32 v1, 31, v0
	v_lshlrev_b64 v[0:1], 10, v[0:1]
	v_lshl_add_u64 v[12:13], v[0:1], 0, v[8:9]
	v_lshl_add_u64 v[10:11], v[12:13], 1, s[62:63]
	ds_read_b128 v[4:7], v55
	s_and_b64 vcc, exec, s[6:7]
	s_waitcnt lgkmcnt(0)
	v_lshlrev_b32_e32 v2, 16, v4
	v_and_b32_e32 v3, 0xffff0000, v4
	v_lshlrev_b32_e32 v4, 16, v5
	v_and_b32_e32 v5, 0xffff0000, v5
	s_waitcnt vmcnt(7)
	v_mov_b32_e32 v14, v40
	v_mov_b32_e32 v15, v41
	v_mov_b32_e32 v16, v42
	v_mov_b32_e32 v17, v43
	v_lshlrev_b32_e32 v0, 16, v14
	v_and_b32_e32 v1, 0xffff0000, v14
	v_pk_add_f32 v[0:1], v[2:3], v[0:1]
	v_lshlrev_b32_e32 v2, 16, v15
	v_and_b32_e32 v3, 0xffff0000, v15
	v_pk_add_f32 v[2:3], v[4:5], v[2:3]
	v_lshlrev_b32_e32 v4, 16, v16
	v_and_b32_e32 v5, 0xffff0000, v16
	v_lshlrev_b32_e32 v14, 16, v6
	v_and_b32_e32 v15, 0xffff0000, v6
	v_pk_add_f32 v[4:5], v[14:15], v[4:5]
	v_lshlrev_b32_e32 v14, 16, v17
	v_and_b32_e32 v15, 0xffff0000, v17
	v_lshlrev_b32_e32 v6, 16, v7
	v_and_b32_e32 v7, 0xffff0000, v7
	v_pk_add_f32 v[6:7], v[6:7], v[14:15]
	s_cbranch_vccnz .LBB0_247
	v_lshl_add_u64 v[12:13], v[12:13], 2, s[8:9]
	global_store_dwordx4 v[12:13], v[0:3], off nt
	global_store_dwordx4 v[12:13], v[4:7], off offset:16 nt
	s_cbranch_execnz .LBB0_227

; DI float bflo(unsigned u) { return __uint_as_float(u << 16); }
; DI float bfhi(unsigned u) { return __uint_as_float(u & 0xffff0000u); }
; template <int EPI, bool RS>
; DI void gemm_epilogue(unsigned char* smem, f32x16 (&acc)[2][4], const float (&ssq)[4], int K, int m0, int nt256, const EpiArgs& ea, int wt, int wf, int r, int h) {
;     ...
; #pragma unroll
;       for (int i = 0; i < 8; ++i) {
;         const int c = tid + NTHR * i, row = c >> 5, kc = c & 31;
;         const u32x4 d = *(const u32x4*)(es + row * EP + kc * 16);
;         const size_t off = (size_t)(m0 + hf * 128 + row) * 1024 + nt256 * 256 + kc * 8;
;         const u32x4 xo = *(const u32x4*)(ea.XB + off);
;         float xn[8];
; #pragma unroll
;         for (int j = 0; j < 4; ++j) { xn[2 * j] = bflo(xo[j]) + bflo(d[j]); xn[2 * j + 1] = bfhi(xo[j]) + bfhi(d[j]); }
;         if (ea.X) {
;           f32x4 o0 = {xn[0], xn[1], xn[2], xn[3]}, o1 = {xn[4], xn[5], xn[6], xn[7]};
;           __builtin_nontemporal_store(o0, (f32x4*)(ea.X + off)); __builtin_nontemporal_store(o1, (f32x4*)(ea.X + off + 4));
;         } else {
;           u32x4 w;
; #pragma unroll
;           for (int j = 0; j < 4; ++j) w[j] = pk2(xn[2 * j], xn[2 * j + 1]);
;           *(u32x4*)(ea.XB + off) = w;
.LBB0_227:
	s_nop 1
	v_add_u32_e32 v0, s33, v56
	v_ashrrev_i32_e32 v1, 31, v0
	v_lshlrev_b64 v[0:1], 10, v[0:1]
	v_lshl_add_u64 v[12:13], v[0:1], 0, v[8:9]
	v_lshl_add_u64 v[10:11], v[12:13], 1, s[62:63]
	ds_read_b128 v[4:7], v57
	s_and_b64 vcc, exec, s[6:7]
	s_waitcnt lgkmcnt(0)
	v_lshlrev_b32_e32 v2, 16, v4
	v_and_b32_e32 v3, 0xffff0000, v4
	v_lshlrev_b32_e32 v4, 16, v5
	v_and_b32_e32 v5, 0xffff0000, v5
	s_waitcnt vmcnt(7)
	v_mov_b32_e32 v14, v44
	v_mov_b32_e32 v15, v45
	v_mov_b32_e32 v16, v46
	v_mov_b32_e32 v17, v47
	v_lshlrev_b32_e32 v0, 16, v14
	v_and_b32_e32 v1, 0xffff0000, v14
	v_pk_add_f32 v[0:1], v[2:3], v[0:1]
	v_lshlrev_b32_e32 v2, 16, v15
	v_and_b32_e32 v3, 0xffff0000, v15
	v_pk_add_f32 v[2:3], v[4:5], v[2:3]
	v_lshlrev_b32_e32 v4, 16, v16
	v_and_b32_e32 v5, 0xffff0000, v16
	v_lshlrev_b32_e32 v14, 16, v6
	v_and_b32_e32 v15, 0xffff0000, v6
	v_pk_add_f32 v[4:5], v[14:15], v[4:5]
	v_lshlrev_b32_e32 v14, 16, v17
	v_and_b32_e32 v15, 0xffff0000, v17
	v_lshlrev_b32_e32 v6, 16, v7
	v_and_b32_e32 v7, 0xffff0000, v7
	v_pk_add_f32 v[6:7], v[6:7], v[14:15]
	s_cbranch_vccnz .LBB0_248
	v_lshl_add_u64 v[12:13], v[12:13], 2, s[8:9]
	global_store_dwordx4 v[12:13], v[0:3], off nt
	global_store_dwordx4 v[12:13], v[4:7], off offset:16 nt
	s_cbranch_execnz .LBB0_230

; DI float bflo(unsigned u) { return __uint_as_float(u << 16); }
; DI float bfhi(unsigned u) { return __uint_as_float(u & 0xffff0000u); }
; template <int EPI, bool RS>
; DI void gemm_epilogue(unsigned char* smem, f32x16 (&acc)[2][4], const float (&ssq)[4], int K, int m0, int nt256, const EpiArgs& ea, int wt, int wf, int r, int h) {
;     ...
; #pragma unroll
;       for (int i = 0; i < 8; ++i) {
;         const int c = tid + NTHR * i, row = c >> 5, kc = c & 31;
;         const u32x4 d = *(const u32x4*)(es + row * EP + kc * 16);
;         const size_t off = (size_t)(m0 + hf * 128 + row) * 1024 + nt256 * 256 + kc * 8;
;         const u32x4 xo = *(const u32x4*)(ea.XB + off);
;         float xn[8];
; #pragma unroll
;         for (int j = 0; j < 4; ++j) { xn[2 * j] = bflo(xo[j]) + bflo(d[j]); xn[2 * j + 1] = bfhi(xo[j]) + bfhi(d[j]); }
;         if (ea.X) {
;           f32x4 o0 = {xn[0], xn[1], xn[2], xn[3]}, o1 = {xn[4], xn[5], xn[6], xn[7]};
;           __builtin_nontemporal_store(o0, (f32x4*)(ea.X + off)); __builtin_nontemporal_store(o1, (f32x4*)(ea.X + off + 4));
;         } else {
;           u32x4 w;
; #pragma unroll
;           for (int j = 0; j < 4; ++j) w[j] = pk2(xn[2 * j], xn[2 * j + 1]);
;           *(u32x4*)(ea.XB + off) = w;
.LBB0_230:
	s_nop 1
	v_add_u32_e32 v0, s33, v58
	v_ashrrev_i32_e32 v1, 31, v0
	v_lshlrev_b64 v[0:1], 10, v[0:1]
	v_lshl_add_u64 v[12:13], v[0:1], 0, v[8:9]
	v_lshl_add_u64 v[10:11], v[12:13], 1, s[62:63]
	ds_read_b128 v[4:7], v59
	s_and_b64 vcc, exec, s[6:7]
	s_waitcnt lgkmcnt(0)
	v_lshlrev_b32_e32 v2, 16, v4
	v_and_b32_e32 v3, 0xffff0000, v4
	v_lshlrev_b32_e32 v4, 16, v5
	v_and_b32_e32 v5, 0xffff0000, v5
	s_waitcnt vmcnt(7)
	v_mov_b32_e32 v14, v62
	v_mov_b32_e32 v15, v63
	v_mov_b32_e32 v16, v64
	v_mov_b32_e32 v17, v65
	v_lshlrev_b32_e32 v0, 16, v14
	v_and_b32_e32 v1, 0xffff0000, v14
	v_pk_add_f32 v[0:1], v[2:3], v[0:1]
	v_lshlrev_b32_e32 v2, 16, v15
	v_and_b32_e32 v3, 0xffff0000, v15
	v_pk_add_f32 v[2:3], v[4:5], v[2:3]
	v_lshlrev_b32_e32 v4, 16, v16
	v_and_b32_e32 v5, 0xffff0000, v16
	v_lshlrev_b32_e32 v14, 16, v6
	v_and_b32_e32 v15, 0xffff0000, v6
	v_pk_add_f32 v[4:5], v[14:15], v[4:5]
	v_lshlrev_b32_e32 v14, 16, v17
	v_and_b32_e32 v15, 0xffff0000, v17
	v_lshlrev_b32_e32 v6, 16, v7
	v_and_b32_e32 v7, 0xffff0000, v7
	v_pk_add_f32 v[6:7], v[6:7], v[14:15]
	s_cbranch_vccnz .LBB0_249
	v_lshl_add_u64 v[12:13], v[12:13], 2, s[8:9]
	global_store_dwordx4 v[12:13], v[0:3], off nt
	global_store_dwordx4 v[12:13], v[4:7], off offset:16 nt
	s_cbranch_execnz .LBB0_233

; DI float bflo(unsigned u) { return __uint_as_float(u << 16); }
; DI float bfhi(unsigned u) { return __uint_as_float(u & 0xffff0000u); }
; template <int EPI, bool RS>
; DI void gemm_epilogue(unsigned char* smem, f32x16 (&acc)[2][4], const float (&ssq)[4], int K, int m0, int nt256, const EpiArgs& ea, int wt, int wf, int r, int h) {
;     ...
; #pragma unroll
;       for (int i = 0; i < 8; ++i) {
;         const int c = tid + NTHR * i, row = c >> 5, kc = c & 31;
;         const u32x4 d = *(const u32x4*)(es + row * EP + kc * 16);
;         const size_t off = (size_t)(m0 + hf * 128 + row) * 1024 + nt256 * 256 + kc * 8;
;         const u32x4 xo = *(const u32x4*)(ea.XB + off);
;         float xn[8];
; #pragma unroll
;         for (int j = 0; j < 4; ++j) { xn[2 * j] = bflo(xo[j]) + bflo(d[j]); xn[2 * j + 1] = bfhi(xo[j]) + bfhi(d[j]); }
;         if (ea.X) {
;           f32x4 o0 = {xn[0], xn[1], xn[2], xn[3]}, o1 = {xn[4], xn[5], xn[6], xn[7]};
;           __builtin_nontemporal_store(o0, (f32x4*)(ea.X + off)); __builtin_nontemporal_store(o1, (f32x4*)(ea.X + off + 4));
;         } else {
;           u32x4 w;
; #pragma unroll
;           for (int j = 0; j < 4; ++j) w[j] = pk2(xn[2 * j], xn[2 * j + 1]);
;           *(u32x4*)(ea.XB + off) = w;
.LBB0_233:
	s_nop 1
	v_add_u32_e32 v0, s33, v60
	v_ashrrev_i32_e32 v1, 31, v0
	v_lshlrev_b64 v[0:1], 10, v[0:1]
	v_lshl_add_u64 v[10:11], v[0:1], 0, v[8:9]
	v_lshl_add_u64 v[8:9], v[10:11], 1, s[62:63]
	ds_read_b128 v[4:7], v61
	s_and_b64 vcc, exec, s[6:7]
	s_waitcnt lgkmcnt(0)
	v_lshlrev_b32_e32 v2, 16, v4
	v_and_b32_e32 v3, 0xffff0000, v4
	v_lshlrev_b32_e32 v4, 16, v5
	v_and_b32_e32 v5, 0xffff0000, v5
	s_waitcnt vmcnt(7)
	v_mov_b32_e32 v12, v66
	v_mov_b32_e32 v13, v67
	v_mov_b32_e32 v14, v68
	v_mov_b32_e32 v15, v69
	v_lshlrev_b32_e32 v0, 16, v12
	v_and_b32_e32 v1, 0xffff0000, v12
	v_pk_add_f32 v[0:1], v[2:3], v[0:1]
	v_lshlrev_b32_e32 v2, 16, v13
	v_and_b32_e32 v3, 0xffff0000, v13
	v_pk_add_f32 v[2:3], v[4:5], v[2:3]
	v_lshlrev_b32_e32 v4, 16, v14
	v_and_b32_e32 v5, 0xffff0000, v14
	v_lshlrev_b32_e32 v12, 16, v6
	v_and_b32_e32 v13, 0xffff0000, v6
	v_pk_add_f32 v[4:5], v[12:13], v[4:5]
	v_lshlrev_b32_e32 v12, 16, v15
	v_and_b32_e32 v13, 0xffff0000, v15
	v_lshlrev_b32_e32 v6, 16, v7
	v_and_b32_e32 v7, 0xffff0000, v7
	v_pk_add_f32 v[6:7], v[6:7], v[12:13]
	s_cbranch_vccnz .LBB0_250
	v_lshl_add_u64 v[10:11], v[10:11], 2, s[8:9]
	global_store_dwordx4 v[10:11], v[0:3], off nt
	global_store_dwordx4 v[10:11], v[4:7], off offset:16 nt
	s_cbranch_execnz .LBB0_177
	s_branch .LBB0_176

; template <int EPI, bool RS>
; DI void gemm_phase(unsigned char* smem, const bf16_t* __restrict__ A, int lda, const bf16_t* __restrict__ Bt, int K, int mt0, int nMt, int nNt, const EpiArgs& ea) {
;     ...
;     f32x16 acc[2][4];
; #pragma unroll
;     for (int a = 0; a < 2; ++a)
; #pragma unroll
;       for (int b = 0; b < 4; ++b)
; #pragma unroll
;         for (int i = 0; i < 16; ++i) acc[a][b][i] = 0.f;
;     float ssq[4] = {0.f, 0.f, 0.f, 0.f};
.LBB0_279:
	v_mov_b32_e32 v191, 0
	s_mov_b64 s[2:3], 0
	s_mov_b32 s17, 1
	v_mov_b32_e32 v190, 0
	v_mov_b32_e32 v189, 0
	v_mov_b32_e32 v188, 0
	v_mov_b32_e32 v0, 0
	v_mov_b32_e32 v1, v191
	v_mov_b32_e32 v2, v191
	v_mov_b32_e32 v3, v191
	v_mov_b32_e32 v4, v191
	v_mov_b32_e32 v5, v191
	v_mov_b32_e32 v6, v191
	v_mov_b32_e32 v7, v191
	v_mov_b32_e32 v8, v191
	v_mov_b32_e32 v9, v191
	v_mov_b32_e32 v10, v191
	v_mov_b32_e32 v11, v191
	v_mov_b32_e32 v12, v191
	v_mov_b32_e32 v13, v191
	v_mov_b32_e32 v14, v191
	v_mov_b32_e32 v15, v191
	v_mov_b32_e32 v16, 0
	v_mov_b32_e32 v17, v191
	v_mov_b32_e32 v18, v191
	v_mov_b32_e32 v19, v191
	v_mov_b32_e32 v20, v191
	v_mov_b32_e32 v21, v191
	v_mov_b32_e32 v22, v191
	v_mov_b32_e32 v23, v191
	v_mov_b32_e32 v24, v191
	v_mov_b32_e32 v25, v191
	v_mov_b32_e32 v26, v191
	v_mov_b32_e32 v27, v191
	v_mov_b32_e32 v28, v191
	v_mov_b32_e32 v29, v191
	v_mov_b32_e32 v30, v191
	v_mov_b32_e32 v31, v191
	v_mov_b32_e32 v48, 0
	v_mov_b32_e32 v49, v191
	v_mov_b32_e32 v50, v191
	v_mov_b32_e32 v51, v191
	v_mov_b32_e32 v52, v191
	v_mov_b32_e32 v53, v191
	v_mov_b32_e32 v54, v191
	v_mov_b32_e32 v55, v191
	v_mov_b32_e32 v56, v191
	v_mov_b32_e32 v57, v191
	v_mov_b32_e32 v58, v191
	v_mov_b32_e32 v59, v191
	v_mov_b32_e32 v60, v191
	v_mov_b32_e32 v61, v191
	v_mov_b32_e32 v62, v191
	v_mov_b32_e32 v63, v191
	v_mov_b32_e32 v80, 0
	v_mov_b32_e32 v81, v191
	v_mov_b32_e32 v82, v191
	v_mov_b32_e32 v83, v191
	v_mov_b32_e32 v84, v191
	v_mov_b32_e32 v85, v191
	v_mov_b32_e32 v86, v191
	v_mov_b32_e32 v87, v191
	v_mov_b32_e32 v88, v191
	v_mov_b32_e32 v89, v191
	v_mov_b32_e32 v90, v191
	v_mov_b32_e32 v91, v191
	v_mov_b32_e32 v92, v191
	v_mov_b32_e32 v93, v191
	v_mov_b32_e32 v94, v191
	v_mov_b32_e32 v95, v191
	v_mov_b32_e32 v32, 0
	v_mov_b32_e32 v33, v191
	v_mov_b32_e32 v34, v191
	v_mov_b32_e32 v35, v191
	v_mov_b32_e32 v36, v191
	v_mov_b32_e32 v37, v191
	v_mov_b32_e32 v38, v191
	v_mov_b32_e32 v39, v191
	v_mov_b32_e32 v40, v191
	v_mov_b32_e32 v41, v191
	v_mov_b32_e32 v42, v191
	v_mov_b32_e32 v43, v191
	v_mov_b32_e32 v44, v191
	v_mov_b32_e32 v45, v191
	v_mov_b32_e32 v46, v191
	v_mov_b32_e32 v47, v191
	v_mov_b32_e32 v64, 0
	v_mov_b32_e32 v65, v191
	v_mov_b32_e32 v66, v191
	v_mov_b32_e32 v67, v191
	v_mov_b32_e32 v68, v191
	v_mov_b32_e32 v69, v191
	v_mov_b32_e32 v70, v191
	v_mov_b32_e32 v71, v191
	v_mov_b32_e32 v72, v191
	v_mov_b32_e32 v73, v191
	v_mov_b32_e32 v74, v191
	v_mov_b32_e32 v75, v191
	v_mov_b32_e32 v76, v191
	v_mov_b32_e32 v77, v191
	v_mov_b32_e32 v78, v191
	v_mov_b32_e32 v79, v191
	v_mov_b32_e32 v96, 0
	v_mov_b32_e32 v97, v191
	v_mov_b32_e32 v98, v191
	v_mov_b32_e32 v99, v191
	v_mov_b32_e32 v100, v191
	v_mov_b32_e32 v101, v191
	v_mov_b32_e32 v102, v191
	v_mov_b32_e32 v103, v191
	v_mov_b32_e32 v104, v191
	v_mov_b32_e32 v105, v191
	v_mov_b32_e32 v106, v191
	v_mov_b32_e32 v107, v191
	v_mov_b32_e32 v108, v191
	v_mov_b32_e32 v109, v191
	v_mov_b32_e32 v110, v191
	v_mov_b32_e32 v111, v191
	v_mov_b32_e32 v112, 0
	v_mov_b32_e32 v113, v191
	v_mov_b32_e32 v114, v191
	v_mov_b32_e32 v115, v191
	v_mov_b32_e32 v116, v191
	v_mov_b32_e32 v117, v191
	v_mov_b32_e32 v118, v191
	v_mov_b32_e32 v119, v191
	v_mov_b32_e32 v120, v191
	v_mov_b32_e32 v121, v191
	v_mov_b32_e32 v122, v191
	v_mov_b32_e32 v123, v191
	v_mov_b32_e32 v124, v191
	v_mov_b32_e32 v125, v191
	v_mov_b32_e32 v126, v191
	v_mov_b32_e32 v127, v191
	v_readfirstlane_b32 s100, v219
	s_nop 3
	s_bfe_u32 s100, s100, 0x20006
.LBB0_280:
	s_waitcnt lgkmcnt(3)
	s_nop 0
	v_mfma_f32_32x32x16_bf16 v[112:127], v[136:139], v[180:183], v[112:127]
	s_waitcnt lgkmcnt(2)
	s_waitcnt lgkmcnt(1)
	s_waitcnt lgkmcnt(0)
	v_mfma_f32_32x32x16_bf16 v[80:95], v[128:131], v[180:183], v[80:95]
	s_bitcmp1_b32 s17, 0
	s_cselect_b32 s0, 0, 0x12000
	v_mfma_f32_32x32x16_bf16 v[96:111], v[136:139], v[176:179], v[96:111]
	s_cselect_b32 s1, 0x12000, 0
	s_cmp_eq_u32 s100, 0
	s_cbranch_scc0 .Lgudot_skip0
	v_dot2c_f32_bf16_e32 v191, v180, v180
	v_dot2c_f32_bf16_e32 v190, v176, v176
	v_dot2c_f32_bf16_e32 v189, v140, v140
	v_dot2c_f32_bf16_e32 v188, v132, v132
	v_dot2c_f32_bf16_e32 v191, v181, v181
	v_dot2c_f32_bf16_e32 v190, v177, v177
	v_dot2c_f32_bf16_e32 v189, v141, v141
	v_dot2c_f32_bf16_e32 v188, v133, v133
	v_dot2c_f32_bf16_e32 v191, v182, v182
	v_dot2c_f32_bf16_e32 v190, v178, v178
	v_dot2c_f32_bf16_e32 v189, v142, v142
	v_dot2c_f32_bf16_e32 v188, v134, v134
	v_dot2c_f32_bf16_e32 v191, v183, v183
	v_dot2c_f32_bf16_e32 v190, v179, v179
	v_dot2c_f32_bf16_e32 v189, v143, v143
	v_dot2c_f32_bf16_e32 v188, v135, v135
.Lgudot_skip0:
	s_add_i32 s0, s0, 0
	s_add_i32 s20, s1, 0
	v_mfma_f32_32x32x16_bf16 v[48:63], v[128:131], v[176:179], v[48:63]
	v_mfma_f32_32x32x16_bf16 v[64:79], v[136:139], v[140:143], v[64:79]
	v_mfma_f32_32x32x16_bf16 v[16:31], v[128:131], v[140:143], v[16:31]
	v_mfma_f32_32x32x16_bf16 v[32:47], v[136:139], v[132:135], v[32:47]
	v_mfma_f32_32x32x16_bf16 v[0:15], v[128:131], v[132:135], v[0:15]
	v_lshl_add_u64 v[204:205], v[192:193], 0, s[2:3]
	v_add_u32_e32 v203, s20, v184
	v_add_co_u32_e32 v128, vcc, s42, v204
	v_lshl_add_u64 v[206:207], v[194:195], 0, s[2:3]
	s_waitcnt vmcnt(7)
	ds_write_b128 v203, v[148:151]
	s_waitcnt vmcnt(6)
	ds_write_b128 v203, v[144:147] offset:36864
	v_addc_co_u32_e32 v129, vcc, 0, v205, vcc
	global_load_dwordx4 v[148:151], v[204:205], off offset:256
	global_load_dwordx4 v[144:147], v[206:207], off offset:256
	s_waitcnt vmcnt(7)
	ds_write_b128 v203, v[152:155] offset:9216
	s_waitcnt vmcnt(6)
	ds_write_b128 v203, v[156:159] offset:46080
	v_add_co_u32_e32 v130, vcc, s42, v206
	v_add_u32_e32 v208, s0, v187
	s_nop 0
	v_addc_co_u32_e32 v131, vcc, 0, v207, vcc
	global_load_dwordx4 v[152:155], v[128:129], off offset:256
	global_load_dwordx4 v[156:159], v[130:131], off offset:256
	v_add_u32_e32 v209, s0, v186
	ds_read_b128 v[128:131], v208 offset:36896
	ds_read_b128 v[132:135], v208 offset:41504
	ds_read_b128 v[136:139], v209 offset:32
	ds_read_b128 v[140:143], v209 offset:4640
	ds_read_b128 v[176:179], v209 offset:9248
	ds_read_b128 v[180:183], v209 offset:13856
	s_waitcnt lgkmcnt(3)
	v_mfma_f32_32x32x16_bf16 v[112:127], v[128:131], v[136:139], v[112:127]
	s_waitcnt lgkmcnt(2)
	s_waitcnt lgkmcnt(1)
	s_waitcnt lgkmcnt(0)
	v_mfma_f32_32x32x16_bf16 v[80:95], v[132:135], v[136:139], v[80:95]
	v_mfma_f32_32x32x16_bf16 v[96:111], v[128:131], v[140:143], v[96:111]
	s_cmp_eq_u32 s100, 1
	s_cbranch_scc0 .Lgudot_skip1
	v_dot2c_f32_bf16_e32 v191, v136, v136
	v_dot2c_f32_bf16_e32 v190, v140, v140
	v_dot2c_f32_bf16_e32 v189, v176, v176
	v_dot2c_f32_bf16_e32 v188, v180, v180
	v_dot2c_f32_bf16_e32 v191, v137, v137
	v_dot2c_f32_bf16_e32 v190, v141, v141
	v_dot2c_f32_bf16_e32 v189, v177, v177
	v_dot2c_f32_bf16_e32 v188, v181, v181
	v_dot2c_f32_bf16_e32 v191, v138, v138
	v_dot2c_f32_bf16_e32 v190, v142, v142
	v_dot2c_f32_bf16_e32 v189, v178, v178
	v_dot2c_f32_bf16_e32 v188, v182, v182
	v_dot2c_f32_bf16_e32 v191, v139, v139
	v_dot2c_f32_bf16_e32 v190, v143, v143
	v_dot2c_f32_bf16_e32 v189, v179, v179
	v_dot2c_f32_bf16_e32 v188, v183, v183
.Lgudot_skip1:
	v_mfma_f32_32x32x16_bf16 v[48:63], v[132:135], v[140:143], v[48:63]
	v_mfma_f32_32x32x16_bf16 v[64:79], v[128:131], v[176:179], v[64:79]
	v_mfma_f32_32x32x16_bf16 v[16:31], v[132:135], v[176:179], v[16:31]
	v_mfma_f32_32x32x16_bf16 v[32:47], v[128:131], v[180:183], v[32:47]
	v_mfma_f32_32x32x16_bf16 v[0:15], v[132:135], v[180:183], v[0:15]
	v_add_co_u32_e32 v128, vcc, s43, v204
	s_waitcnt vmcnt(7)
	ds_write_b128 v203, v[160:163] offset:18432
	s_waitcnt vmcnt(6)
	ds_write_b128 v203, v[168:171] offset:55296
	v_addc_co_u32_e32 v129, vcc, 0, v205, vcc
	global_load_dwordx4 v[160:163], v[128:129], off offset:256
	v_add_co_u32_e32 v128, vcc, s43, v206
	s_nop 1
	v_addc_co_u32_e32 v129, vcc, 0, v207, vcc
	global_load_dwordx4 v[168:171], v[128:129], off offset:256
	v_add_co_u32_e32 v128, vcc, s75, v204
	s_waitcnt vmcnt(7)
	ds_write_b128 v203, v[164:167] offset:27648
	s_waitcnt vmcnt(6)
	ds_write_b128 v203, v[172:175] offset:64512
	v_addc_co_u32_e32 v129, vcc, 0, v205, vcc
	global_load_dwordx4 v[164:167], v[128:129], off offset:256
	v_add_co_u32_e32 v128, vcc, s75, v206
	s_nop 1
	v_addc_co_u32_e32 v129, vcc, 0, v207, vcc
	global_load_dwordx4 v[172:175], v[128:129], off offset:256
	ds_read_b128 v[128:131], v208 offset:36928
	ds_read_b128 v[132:135], v208 offset:41536
	ds_read_b128 v[136:139], v209 offset:64
	ds_read_b128 v[140:143], v209 offset:4672
	ds_read_b128 v[176:179], v209 offset:9280
	ds_read_b128 v[180:183], v209 offset:13888
	s_waitcnt lgkmcnt(3)
	v_mfma_f32_32x32x16_bf16 v[112:127], v[128:131], v[136:139], v[112:127]
	s_waitcnt lgkmcnt(2)
	s_waitcnt lgkmcnt(1)
	s_waitcnt lgkmcnt(0)
	v_mfma_f32_32x32x16_bf16 v[80:95], v[132:135], v[136:139], v[80:95]
	v_mfma_f32_32x32x16_bf16 v[96:111], v[128:131], v[140:143], v[96:111]
	s_cmp_eq_u32 s100, 2
	s_cbranch_scc0 .Lgudot_skip2
	v_dot2c_f32_bf16_e32 v191, v136, v136
	v_dot2c_f32_bf16_e32 v190, v140, v140
	v_dot2c_f32_bf16_e32 v189, v176, v176
	v_dot2c_f32_bf16_e32 v188, v180, v180
	v_dot2c_f32_bf16_e32 v191, v137, v137
	v_dot2c_f32_bf16_e32 v190, v141, v141
	v_dot2c_f32_bf16_e32 v189, v177, v177
	v_dot2c_f32_bf16_e32 v188, v181, v181
	v_dot2c_f32_bf16_e32 v191, v138, v138
	v_dot2c_f32_bf16_e32 v190, v142, v142
	v_dot2c_f32_bf16_e32 v189, v178, v178
	v_dot2c_f32_bf16_e32 v188, v182, v182
	v_dot2c_f32_bf16_e32 v191, v139, v139
	v_dot2c_f32_bf16_e32 v190, v143, v143
	v_dot2c_f32_bf16_e32 v189, v179, v179
	v_dot2c_f32_bf16_e32 v188, v183, v183
; #define G_ITER(R, kt_) do { const int k3 = (kt_) + 3; \
;         const char* pa = k3 < nk ? ga + k3 * 128 : ga_n + (k3 - nk) * 128; const char* pb = k3 < nk ? gb + k3 * 128 : gb_n + (k3 - nk) * 128; \
;         G_BODY(R, kt_, pa, pb); } while (0)
; template <int EPI, bool RS>
; DI void gemm_phase(unsigned char* smem, const bf16_t* __restrict__ A, int lda, const bf16_t* __restrict__ Bt, int K, int mt0, int nMt, int nNt, const EpiArgs& ea) {
;     ...
;     if (DEEP) {
;     ...
;       for (int kt = 0; kt < nk; kt += 2) { G_ITER(rg, kt); G_ITER(rh, kt + 1); }
;     ...
;     } else {
;       for (int kt = 0; kt < (XPR ? nk - 1 : nk); ++kt) {
;         const int k2 = kt + 2;
;         const char* pa = k2 < nk ? ga + k2 * 128 : ((XPF || XPR) ? ga_n + (k2 - nk) * 128 : ga);
;         const char* pb = k2 < nk ? gb + k2 * 128 : ((XPF || XPR) ? gb_n + (k2 - nk) * 128 : gb);
;         G_BODY(rg, kt, pa, pb);
.Lgudot_skip2:
	v_mfma_f32_32x32x16_bf16 v[48:63], v[132:135], v[140:143], v[48:63]
	v_mfma_f32_32x32x16_bf16 v[64:79], v[128:131], v[176:179], v[64:79]
	v_mfma_f32_32x32x16_bf16 v[16:31], v[132:135], v[176:179], v[16:31]
	v_mfma_f32_32x32x16_bf16 v[32:47], v[128:131], v[180:183], v[32:47]
	v_mfma_f32_32x32x16_bf16 v[0:15], v[132:135], v[180:183], v[0:15]
	ds_read_b128 v[128:131], v208 offset:36960
	ds_read_b128 v[132:135], v208 offset:41568
	ds_read_b128 v[136:139], v209 offset:96
	ds_read_b128 v[140:143], v209 offset:4704
	ds_read_b128 v[176:179], v209 offset:9312
	ds_read_b128 v[180:183], v209 offset:13920
	s_waitcnt lgkmcnt(3)
	v_mfma_f32_32x32x16_bf16 v[112:127], v[128:131], v[136:139], v[112:127]
	s_waitcnt lgkmcnt(2)
	s_waitcnt lgkmcnt(1)
	s_waitcnt lgkmcnt(0)
	v_mfma_f32_32x32x16_bf16 v[80:95], v[132:135], v[136:139], v[80:95]
	v_mfma_f32_32x32x16_bf16 v[96:111], v[128:131], v[140:143], v[96:111]
	s_cmp_eq_u32 s100, 3
	s_cbranch_scc0 .Lgudot_skip3
	v_dot2c_f32_bf16_e32 v191, v136, v136
	v_dot2c_f32_bf16_e32 v190, v140, v140
	v_dot2c_f32_bf16_e32 v189, v176, v176
	v_dot2c_f32_bf16_e32 v188, v180, v180
	v_dot2c_f32_bf16_e32 v191, v137, v137
	v_dot2c_f32_bf16_e32 v190, v141, v141
	v_dot2c_f32_bf16_e32 v189, v177, v177
	v_dot2c_f32_bf16_e32 v188, v181, v181
	v_dot2c_f32_bf16_e32 v191, v138, v138
	v_dot2c_f32_bf16_e32 v190, v142, v142
	v_dot2c_f32_bf16_e32 v189, v178, v178
	v_dot2c_f32_bf16_e32 v188, v182, v182
	v_dot2c_f32_bf16_e32 v191, v139, v139
	v_dot2c_f32_bf16_e32 v190, v143, v143
	v_dot2c_f32_bf16_e32 v189, v179, v179
	v_dot2c_f32_bf16_e32 v188, v183, v183
.Lgudot_skip3:
	s_barrier
	v_mfma_f32_32x32x16_bf16 v[48:63], v[132:135], v[140:143], v[48:63]
	v_mfma_f32_32x32x16_bf16 v[64:79], v[128:131], v[176:179], v[64:79]
	v_mfma_f32_32x32x16_bf16 v[16:31], v[132:135], v[176:179], v[16:31]
	v_mfma_f32_32x32x16_bf16 v[32:47], v[128:131], v[180:183], v[32:47]
	v_mfma_f32_32x32x16_bf16 v[0:15], v[132:135], v[180:183], v[0:15]
	v_add_u32_e32 v128, s20, v187
	v_add_u32_e32 v132, s20, v186
	ds_read_b128 v[136:139], v128 offset:36864
	ds_read_b128 v[128:131], v128 offset:41472
	ds_read_b128 v[180:183], v132
	ds_read_b128 v[176:179], v132 offset:4608
	ds_read_b128 v[140:143], v132 offset:9216
	ds_read_b128 v[132:135], v132 offset:13824
	s_add_u32 s2, s2, 0x80
	s_addc_u32 s3, s3, 0
	s_add_i32 s17, s17, 1
	s_cmpk_eq_i32 s2, 0x700
	s_cbranch_scc0 .LBB0_280
	s_waitcnt lgkmcnt(2)
	v_mfma_f32_32x32x16_bf16 v[48:63], v[128:131], v[176:179], v[48:63]
	s_ashr_i32 s17, s16, 31
	s_lshl_b32 s2, s70, 8
	s_lshl_b64 s[0:1], s[16:17], 11
	s_ashr_i32 s3, s2, 31
	s_add_u32 s20, s62, s0
	s_addc_u32 s21, s63, s1
	s_lshl_b64 s[0:1], s[2:3], 11
	s_waitcnt lgkmcnt(1)
	v_mfma_f32_32x32x16_bf16 v[16:31], v[128:131], v[140:143], v[16:31]
	s_waitcnt lgkmcnt(0)
	s_add_u32 s36, s53, s0
	v_mfma_f32_32x32x16_bf16 v[32:47], v[136:139], v[132:135], v[32:47]
	s_addc_u32 s37, s59, s1
	v_mfma_f32_32x32x16_bf16 v[0:15], v[128:131], v[132:135], v[0:15]
	s_cmp_eq_u32 s100, 0
	s_cbranch_scc0 .Lgudot_skip4
	v_dot2c_f32_bf16_e32 v191, v180, v180
	v_dot2c_f32_bf16_e32 v190, v176, v176
	v_dot2c_f32_bf16_e32 v189, v140, v140
	v_dot2c_f32_bf16_e32 v188, v132, v132
	v_dot2c_f32_bf16_e32 v191, v181, v181
	v_dot2c_f32_bf16_e32 v190, v177, v177
	v_dot2c_f32_bf16_e32 v189, v141, v141
	v_dot2c_f32_bf16_e32 v188, v133, v133
	v_dot2c_f32_bf16_e32 v191, v182, v182
	v_dot2c_f32_bf16_e32 v190, v178, v178
	v_dot2c_f32_bf16_e32 v189, v142, v142
	v_dot2c_f32_bf16_e32 v188, v134, v134
	v_dot2c_f32_bf16_e32 v191, v183, v183
	v_dot2c_f32_bf16_e32 v190, v179, v179
	v_dot2c_f32_bf16_e32 v189, v143, v143
	v_dot2c_f32_bf16_e32 v188, v135, v135
.Lgudot_skip4:
	v_mfma_f32_32x32x16_bf16 v[112:127], v[136:139], v[180:183], v[112:127]
	v_mfma_f32_32x32x16_bf16 v[80:95], v[128:131], v[180:183], v[80:95]
	v_mfma_f32_32x32x16_bf16 v[96:111], v[136:139], v[176:179], v[96:111]
	v_mfma_f32_32x32x16_bf16 v[64:79], v[136:139], v[140:143], v[64:79]
	v_lshl_add_u64 v[192:193], s[20:21], 0, v[216:217]
	v_add_co_u32_e32 v136, vcc, s42, v192
	v_lshl_add_u64 v[194:195], s[36:37], 0, v[216:217]
	s_nop 0
	v_addc_co_u32_e32 v137, vcc, 0, v193, vcc
	v_add_co_u32_e32 v140, vcc, s42, v194
	global_load_dwordx4 v[132:135], v[192:193], off
	global_load_dwordx4 v[128:131], v[194:195], off
	v_addc_co_u32_e32 v141, vcc, 0, v195, vcc
	global_load_dwordx4 v[136:139], v[136:137], off
	s_nop 0
	global_load_dwordx4 v[140:143], v[140:141], off
	v_add_u32_e32 v203, s35, v184
	s_waitcnt vmcnt(11)
	ds_write_b128 v203, v[148:151]
	s_waitcnt vmcnt(10)
	ds_write_b128 v203, v[144:147] offset:36864
	s_waitcnt vmcnt(9)
	ds_write_b128 v203, v[152:155] offset:9216
	s_waitcnt vmcnt(8)
	ds_write_b128 v203, v[156:159] offset:46080
	ds_read_b128 v[144:147], v202 offset:36896
	ds_read_b128 v[148:151], v202 offset:41504
	ds_read_b128 v[152:155], v201 offset:32
	ds_read_b128 v[156:159], v201 offset:4640
	ds_read_b128 v[176:179], v201 offset:9248
	ds_read_b128 v[180:183], v201 offset:13856
	s_waitcnt lgkmcnt(2)
	v_mfma_f32_32x32x16_bf16 v[48:63], v[148:151], v[156:159], v[48:63]
	s_waitcnt lgkmcnt(1)
	s_waitcnt lgkmcnt(0)
	v_mfma_f32_32x32x16_bf16 v[16:31], v[148:151], v[176:179], v[16:31]
	v_mfma_f32_32x32x16_bf16 v[32:47], v[144:147], v[180:183], v[32:47]
	s_cmp_eq_u32 s100, 1
	s_cbranch_scc0 .Lgudot_skip5
	v_dot2c_f32_bf16_e32 v191, v152, v152
	v_dot2c_f32_bf16_e32 v190, v156, v156
	v_dot2c_f32_bf16_e32 v189, v176, v176
	v_dot2c_f32_bf16_e32 v188, v180, v180
	v_dot2c_f32_bf16_e32 v191, v153, v153
	v_dot2c_f32_bf16_e32 v190, v157, v157
	v_dot2c_f32_bf16_e32 v189, v177, v177
	v_dot2c_f32_bf16_e32 v188, v181, v181
	v_dot2c_f32_bf16_e32 v191, v154, v154
	v_dot2c_f32_bf16_e32 v190, v158, v158
	v_dot2c_f32_bf16_e32 v189, v178, v178
	v_dot2c_f32_bf16_e32 v188, v182, v182
	v_dot2c_f32_bf16_e32 v191, v155, v155
	v_dot2c_f32_bf16_e32 v190, v159, v159
	v_dot2c_f32_bf16_e32 v189, v179, v179
	v_dot2c_f32_bf16_e32 v188, v183, v183
; #define G_FRAGS(F, sb, s) do { F[0] = *(const bf16x8*)((sb) + boff + (s) * 32); F[1] = *(const bf16x8*)((sb) + boff + 4608 + (s) * 32); \
;     _Pragma("unroll") for (int t_ = 0; t_ < 4; ++t_) F[2 + t_] = *(const bf16x8*)((sb) + aoff + t_ * 4608 + (s) * 32); } while (0)
; #define G_MMA(F) do { if (RS) { _Pragma("unroll") for (int t_ = 0; t_ < 4; ++t_) ssq[t_] = ssq8(F[2 + t_], ssq[t_]); } \
;     _Pragma("unroll") for (int t_ = 0; t_ < 4; ++t_) { acc[0][t_] = MFMA(F[0], F[2 + t_], acc[0][t_]); acc[1][t_] = MFMA(F[1], F[2 + t_], acc[1][t_]); } } while (0)
; #define SB() __builtin_amdgcn_sched_barrier(0)
; #define G_ITER(R, kt_) do { const int k3 = (kt_) + 3; \
;         const char* pa = k3 < nk ? ga + k3 * 128 : ga_n + (k3 - nk) * 128; const char* pb = k3 < nk ? gb + k3 * 128 : gb_n + (k3 - nk) * 128; \
;         G_BODY(R, kt_, pa, pb); } while (0)
; template <int EPI, bool RS>
; DI void gemm_phase(unsigned char* smem, const bf16_t* __restrict__ A, int lda, const bf16_t* __restrict__ Bt, int K, int mt0, int nMt, int nNt, const EpiArgs& ea) {
;     ...
;     if (DEEP) {
;     ...
;       for (int kt = 0; kt < nk; kt += 2) { G_ITER(rg, kt); G_ITER(rh, kt + 1); }
;     ...
;     } else {
;       for (int kt = 0; kt < (XPR ? nk - 1 : nk); ++kt) {
;         const int k2 = kt + 2;
;         const char* pa = k2 < nk ? ga + k2 * 128 : ((XPF || XPR) ? ga_n + (k2 - nk) * 128 : ga);
;         const char* pb = k2 < nk ? gb + k2 * 128 : ((XPF || XPR) ? gb_n + (k2 - nk) * 128 : gb);
;         G_BODY(rg, kt, pa, pb);
;       }
;       if (XPR) {
;         const unsigned char* sb_ = smem + 73728;
;         G_MMA(fa); SB(); G_FRAGS(fa, sb_, 1); SB();
;         G_MMA(fa); SB(); G_FRAGS(fa, sb_, 2); SB();
;         G_MMA(fa); SB(); G_FRAGS(fa, sb_, 3); SB();
;         __syncthreads();
;         G_MMA(fa); SB();
;       }
.Lgudot_skip5:
	v_mfma_f32_32x32x16_bf16 v[0:15], v[148:151], v[180:183], v[0:15]
	v_mfma_f32_32x32x16_bf16 v[112:127], v[144:147], v[152:155], v[112:127]
	v_mfma_f32_32x32x16_bf16 v[80:95], v[148:151], v[152:155], v[80:95]
	v_mfma_f32_32x32x16_bf16 v[96:111], v[144:147], v[156:159], v[96:111]
	v_mfma_f32_32x32x16_bf16 v[64:79], v[144:147], v[176:179], v[64:79]
	v_add_co_u32_e32 v144, vcc, s43, v192
	s_nop 1
	v_addc_co_u32_e32 v145, vcc, 0, v193, vcc
	v_add_co_u32_e32 v148, vcc, s43, v194
	s_nop 1
	v_addc_co_u32_e32 v149, vcc, 0, v195, vcc
	v_add_co_u32_e32 v152, vcc, s75, v192
	global_load_dwordx4 v[144:147], v[144:145], off
	s_nop 0
	global_load_dwordx4 v[148:151], v[148:149], off
	v_addc_co_u32_e32 v153, vcc, 0, v193, vcc
	v_add_co_u32_e32 v156, vcc, s75, v194
	s_nop 1
	v_addc_co_u32_e32 v157, vcc, 0, v195, vcc
	global_load_dwordx4 v[152:155], v[152:153], off
	s_nop 0
	global_load_dwordx4 v[156:159], v[156:157], off
	s_waitcnt vmcnt(11)
	ds_write_b128 v203, v[160:163] offset:18432
	s_waitcnt vmcnt(10)
	ds_write_b128 v203, v[168:171] offset:55296
	s_waitcnt vmcnt(9)
	ds_write_b128 v203, v[164:167] offset:27648
	s_waitcnt vmcnt(8)
	ds_write_b128 v203, v[172:175] offset:64512
	ds_read_b128 v[160:163], v202 offset:36928
	ds_read_b128 v[164:167], v202 offset:41536
	ds_read_b128 v[168:171], v201 offset:64
	ds_read_b128 v[172:175], v201 offset:4672
	ds_read_b128 v[176:179], v201 offset:9280
	ds_read_b128 v[180:183], v201 offset:13888
	s_waitcnt lgkmcnt(2)
	v_mfma_f32_32x32x16_bf16 v[48:63], v[164:167], v[172:175], v[48:63]
	s_waitcnt lgkmcnt(1)
	s_waitcnt lgkmcnt(0)
	v_mfma_f32_32x32x16_bf16 v[16:31], v[164:167], v[176:179], v[16:31]
	v_mfma_f32_32x32x16_bf16 v[32:47], v[160:163], v[180:183], v[32:47]
	s_cmp_eq_u32 s100, 2
	s_cbranch_scc0 .Lgudot_skip6
	v_dot2c_f32_bf16_e32 v191, v168, v168
	v_dot2c_f32_bf16_e32 v190, v172, v172
	v_dot2c_f32_bf16_e32 v189, v176, v176
	v_dot2c_f32_bf16_e32 v188, v180, v180
	v_dot2c_f32_bf16_e32 v191, v169, v169
	v_dot2c_f32_bf16_e32 v190, v173, v173
	v_dot2c_f32_bf16_e32 v189, v177, v177
	v_dot2c_f32_bf16_e32 v188, v181, v181
	v_dot2c_f32_bf16_e32 v191, v170, v170
	v_dot2c_f32_bf16_e32 v190, v174, v174
	v_dot2c_f32_bf16_e32 v189, v178, v178
	v_dot2c_f32_bf16_e32 v188, v182, v182
	v_dot2c_f32_bf16_e32 v191, v171, v171
	v_dot2c_f32_bf16_e32 v190, v175, v175
	v_dot2c_f32_bf16_e32 v189, v179, v179
	v_dot2c_f32_bf16_e32 v188, v183, v183
.Lgudot_skip6:
	v_mfma_f32_32x32x16_bf16 v[0:15], v[164:167], v[180:183], v[0:15]
	v_mfma_f32_32x32x16_bf16 v[112:127], v[160:163], v[168:171], v[112:127]
	v_mfma_f32_32x32x16_bf16 v[80:95], v[164:167], v[168:171], v[80:95]
	v_mfma_f32_32x32x16_bf16 v[96:111], v[160:163], v[172:175], v[96:111]
	v_mfma_f32_32x32x16_bf16 v[64:79], v[160:163], v[176:179], v[64:79]
	ds_read_b128 v[160:163], v202 offset:36960
	ds_read_b128 v[164:167], v202 offset:41568
	ds_read_b128 v[168:171], v201 offset:96
	ds_read_b128 v[172:175], v201 offset:4704
	ds_read_b128 v[176:179], v201 offset:9312
	ds_read_b128 v[180:183], v201 offset:13920
	s_waitcnt lgkmcnt(2)
	v_mfma_f32_32x32x16_bf16 v[48:63], v[164:167], v[172:175], v[48:63]
	s_waitcnt lgkmcnt(1)
	s_waitcnt lgkmcnt(0)
	v_mfma_f32_32x32x16_bf16 v[16:31], v[164:167], v[176:179], v[16:31]
	s_barrier
	v_mfma_f32_32x32x16_bf16 v[32:47], v[160:163], v[180:183], v[32:47]
	s_cmp_eq_u32 s100, 3
	s_cbranch_scc0 .Lgudot_skip7
	v_dot2c_f32_bf16_e32 v191, v168, v168
	v_dot2c_f32_bf16_e32 v190, v172, v172
	v_dot2c_f32_bf16_e32 v189, v176, v176
	v_dot2c_f32_bf16_e32 v188, v180, v180
	v_dot2c_f32_bf16_e32 v191, v169, v169
	v_dot2c_f32_bf16_e32 v190, v173, v173
	v_dot2c_f32_bf16_e32 v189, v177, v177
	v_dot2c_f32_bf16_e32 v188, v181, v181
	v_dot2c_f32_bf16_e32 v191, v170, v170
	v_dot2c_f32_bf16_e32 v190, v174, v174
	v_dot2c_f32_bf16_e32 v189, v178, v178
	v_dot2c_f32_bf16_e32 v188, v182, v182
	v_dot2c_f32_bf16_e32 v191, v171, v171
	v_dot2c_f32_bf16_e32 v190, v175, v175
	v_dot2c_f32_bf16_e32 v189, v179, v179
	v_dot2c_f32_bf16_e32 v188, v183, v183
.Lgudot_skip7:
	v_mfma_f32_32x32x16_bf16 v[0:15], v[164:167], v[180:183], v[0:15]
	v_mfma_f32_32x32x16_bf16 v[112:127], v[160:163], v[168:171], v[112:127]
	v_mfma_f32_32x32x16_bf16 v[80:95], v[164:167], v[168:171], v[80:95]
	v_mfma_f32_32x32x16_bf16 v[96:111], v[160:163], v[172:175], v[96:111]
	v_mfma_f32_32x32x16_bf16 v[64:79], v[160:163], v[176:179], v[64:79]
	v_add_u32_e32 v192, s35, v186
	ds_read_b128 v[160:163], v200
	ds_read_b128 v[164:167], v200 offset:4608
	ds_read_b128 v[168:171], v192
	ds_read_b128 v[172:175], v192 offset:4608
	ds_read_b128 v[176:179], v192 offset:9216
	ds_read_b128 v[180:183], v192 offset:13824
	s_waitcnt lgkmcnt(2)
	v_mfma_f32_32x32x16_bf16 v[48:63], v[164:167], v[172:175], v[48:63]
	s_waitcnt lgkmcnt(1)
	s_waitcnt lgkmcnt(0)
	v_mfma_f32_32x32x16_bf16 v[16:31], v[164:167], v[176:179], v[16:31]
	v_mfma_f32_32x32x16_bf16 v[32:47], v[160:163], v[180:183], v[32:47]
	s_cmp_eq_u32 s100, 0
	s_cbranch_scc0 .Lgudot_skip8
	v_dot2c_f32_bf16_e32 v191, v168, v168
	v_dot2c_f32_bf16_e32 v190, v172, v172
	v_dot2c_f32_bf16_e32 v189, v176, v176
	v_dot2c_f32_bf16_e32 v188, v180, v180
	v_dot2c_f32_bf16_e32 v191, v169, v169
	v_dot2c_f32_bf16_e32 v190, v173, v173
	v_dot2c_f32_bf16_e32 v189, v177, v177
	v_dot2c_f32_bf16_e32 v188, v181, v181
	v_dot2c_f32_bf16_e32 v191, v170, v170
	v_dot2c_f32_bf16_e32 v190, v174, v174
	v_dot2c_f32_bf16_e32 v189, v178, v178
	v_dot2c_f32_bf16_e32 v188, v182, v182
	v_dot2c_f32_bf16_e32 v191, v171, v171
	v_dot2c_f32_bf16_e32 v190, v175, v175
	v_dot2c_f32_bf16_e32 v189, v179, v179
	v_dot2c_f32_bf16_e32 v188, v183, v183
; #define G_FRAGS(F, sb, s) do { F[0] = *(const bf16x8*)((sb) + boff + (s) * 32); F[1] = *(const bf16x8*)((sb) + boff + 4608 + (s) * 32); \
;     _Pragma("unroll") for (int t_ = 0; t_ < 4; ++t_) F[2 + t_] = *(const bf16x8*)((sb) + aoff + t_ * 4608 + (s) * 32); } while (0)
; #define G_MMA(F) do { if (RS) { _Pragma("unroll") for (int t_ = 0; t_ < 4; ++t_) ssq[t_] = ssq8(F[2 + t_], ssq[t_]); } \
;     _Pragma("unroll") for (int t_ = 0; t_ < 4; ++t_) { acc[0][t_] = MFMA(F[0], F[2 + t_], acc[0][t_]); acc[1][t_] = MFMA(F[1], F[2 + t_], acc[1][t_]); } } while (0)
; #define SB() __builtin_amdgcn_sched_barrier(0)
; template <int EPI, bool RS>
; DI void gemm_phase(unsigned char* smem, const bf16_t* __restrict__ A, int lda, const bf16_t* __restrict__ Bt, int K, int mt0, int nMt, int nNt, const EpiArgs& ea) {
;     ...
;       if (XPR) {
;         const unsigned char* sb_ = smem + 73728;
;         G_MMA(fa); SB(); G_FRAGS(fa, sb_, 1); SB();
;         G_MMA(fa); SB(); G_FRAGS(fa, sb_, 2); SB();
;         G_MMA(fa); SB(); G_FRAGS(fa, sb_, 3); SB();
;         __syncthreads();
;         G_MMA(fa); SB();
;       }
.Lgudot_skip8:
	v_mfma_f32_32x32x16_bf16 v[0:15], v[164:167], v[180:183], v[0:15]
	v_mfma_f32_32x32x16_bf16 v[112:127], v[160:163], v[168:171], v[112:127]
	v_mfma_f32_32x32x16_bf16 v[80:95], v[164:167], v[168:171], v[80:95]
	v_mfma_f32_32x32x16_bf16 v[96:111], v[160:163], v[172:175], v[96:111]
	v_mfma_f32_32x32x16_bf16 v[64:79], v[160:163], v[176:179], v[64:79]
	ds_read_b128 v[160:163], v200 offset:32
	ds_read_b128 v[164:167], v200 offset:4640
	ds_read_b128 v[168:171], v192 offset:32
	ds_read_b128 v[172:175], v192 offset:4640
	ds_read_b128 v[176:179], v192 offset:9248
	ds_read_b128 v[180:183], v192 offset:13856
	s_waitcnt lgkmcnt(2)
	v_mfma_f32_32x32x16_bf16 v[48:63], v[164:167], v[172:175], v[48:63]
	s_waitcnt lgkmcnt(1)
	s_waitcnt lgkmcnt(0)
	v_mfma_f32_32x32x16_bf16 v[16:31], v[164:167], v[176:179], v[16:31]
	v_mfma_f32_32x32x16_bf16 v[32:47], v[160:163], v[180:183], v[32:47]
	s_cmp_eq_u32 s100, 1
	s_cbranch_scc0 .Lgudot_skip9
	v_dot2c_f32_bf16_e32 v191, v168, v168
	v_dot2c_f32_bf16_e32 v190, v172, v172
	v_dot2c_f32_bf16_e32 v189, v176, v176
	v_dot2c_f32_bf16_e32 v188, v180, v180
	v_dot2c_f32_bf16_e32 v191, v169, v169
	v_dot2c_f32_bf16_e32 v190, v173, v173
	v_dot2c_f32_bf16_e32 v189, v177, v177
	v_dot2c_f32_bf16_e32 v188, v181, v181
	v_dot2c_f32_bf16_e32 v191, v170, v170
	v_dot2c_f32_bf16_e32 v190, v174, v174
	v_dot2c_f32_bf16_e32 v189, v178, v178
	v_dot2c_f32_bf16_e32 v188, v182, v182
	v_dot2c_f32_bf16_e32 v191, v171, v171
	v_dot2c_f32_bf16_e32 v190, v175, v175
	v_dot2c_f32_bf16_e32 v189, v179, v179
	v_dot2c_f32_bf16_e32 v188, v183, v183
.Lgudot_skip9:
	v_mfma_f32_32x32x16_bf16 v[0:15], v[164:167], v[180:183], v[0:15]
	v_mfma_f32_32x32x16_bf16 v[112:127], v[160:163], v[168:171], v[112:127]
	v_mfma_f32_32x32x16_bf16 v[80:95], v[164:167], v[168:171], v[80:95]
	v_mfma_f32_32x32x16_bf16 v[96:111], v[160:163], v[172:175], v[96:111]
	v_mfma_f32_32x32x16_bf16 v[64:79], v[160:163], v[176:179], v[64:79]
	ds_read_b128 v[160:163], v200 offset:64
	ds_read_b128 v[164:167], v200 offset:4672
	ds_read_b128 v[168:171], v192 offset:64
	ds_read_b128 v[172:175], v192 offset:4672
	ds_read_b128 v[176:179], v192 offset:9280
	ds_read_b128 v[180:183], v192 offset:13888
	s_waitcnt lgkmcnt(2)
	v_mfma_f32_32x32x16_bf16 v[48:63], v[164:167], v[172:175], v[48:63]
	s_waitcnt lgkmcnt(1)
	s_waitcnt lgkmcnt(0)
	v_mfma_f32_32x32x16_bf16 v[16:31], v[164:167], v[176:179], v[16:31]
	v_mfma_f32_32x32x16_bf16 v[32:47], v[160:163], v[180:183], v[32:47]
	s_cmp_eq_u32 s100, 2
	s_cbranch_scc0 .Lgudot_skip10
	v_dot2c_f32_bf16_e32 v191, v168, v168
	v_dot2c_f32_bf16_e32 v190, v172, v172
	v_dot2c_f32_bf16_e32 v189, v176, v176
	v_dot2c_f32_bf16_e32 v188, v180, v180
	v_dot2c_f32_bf16_e32 v191, v169, v169
	v_dot2c_f32_bf16_e32 v190, v173, v173
	v_dot2c_f32_bf16_e32 v189, v177, v177
	v_dot2c_f32_bf16_e32 v188, v181, v181
	v_dot2c_f32_bf16_e32 v191, v170, v170
	v_dot2c_f32_bf16_e32 v190, v174, v174
	v_dot2c_f32_bf16_e32 v189, v178, v178
	v_dot2c_f32_bf16_e32 v188, v182, v182
	v_dot2c_f32_bf16_e32 v191, v171, v171
	v_dot2c_f32_bf16_e32 v190, v175, v175
	v_dot2c_f32_bf16_e32 v189, v179, v179
	v_dot2c_f32_bf16_e32 v188, v183, v183
.Lgudot_skip10:
	v_mfma_f32_32x32x16_bf16 v[0:15], v[164:167], v[180:183], v[0:15]
	v_mfma_f32_32x32x16_bf16 v[112:127], v[160:163], v[168:171], v[112:127]
	v_mfma_f32_32x32x16_bf16 v[80:95], v[164:167], v[168:171], v[80:95]
	v_mfma_f32_32x32x16_bf16 v[96:111], v[160:163], v[172:175], v[96:111]
	v_mfma_f32_32x32x16_bf16 v[64:79], v[160:163], v[176:179], v[64:79]
	ds_read_b128 v[160:163], v200 offset:96
	ds_read_b128 v[164:167], v200 offset:4704
	ds_read_b128 v[168:171], v192 offset:96
	ds_read_b128 v[172:175], v192 offset:4704
	ds_read_b128 v[176:179], v192 offset:9312
	ds_read_b128 v[180:183], v192 offset:13920
	s_waitcnt lgkmcnt(2)
	v_mfma_f32_32x32x16_bf16 v[48:63], v[164:167], v[172:175], v[48:63]
	s_waitcnt lgkmcnt(1)
	s_waitcnt lgkmcnt(0)
	v_mfma_f32_32x32x16_bf16 v[16:31], v[164:167], v[176:179], v[16:31]
	s_barrier
	v_mfma_f32_32x32x16_bf16 v[32:47], v[160:163], v[180:183], v[32:47]
	s_cmp_eq_u32 s100, 3
	s_cbranch_scc0 .Lgudot_skip11
	v_dot2c_f32_bf16_e32 v191, v168, v168
	v_dot2c_f32_bf16_e32 v190, v172, v172
	v_dot2c_f32_bf16_e32 v189, v176, v176
	v_dot2c_f32_bf16_e32 v188, v180, v180
	v_dot2c_f32_bf16_e32 v191, v169, v169
	v_dot2c_f32_bf16_e32 v190, v173, v173
	v_dot2c_f32_bf16_e32 v189, v177, v177
	v_dot2c_f32_bf16_e32 v188, v181, v181
	v_dot2c_f32_bf16_e32 v191, v170, v170
	v_dot2c_f32_bf16_e32 v190, v174, v174
	v_dot2c_f32_bf16_e32 v189, v178, v178
	v_dot2c_f32_bf16_e32 v188, v182, v182
	v_dot2c_f32_bf16_e32 v191, v171, v171
	v_dot2c_f32_bf16_e32 v190, v175, v175
	v_dot2c_f32_bf16_e32 v189, v179, v179
	v_dot2c_f32_bf16_e32 v188, v183, v183
; template <int EPI, bool RS>
; DI void gemm_epilogue(unsigned char* smem, f32x16 (&acc)[2][4], const float (&ssq)[4], int K, int m0, int nt256, const EpiArgs& ea, int wt, int wf, int r, int h) {
;   asm volatile("" : "+v"(r), "+v"(h));
;   const int nt = nt256 * 2 + (wf >> 1), wc = wf & 1;
;   const int n0 = nt * 128;
;   float rstd[4] = {1.f, 1.f, 1.f, 1.f};
;   if (RS) {
; #pragma unroll
;     for (int tb = 0; tb < 4; ++tb) { float s = ssq[tb]; s += __shfl_xor(s, 32); rstd[tb] = rsqrtf(s / (float)K + EPS); }
;     ...
;     {
;       unsigned char* dst = smem + (wf < 2 ? 0 : 73728);
; #pragma unroll
;       for (int tb = 0; tb < 4; ++tb) {
;         const int rr = wt * 128 + tb * 32 + r; const float rs = rstd[tb];
; #pragma unroll
;         for (int fb = 0; fb < 2; ++fb)
; #pragma unroll
;           for (int g4 = 0; g4 < 4; ++g4) {
;             const int f = fw + fb * 32 + g4 * 8 + 4 * h;
;             u32x2 w; w[0] = pk2(acc[fb][tb][4 * g4] * rs, acc[fb][tb][4 * g4 + 1] * rs); w[1] = pk2(acc[fb][tb][4 * g4 + 2] * rs, acc[fb][tb][4 * g4 + 3] * rs);
;             *(u32x2*)(dst + rr * GP + f * 2) = w;
;           }
;       }
;     }
.Lgudot_skip11:
	v_mfma_f32_32x32x16_bf16 v[0:15], v[164:167], v[180:183], v[0:15]
	v_mfma_f32_32x32x16_bf16 v[112:127], v[160:163], v[168:171], v[112:127]
	v_mfma_f32_32x32x16_bf16 v[80:95], v[164:167], v[168:171], v[80:95]
	v_mfma_f32_32x32x16_bf16 v[96:111], v[160:163], v[172:175], v[96:111]
	v_mfma_f32_32x32x16_bf16 v[64:79], v[160:163], v[176:179], v[64:79]
	v_lshlrev_b32_e32 v210, 2, v219
	v_add_u32_e32 v210, 0x24010, v210
	ds_write_b32 v210, v191
	ds_write_b32 v210, v190 offset:2048
	ds_write_b32 v210, v189 offset:4096
	ds_write_b32 v210, v188 offset:6144
	v_and_b32_e32 v211, 0x13f, v219
	v_lshlrev_b32_e32 v211, 2, v211
	v_add_u32_e32 v211, 0x24010, v211
	s_waitcnt lgkmcnt(0)
	s_barrier
	ds_read_b32 v212, v211
	ds_read_b32 v213, v211 offset:256
	ds_read_b32 v214, v211 offset:512
	ds_read_b32 v215, v211 offset:768
	ds_read_b32 v220, v211 offset:2048
	ds_read_b32 v221, v211 offset:2304
	ds_read_b32 v222, v211 offset:2560
	ds_read_b32 v223, v211 offset:2816
	ds_read_b32 v224, v211 offset:4096
	ds_read_b32 v225, v211 offset:4352
	ds_read_b32 v226, v211 offset:4608
	ds_read_b32 v227, v211 offset:4864
	ds_read_b32 v228, v211 offset:6144
	ds_read_b32 v229, v211 offset:6400
	ds_read_b32 v230, v211 offset:6656
	ds_read_b32 v231, v211 offset:6912
	s_waitcnt lgkmcnt(0)
	v_add_f32_e32 v191, v212, v213
	v_add_f32_e32 v191, v191, v214
	v_add_f32_e32 v191, v191, v215
	v_add_f32_e32 v190, v220, v221
	v_add_f32_e32 v190, v190, v222
	v_add_f32_e32 v190, v190, v223
	v_add_f32_e32 v189, v224, v225
	v_add_f32_e32 v189, v189, v226
	v_add_f32_e32 v189, v189, v227
	v_add_f32_e32 v188, v228, v229
	v_add_f32_e32 v188, v188, v230
	v_add_f32_e32 v188, v188, v231
	v_and_b32_e32 v161, 64, v253
	v_xor_b32_e32 v160, 32, v253
	v_add_u32_e32 v161, 64, v161
	v_cmp_lt_i32_e32 vcc, v160, v161
	s_mov_b32 s0, 0x358637bd
	v_mov_b64_e32 v[162:163], s[0:1]
	v_cndmask_b32_e32 v160, v253, v160, vcc
	v_lshlrev_b32_e32 v166, 2, v160
	ds_bpermute_b32 v161, v166, v191
	ds_bpermute_b32 v160, v166, v190
	s_mov_b32 s0, 0x3a800000
	v_mov_b32_e32 v164, v196
	v_mov_b32_e32 v165, v197
	s_waitcnt lgkmcnt(0)
	v_pk_add_f32 v[160:161], v[190:191], v[160:161]
	s_mov_b32 s76, 0x3a800000
	v_pk_fma_f32 v[160:161], v[160:161], s[0:1], v[162:163] op_sel_hi:[1,0,0]
	s_nop 0
	v_mul_f32_e32 v167, 0x4b800000, v161
	v_cmp_gt_f32_e64 s[2:3], s67, v161
	v_cmp_gt_f32_e32 vcc, s67, v160
	s_nop 0
	v_cndmask_b32_e64 v161, v161, v167, s[2:3]
	v_rsq_f32_e32 v161, v161
	s_nop 0
	v_mul_f32_e32 v167, 0x45800000, v161
	v_cndmask_b32_e64 v167, v161, v167, s[2:3]
	v_mul_f32_e32 v161, 0x4b800000, v160
	v_cndmask_b32_e32 v160, v160, v161, vcc
	v_rsq_f32_e32 v160, v160
	v_mul_f32_e32 v80, v80, v167
	v_mul_f32_e32 v81, v81, v167
	v_cvt_pk_bf16_f32 v80, v80, v81
	v_mul_f32_e32 v161, 0x45800000, v160
	v_cndmask_b32_e32 v168, v160, v161, vcc
	ds_bpermute_b32 v161, v166, v189
	ds_bpermute_b32 v160, v166, v188
	v_mul_f32_e32 v81, v82, v167
	v_mul_f32_e32 v82, v83, v167
	v_cvt_pk_bf16_f32 v81, v81, v82
	v_mul_f32_e32 v82, v84, v167
	s_waitcnt lgkmcnt(0)
	v_pk_add_f32 v[160:161], v[188:189], v[160:161]
	v_mul_f32_e32 v83, v85, v167
	v_pk_fma_f32 v[160:161], v[160:161], s[0:1], v[162:163] op_sel_hi:[1,0,0]
	s_movk_i32 s1, 0x110
	v_mul_f32_e32 v162, 0x4b800000, v161
	v_cmp_gt_f32_e64 s[2:3], s67, v161
	v_cmp_gt_f32_e32 vcc, s67, v160
	v_lshlrev_b32_e32 v163, 3, v165
	v_cndmask_b32_e64 v161, v161, v162, s[2:3]
	v_rsq_f32_e32 v161, v161
	v_cvt_pk_bf16_f32 v82, v82, v83
	v_mul_f32_e32 v83, v86, v167
	v_mul_f32_e32 v84, v87, v167
	v_mul_f32_e32 v162, 0x45800000, v161
	v_cndmask_b32_e64 v161, v161, v162, s[2:3]
	v_mul_f32_e32 v162, 0x4b800000, v160
	v_cndmask_b32_e32 v160, v160, v162, vcc
	v_rsq_f32_e32 v160, v160
	v_cvt_pk_bf16_f32 v83, v83, v84
	v_mul_f32_e32 v84, v95, v167
	v_mul_f32_e32 v48, v48, v168
	v_mul_f32_e32 v162, 0x45800000, v160
	v_cndmask_b32_e32 v160, v160, v162, vcc
	v_add_u32_e32 v162, v164, v185
	v_mul_lo_u32 v162, v162, s1
	v_add3_u32 v162, v198, v163, v162
	ds_write2_b64 v162, v[80:81], v[82:83] offset0:8 offset1:10
	v_mul_f32_e32 v80, v88, v167
	v_mul_f32_e32 v81, v89, v167
	v_cvt_pk_bf16_f32 v80, v80, v81
	v_mul_f32_e32 v81, v90, v167
	v_mul_f32_e32 v82, v91, v167
	v_cvt_pk_bf16_f32 v81, v81, v82
	v_mul_f32_e32 v82, v92, v167
	v_mul_f32_e32 v83, v93, v167
	v_cvt_pk_bf16_f32 v82, v82, v83
	v_mul_f32_e32 v83, v94, v167
	v_cvt_pk_bf16_f32 v83, v83, v84
	ds_write2_b64 v162, v[80:81], v[82:83] offset0:12 offset1:14
	v_mul_f32_e32 v80, v96, v168
	v_mul_f32_e32 v81, v97, v168
	v_mul_f32_e32 v49, v49, v168
	v_cvt_pk_bf16_f32 v80, v80, v81
	v_mul_f32_e32 v81, v98, v168
	v_mul_f32_e32 v82, v99, v168
	v_cvt_pk_bf16_f32 v48, v48, v49
	v_mul_f32_e32 v49, v50, v168
	v_mul_f32_e32 v50, v51, v168
	v_cvt_pk_bf16_f32 v81, v81, v82
	v_mul_f32_e32 v82, v100, v168
	v_mul_f32_e32 v83, v101, v168
	v_cvt_pk_bf16_f32 v49, v49, v50
	v_mul_f32_e32 v50, v52, v168
	v_mul_f32_e32 v51, v53, v168
	v_cvt_pk_bf16_f32 v82, v82, v83
	v_mul_f32_e32 v83, v102, v168
	v_mul_f32_e32 v84, v103, v168
	v_cvt_pk_bf16_f32 v50, v50, v51
	v_mul_f32_e32 v51, v54, v168
	v_mul_f32_e32 v52, v55, v168
	v_cvt_pk_bf16_f32 v83, v83, v84
	v_add_u32_e32 v84, 0x2000, v162
	v_cvt_pk_bf16_f32 v51, v51, v52
	ds_write2_b64 v84, v[48:49], v[50:51] offset0:72 offset1:74
	v_mul_f32_e32 v48, v56, v168
	v_mul_f32_e32 v49, v57, v168
	v_cvt_pk_bf16_f32 v48, v48, v49
	v_mul_f32_e32 v49, v58, v168
	v_mul_f32_e32 v50, v59, v168
	v_cvt_pk_bf16_f32 v49, v49, v50
	v_mul_f32_e32 v50, v60, v168
	v_mul_f32_e32 v51, v61, v168
	v_cvt_pk_bf16_f32 v50, v50, v51
	v_mul_f32_e32 v51, v62, v168
	v_mul_f32_e32 v52, v63, v168
	v_cvt_pk_bf16_f32 v51, v51, v52
	ds_write2_b64 v84, v[48:49], v[50:51] offset0:76 offset1:78
; template <int EPI, bool RS>
; DI void gemm_epilogue(unsigned char* smem, f32x16 (&acc)[2][4], const float (&ssq)[4], int K, int m0, int nt256, const EpiArgs& ea, int wt, int wf, int r, int h) {
;     ...
;     {
;       unsigned char* dst = smem + (wf < 2 ? 0 : 73728);
; #pragma unroll
;       for (int tb = 0; tb < 4; ++tb) {
;         const int rr = wt * 128 + tb * 32 + r; const float rs = rstd[tb];
; #pragma unroll
;         for (int fb = 0; fb < 2; ++fb)
; #pragma unroll
;           for (int g4 = 0; g4 < 4; ++g4) {
;             const int f = fw + fb * 32 + g4 * 8 + 4 * h;
;             u32x2 w; w[0] = pk2(acc[fb][tb][4 * g4] * rs, acc[fb][tb][4 * g4 + 1] * rs); w[1] = pk2(acc[fb][tb][4 * g4 + 2] * rs, acc[fb][tb][4 * g4 + 3] * rs);
;             *(u32x2*)(dst + rr * GP + f * 2) = w;
;           }
;       }
;     }
;     __syncthreads();
	v_mul_f32_e32 v48, v64, v161
	v_mul_f32_e32 v49, v65, v161
	v_mul_f32_e32 v16, v16, v161
	v_mul_f32_e32 v17, v17, v161
	v_cvt_pk_bf16_f32 v48, v48, v49
	v_mul_f32_e32 v49, v66, v161
	v_mul_f32_e32 v50, v67, v161
	v_cvt_pk_bf16_f32 v16, v16, v17
	v_mul_f32_e32 v17, v18, v161
	v_mul_f32_e32 v18, v19, v161
	v_cvt_pk_bf16_f32 v49, v49, v50
	v_mul_f32_e32 v50, v68, v161
	v_mul_f32_e32 v51, v69, v161
	v_cvt_pk_bf16_f32 v17, v17, v18
	v_mul_f32_e32 v18, v20, v161
	v_mul_f32_e32 v19, v21, v161
	v_cvt_pk_bf16_f32 v50, v50, v51
	v_mul_f32_e32 v51, v70, v161
	v_mul_f32_e32 v52, v71, v161
	v_cvt_pk_bf16_f32 v18, v18, v19
	v_mul_f32_e32 v19, v22, v161
	v_mul_f32_e32 v20, v23, v161
	v_cvt_pk_bf16_f32 v51, v51, v52
	v_add_u32_e32 v52, 0x4000, v162
	v_cvt_pk_bf16_f32 v19, v19, v20
	ds_write2_b64 v52, v[16:17], v[18:19] offset0:136 offset1:138
	v_mul_f32_e32 v16, v24, v161
	v_mul_f32_e32 v17, v25, v161
	v_cvt_pk_bf16_f32 v16, v16, v17
	v_mul_f32_e32 v17, v26, v161
	v_mul_f32_e32 v18, v27, v161
	v_cvt_pk_bf16_f32 v17, v17, v18
	v_mul_f32_e32 v18, v28, v161
	v_mul_f32_e32 v19, v29, v161
	v_cvt_pk_bf16_f32 v18, v18, v19
	v_mul_f32_e32 v19, v30, v161
	v_mul_f32_e32 v20, v31, v161
	v_cvt_pk_bf16_f32 v19, v19, v20
	ds_write2_b64 v52, v[16:17], v[18:19] offset0:140 offset1:142
	v_mul_f32_e32 v16, v32, v160
	v_mul_f32_e32 v17, v33, v160
	v_mul_f32_e32 v0, v0, v160
	v_mul_f32_e32 v1, v1, v160
	v_cvt_pk_bf16_f32 v16, v16, v17
	v_mul_f32_e32 v17, v34, v160
	v_mul_f32_e32 v18, v35, v160
	v_cvt_pk_bf16_f32 v0, v0, v1
	v_mul_f32_e32 v1, v2, v160
	v_mul_f32_e32 v2, v3, v160
	v_mul_f32_e32 v112, v112, v167
	v_mul_f32_e32 v113, v113, v167
	v_cvt_pk_bf16_f32 v17, v17, v18
	v_mul_f32_e32 v18, v36, v160
	v_mul_f32_e32 v19, v37, v160
	v_cvt_pk_bf16_f32 v1, v1, v2
	v_mul_f32_e32 v2, v4, v160
	v_mul_f32_e32 v3, v5, v160
	v_cvt_pk_bf16_f32 v112, v112, v113
	v_mul_f32_e32 v113, v114, v167
	v_mul_f32_e32 v114, v115, v167
	ds_write2_b64 v52, v[48:49], v[50:51] offset0:128 offset1:130
	v_mul_f32_e32 v48, v72, v161
	v_mul_f32_e32 v49, v73, v161
	v_cvt_pk_bf16_f32 v18, v18, v19
	v_mul_f32_e32 v19, v38, v160
	v_mul_f32_e32 v20, v39, v160
	v_cvt_pk_bf16_f32 v2, v2, v3
	v_mul_f32_e32 v3, v6, v160
	v_mul_f32_e32 v4, v7, v160
	v_cvt_pk_bf16_f32 v113, v113, v114
	v_mul_f32_e32 v114, v116, v167
	v_mul_f32_e32 v115, v117, v167
	v_cvt_pk_bf16_f32 v48, v48, v49
	v_mul_f32_e32 v49, v74, v161
	v_mul_f32_e32 v50, v75, v161
	v_cvt_pk_bf16_f32 v19, v19, v20
	v_add_u32_e32 v20, 0x6000, v162
	v_cvt_pk_bf16_f32 v3, v3, v4
	v_cvt_pk_bf16_f32 v114, v114, v115
	v_mul_f32_e32 v115, v118, v167
	v_mul_f32_e32 v116, v119, v167
	v_cvt_pk_bf16_f32 v49, v49, v50
	v_mul_f32_e32 v50, v76, v161
	v_mul_f32_e32 v51, v77, v161
	ds_write2_b64 v20, v[0:1], v[2:3] offset0:200 offset1:202
	v_mul_f32_e32 v0, v8, v160
	v_mul_f32_e32 v1, v9, v160
	v_cvt_pk_bf16_f32 v115, v115, v116
	v_cvt_pk_bf16_f32 v50, v50, v51
	v_mul_f32_e32 v51, v78, v161
	v_mul_f32_e32 v53, v79, v161
	v_cvt_pk_bf16_f32 v0, v0, v1
	v_mul_f32_e32 v1, v10, v160
	v_mul_f32_e32 v2, v11, v160
	ds_write2_b64 v162, v[112:113], v[114:115] offset1:2
	v_mul_f32_e32 v112, v120, v167
	v_mul_f32_e32 v113, v121, v167
	ds_write2_b64 v84, v[80:81], v[82:83] offset0:64 offset1:66
	v_mul_f32_e32 v80, v104, v168
	v_mul_f32_e32 v81, v105, v168
	v_cvt_pk_bf16_f32 v51, v51, v53
	ds_write2_b64 v20, v[16:17], v[18:19] offset0:192 offset1:194
	v_mul_f32_e32 v16, v40, v160
	v_mul_f32_e32 v17, v41, v160
	v_cvt_pk_bf16_f32 v1, v1, v2
	v_mul_f32_e32 v2, v12, v160
	v_mul_f32_e32 v3, v13, v160
	v_and_b32_e32 v33, 15, v164
	s_lshl_b32 s0, s46, 7
	v_cvt_pk_bf16_f32 v112, v112, v113
	v_mul_f32_e32 v113, v122, v167
	v_mul_f32_e32 v114, v123, v167
	v_cvt_pk_bf16_f32 v80, v80, v81
	v_mul_f32_e32 v81, v106, v168
	v_mul_f32_e32 v82, v107, v168
	ds_write2_b64 v52, v[48:49], v[50:51] offset0:132 offset1:134
	v_cvt_pk_bf16_f32 v16, v16, v17
	v_mul_f32_e32 v17, v42, v160
	v_mul_f32_e32 v18, v43, v160
	v_cvt_pk_bf16_f32 v2, v2, v3
	v_mul_f32_e32 v3, v14, v160
	v_mul_f32_e32 v4, v15, v160
	v_lshl_or_b32 v48, v33, 3, s0
	v_cvt_pk_bf16_f32 v113, v113, v114
	v_mul_f32_e32 v114, v124, v167
	v_mul_f32_e32 v115, v125, v167
	v_cvt_pk_bf16_f32 v81, v81, v82
	v_mul_f32_e32 v82, v108, v168
	v_mul_f32_e32 v83, v109, v168
	v_cvt_pk_bf16_f32 v17, v17, v18
	v_mul_f32_e32 v18, v44, v160
	v_mul_f32_e32 v19, v45, v160
	v_cvt_pk_bf16_f32 v3, v3, v4
	v_ashrrev_i32_e32 v49, 31, v48
	v_cvt_pk_bf16_f32 v114, v114, v115
	v_mul_f32_e32 v115, v126, v167
	v_mul_f32_e32 v116, v127, v167
	v_cvt_pk_bf16_f32 v82, v82, v83
	v_mul_f32_e32 v83, v110, v168
	v_mul_f32_e32 v85, v111, v168
	v_cvt_pk_bf16_f32 v18, v18, v19
	v_mul_f32_e32 v19, v46, v160
	v_mul_f32_e32 v21, v47, v160
	ds_write2_b64 v20, v[0:1], v[2:3] offset0:204 offset1:206
	v_lshlrev_b64 v[0:1], 2, v[48:49]
	v_cvt_pk_bf16_f32 v115, v115, v116
	v_cvt_pk_bf16_f32 v83, v83, v85
	v_cvt_pk_bf16_f32 v19, v19, v21
	v_lshl_add_u64 v[4:5], s[4:5], 0, v[0:1]
	v_lshl_add_u64 v[8:9], s[10:11], 0, v[0:1]
	v_lshl_add_u64 v[12:13], s[12:13], 0, v[0:1]
	v_lshl_add_u64 v[28:29], s[6:7], 0, v[0:1]
	ds_write2_b64 v162, v[112:113], v[114:115] offset0:4 offset1:6
	ds_write2_b64 v84, v[80:81], v[82:83] offset0:68 offset1:70
	ds_write2_b64 v20, v[16:17], v[18:19] offset0:196 offset1:198
	s_waitcnt lgkmcnt(0)
	s_barrier
; DI float bflo(unsigned u) { return __uint_as_float(u << 16); }
; template <int EPI, bool RS>
; DI void gemm_epilogue(unsigned char* smem, f32x16 (&acc)[2][4], const float (&ssq)[4], int K, int m0, int nt256, const EpiArgs& ea, int wt, int wf, int r, int h) {
;     ...
;     {
;       const unsigned char* gs_ = smem; const unsigned char* us_ = smem + 73728;
;       const int tid = ((wt * 4 + wf) * 2 + h) * 32 + r, kc = tid & 15, r0 = tid >> 4, fg = jb * 128 + kc * 8;
;       float w0[8], w1[8], w2[8], bb[8];
; #pragma unroll
;       for (int q4 = 0; q4 < 2; ++q4) {
;         const f32x4 a0 = *(const f32x4*)(ea.cw + fg + 4 * q4), a1 = *(const f32x4*)(ea.cw + 2816 + fg + 4 * q4), a2 = *(const f32x4*)(ea.cw + 5632 + fg + 4 * q4), a3 = *(const f32x4*)(ea.cb + fg + 4 * q4);
; #pragma unroll
;         for (int j = 0; j < 4; ++j) { w0[4 * q4 + j] = a0[j]; w1[4 * q4 + j] = a1[j]; w2[4 * q4 + j] = a2[j]; bb[4 * q4 + j] = a3[j]; }
;       }
; #pragma unroll
;       for (int i = 0; i < 8; ++i) {
;         const int row = r0 + 32 * i;
;         const int rm = (i == 0 && row == 0) ? 0 : row - 1, rp = (i == 7 && row == 255) ? 255 : row + 1;
;         u32x4 gm = *(const u32x4*)(gs_ + rm * GP + kc * 16);
;         const u32x4 gc = *(const u32x4*)(gs_ + row * GP + kc * 16);
;         u32x4 gp = *(const u32x4*)(gs_ + rp * GP + kc * 16);
;         const u32x4 uu = *(const u32x4*)(us_ + row * GP + kc * 16);
;         if (i == 0) { const bool z = row == 0;
; #pragma unroll
;           for (int j = 0; j < 4; ++j) gm[j] = z ? 0u : gm[j]; }
;         if (i == 7) { const bool z = row == 255;
; #pragma unroll
;           for (int j = 0; j < 4; ++j) gp[j] = z ? 0u : gp[j]; }
;         u32x4 o;
; #pragma unroll
;         for (int j = 0; j < 4; ++j) {
;           const float a0 = w0[2 * j] * bflo(gm[j]) + w1[2 * j] * bflo(gc[j]) + w2[2 * j] * bflo(gp[j]) + bb[2 * j];
;           const float a1 = w0[2 * j + 1] * bfhi(gm[j]) + w1[2 * j + 1] * bfhi(gc[j]) + w2[2 * j + 1] * bfhi(gp[j]) + bb[2 * j + 1];
;           const float s0 = a0 * __builtin_amdgcn_rcpf(1.f + __builtin_amdgcn_exp2f(-LOG2E * a0)), s1 = a1 * __builtin_amdgcn_rcpf(1.f + __builtin_amdgcn_exp2f(-LOG2E * a1));
;           o[j] = pk2(s0 * bflo(uu[j]), s1 * bfhi(uu[j]));
;         }
;         __builtin_nontemporal_store(o, (u32x4*)(ea.o0 + (size_t)(m0 + row) * 2816 + fg));
	global_load_dwordx4 v[0:3], v[4:5], off offset:16
	global_load_dwordx4 v[16:19], v[4:5], off
	s_nop 0
	global_load_dwordx4 v[4:7], v[8:9], off offset:16
	global_load_dwordx4 v[20:23], v[8:9], off
	s_nop 0
	global_load_dwordx4 v[8:11], v[12:13], off offset:16
	global_load_dwordx4 v[24:27], v[12:13], off
	s_nop 0
	global_load_dwordx4 v[12:15], v[28:29], off offset:16
	s_nop 0
	global_load_dwordx4 v[28:31], v[28:29], off
	v_add_u32_e32 v32, v199, v165
	v_lshl_add_u32 v32, v32, 5, v164
	v_ashrrev_i32_e32 v54, 4, v32
	v_lshlrev_b32_e32 v33, 4, v33
	v_mul_lo_u32 v57, v54, s1
	v_add_u32_e32 v56, 0, v33
	v_cmp_gt_u32_e32 vcc, 16, v32
	v_add_u32_e32 v44, 0xfffffef0, v57
	v_add_u32_e32 v55, s35, v33
	v_add_u32_e32 v32, v56, v57
	v_cndmask_b32_e64 v44, v44, 0, vcc
	ds_read_b128 v[36:39], v32
	ds_read_b128 v[40:43], v32 offset:272
	v_add_u32_e32 v32, v55, v57
	v_add_u32_e32 v44, v56, v44
	ds_read_b128 v[32:35], v32
	ds_read_b128 v[44:47], v44
	s_ashr_i32 s0, s61, 8
	s_lshl_b32 s71, s0, 2
	s_lshl_b32 s17, s0, 1
	v_add_u32_e32 v58, s61, v54
	s_waitcnt lgkmcnt(0)
	v_cndmask_b32_e64 v50, v44, 0, vcc
	v_cndmask_b32_e64 v51, v45, 0, vcc
	v_lshlrev_b32_e32 v44, 16, v50
	v_and_b32_e32 v45, 0xffff0000, v50
	v_cndmask_b32_e64 v52, v46, 0, vcc
	v_cndmask_b32_e64 v53, v47, 0, vcc
	v_lshlrev_b32_e32 v46, 16, v36
	v_and_b32_e32 v47, 0xffff0000, v36
	s_movk_i32 s0, 0x1600
	v_cmp_gt_i32_e64 s[2:3], 2, v54
	s_waitcnt vmcnt(6)
	v_pk_mul_f32 v[44:45], v[16:17], v[44:45]
	s_waitcnt vmcnt(4)
	v_pk_fma_f32 v[44:45], v[20:21], v[46:47], v[44:45]
	v_lshlrev_b32_e32 v46, 16, v40
	v_and_b32_e32 v47, 0xffff0000, v40
	s_waitcnt vmcnt(2)
	v_pk_fma_f32 v[44:45], v[24:25], v[46:47], v[44:45]
	s_waitcnt vmcnt(0)
	v_pk_add_f32 v[44:45], v[28:29], v[44:45]
	s_nop 0
	v_mul_f32_e32 v40, 0xbfb8aa3b, v44
	v_exp_f32_e32 v40, v40
	s_nop 0
	v_add_f32_e32 v40, 1.0, v40
	v_rcp_f32_e32 v46, v40
	v_mul_f32_e32 v40, 0xbfb8aa3b, v45
	v_exp_f32_e32 v40, v40
	s_nop 0
	v_add_f32_e32 v40, 1.0, v40
	v_rcp_f32_e32 v47, v40
	s_nop 0
	v_pk_mul_f32 v[44:45], v[44:45], v[46:47]
	v_lshlrev_b32_e32 v46, 16, v32
	v_and_b32_e32 v47, 0xffff0000, v32
	v_pk_mul_f32 v[44:45], v[44:45], v[46:47]
	v_lshlrev_b32_e32 v46, 16, v37
	v_cvt_pk_bf16_f32 v40, v44, v45
	v_lshlrev_b32_e32 v44, 16, v51
	v_and_b32_e32 v45, 0xffff0000, v51
	v_pk_mul_f32 v[44:45], v[18:19], v[44:45]
	v_and_b32_e32 v47, 0xffff0000, v37
	v_pk_fma_f32 v[44:45], v[22:23], v[46:47], v[44:45]
	v_lshlrev_b32_e32 v46, 16, v41
	v_and_b32_e32 v47, 0xffff0000, v41
	v_pk_fma_f32 v[44:45], v[26:27], v[46:47], v[44:45]
	s_nop 0
	v_pk_add_f32 v[44:45], v[30:31], v[44:45]
	s_nop 0
	v_mul_f32_e32 v41, 0xbfb8aa3b, v44
	v_exp_f32_e32 v41, v41
	s_nop 0
	v_add_f32_e32 v41, 1.0, v41
	v_rcp_f32_e32 v46, v41
	v_mul_f32_e32 v41, 0xbfb8aa3b, v45
	v_exp_f32_e32 v41, v41
	s_nop 0
	v_add_f32_e32 v41, 1.0, v41
	v_rcp_f32_e32 v47, v41
	s_nop 0
	v_pk_mul_f32 v[44:45], v[44:45], v[46:47]
	v_lshlrev_b32_e32 v46, 16, v33
	v_and_b32_e32 v47, 0xffff0000, v33
	v_pk_mul_f32 v[44:45], v[44:45], v[46:47]
	v_lshlrev_b32_e32 v46, 16, v38
	v_cvt_pk_bf16_f32 v41, v44, v45
	v_lshlrev_b32_e32 v44, 16, v52
	v_and_b32_e32 v45, 0xffff0000, v52
	v_pk_mul_f32 v[44:45], v[0:1], v[44:45]
	v_and_b32_e32 v47, 0xffff0000, v38
	v_pk_fma_f32 v[44:45], v[4:5], v[46:47], v[44:45]
	v_lshlrev_b32_e32 v46, 16, v42
	v_and_b32_e32 v47, 0xffff0000, v42
	v_pk_fma_f32 v[44:45], v[8:9], v[46:47], v[44:45]
	s_nop 0
	v_pk_add_f32 v[44:45], v[12:13], v[44:45]
	s_nop 0
	v_mul_f32_e32 v42, 0xbfb8aa3b, v44
	v_exp_f32_e32 v42, v42
	s_nop 0
	v_add_f32_e32 v42, 1.0, v42
	v_rcp_f32_e32 v46, v42
	v_mul_f32_e32 v42, 0xbfb8aa3b, v45
	v_exp_f32_e32 v42, v42
	s_nop 0
	v_add_f32_e32 v42, 1.0, v42
	v_rcp_f32_e32 v47, v42
	s_nop 0
	v_pk_mul_f32 v[44:45], v[44:45], v[46:47]
	v_lshlrev_b32_e32 v46, 16, v34
	v_and_b32_e32 v47, 0xffff0000, v34
	v_pk_mul_f32 v[44:45], v[44:45], v[46:47]
	v_lshlrev_b32_e32 v46, 16, v39
	v_cvt_pk_bf16_f32 v42, v44, v45
	v_lshlrev_b32_e32 v44, 16, v53
	v_and_b32_e32 v45, 0xffff0000, v53
	v_pk_mul_f32 v[44:45], v[2:3], v[44:45]
	v_and_b32_e32 v47, 0xffff0000, v39
	v_pk_fma_f32 v[44:45], v[6:7], v[46:47], v[44:45]
	v_lshlrev_b32_e32 v46, 16, v43
	v_and_b32_e32 v47, 0xffff0000, v43
	v_pk_fma_f32 v[44:45], v[10:11], v[46:47], v[44:45]
	s_nop 0
	v_pk_add_f32 v[44:45], v[14:15], v[44:45]
	s_nop 0
	v_mul_f32_e32 v43, 0xbfb8aa3b, v44
	v_exp_f32_e32 v43, v43
	s_nop 0
	v_add_f32_e32 v43, 1.0, v43
	v_rcp_f32_e32 v46, v43
	v_mul_f32_e32 v43, 0xbfb8aa3b, v45
	v_exp_f32_e32 v43, v43
	s_nop 0
	v_add_f32_e32 v43, 1.0, v43
	v_rcp_f32_e32 v47, v43
	s_nop 0
	v_pk_mul_f32 v[44:45], v[44:45], v[46:47]
	v_lshlrev_b32_e32 v46, 16, v35
	v_and_b32_e32 v47, 0xffff0000, v35
	v_pk_mul_f32 v[44:45], v[44:45], v[46:47]
	s_nop 0
	v_cvt_pk_bf16_f32 v43, v44, v45
	v_mov_b64_e32 v[44:45], s[68:69]
	v_mad_i64_i32 v[44:45], s[0:1], v58, s0, v[44:45]
	v_lshl_add_u64 v[44:45], v[48:49], 1, v[44:45]
	global_store_dwordx4 v[44:45], v[40:43], off nt
	s_and_saveexec_b64 s[46:47], s[2:3]
	s_movk_i32 s2, 0x1600
	s_cbranch_execz .LBB0_284
	v_add_u32_e32 v42, s71, v54
	v_mov_b64_e32 v[40:41], s[8:9]
	v_mad_i64_i32 v[40:41], s[0:1], v42, s2, v[40:41]
	v_lshl_add_u64 v[40:41], v[48:49], 1, v[40:41]
	global_store_dwordx4 v[40:41], v[36:39], off
	s_and_b64 exec, exec, vcc
	s_cbranch_execz .LBB0_284
	s_mul_i32 s0, s17, 0x1600
	s_mul_hi_i32 s1, s17, 0x1600
	s_add_u32 s0, s50, s0
	s_addc_u32 s1, s52, s1
	v_lshl_add_u64 v[36:37], v[48:49], 1, s[0:1]
	global_store_dwordx4 v[36:37], v[32:35], off

; DI float bflo(unsigned u) { return __uint_as_float(u << 16); }
; DI float bfhi(unsigned u) { return __uint_as_float(u & 0xffff0000u); }
; template <int EPI, bool RS>
; DI void gemm_epilogue(unsigned char* smem, f32x16 (&acc)[2][4], const float (&ssq)[4], int K, int m0, int nt256, const EpiArgs& ea, int wt, int wf, int r, int h) {
;     ...
; #pragma unroll
;       for (int i = 0; i < 8; ++i) {
;         const int c = tid + NTHR * i, row = c >> 5, kc = c & 31;
;         const u32x4 d = *(const u32x4*)(es + row * EP + kc * 16);
;         const size_t off = (size_t)(m0 + hf * 128 + row) * 1024 + nt256 * 256 + kc * 8;
;         const u32x4 xo = *(const u32x4*)(ea.XB + off);
;         float xn[8];
; #pragma unroll
;         for (int j = 0; j < 4; ++j) { xn[2 * j] = bflo(xo[j]) + bflo(d[j]); xn[2 * j + 1] = bfhi(xo[j]) + bfhi(d[j]); }
;         if (ea.X) {
;           f32x4 o0 = {xn[0], xn[1], xn[2], xn[3]}, o1 = {xn[4], xn[5], xn[6], xn[7]};
;           __builtin_nontemporal_store(o0, (f32x4*)(ea.X + off)); __builtin_nontemporal_store(o1, (f32x4*)(ea.X + off + 4));
;         } else {
;           u32x4 w;
; #pragma unroll
;           for (int j = 0; j < 4; ++j) w[j] = pk2(xn[2 * j], xn[2 * j + 1]);
;           *(u32x4*)(ea.XB + off) = w;
;         }
;       }
;       __syncthreads();
.LBB0_294:
	s_or_b64 exec, exec, s[16:17]
	s_add_i32 s9, s50, 0x80
	v_add_u32_e32 v6, s9, v8
	v_ashrrev_i32_e32 v7, 31, v6
	v_lshlrev_b64 v[6:7], 11, v[6:7]
	v_lshl_add_u64 v[6:7], s[62:63], 0, v[6:7]
	v_lshl_add_u64 v[16:17], v[6:7], 0, v[4:5]
	s_mov_b64 s[100:101], 0x8000
	global_load_dwordx4 v[20:23], v[16:17], off
	v_lshl_add_u64 v[28:29], v[16:17], 0, s[100:101]
	global_load_dwordx4 v[24:27], v[28:29], off
	v_lshl_add_u64 v[28:29], v[28:29], 0, s[100:101]
	global_load_dwordx4 v[32:35], v[28:29], off
	v_lshl_add_u64 v[28:29], v[28:29], 0, s[100:101]
	global_load_dwordx4 v[36:39], v[28:29], off
	v_lshl_add_u64 v[28:29], v[28:29], 0, s[100:101]
	global_load_dwordx4 v[40:43], v[28:29], off
	v_lshl_add_u64 v[28:29], v[28:29], 0, s[100:101]
	global_load_dwordx4 v[52:55], v[28:29], off
	v_lshl_add_u64 v[28:29], v[28:29], 0, s[100:101]
	global_load_dwordx4 v[56:59], v[28:29], off
	v_lshl_add_u64 v[28:29], v[28:29], 0, s[100:101]
	global_load_dwordx4 v[60:63], v[28:29], off
	s_waitcnt lgkmcnt(0)
	s_barrier
	ds_read_b128 v[0:3], v9
	s_mov_b64 s[36:37], 0
	s_and_b64 vcc, exec, s[10:11]
	s_mov_b32 s33, s49
	s_waitcnt lgkmcnt(0)
	v_lshlrev_b32_e32 v19, 16, v0
	v_and_b32_e32 v0, 0xffff0000, v0
	s_mov_b64 s[20:21], s[14:15]
	s_mov_b64 s[16:17], s[12:13]
	s_mov_b32 s50, s8
	s_waitcnt vmcnt(7)
	v_mov_b32_e32 v6, v20
	v_mov_b32_e32 v7, v21
	v_mov_b32_e32 v8, v22
	v_mov_b32_e32 v9, v23
	v_lshlrev_b32_e32 v18, 16, v6
	v_and_b32_e32 v6, 0xffff0000, v6
	v_add_f32_e32 v18, v18, v19
	v_add_f32_e32 v0, v6, v0
	v_lshlrev_b32_e32 v6, 16, v7
	v_lshlrev_b32_e32 v19, 16, v1
	v_and_b32_e32 v7, 0xffff0000, v7
	v_and_b32_e32 v1, 0xffff0000, v1
	v_add_f32_e32 v6, v6, v19
	v_add_f32_e32 v1, v7, v1
	v_lshlrev_b32_e32 v7, 16, v8
	v_lshlrev_b32_e32 v19, 16, v2
	v_and_b32_e32 v8, 0xffff0000, v8
	v_and_b32_e32 v2, 0xffff0000, v2
	v_add_f32_e32 v7, v7, v19
	v_add_f32_e32 v2, v8, v2
	v_cvt_pk_bf16_f32 v1, v6, v1
	v_add_u32_e32 v6, s9, v10
	v_lshlrev_b32_e32 v8, 16, v9
	v_lshlrev_b32_e32 v19, 16, v3
	v_and_b32_e32 v9, 0xffff0000, v9
	v_and_b32_e32 v3, 0xffff0000, v3
	v_cvt_pk_bf16_f32 v2, v7, v2
	v_ashrrev_i32_e32 v7, 31, v6
	v_add_f32_e32 v8, v8, v19
	v_add_f32_e32 v3, v9, v3
	v_lshlrev_b64 v[6:7], 11, v[6:7]
	v_cvt_pk_bf16_f32 v0, v18, v0
	v_cvt_pk_bf16_f32 v3, v8, v3
	v_lshl_add_u64 v[6:7], s[62:63], 0, v[6:7]
	global_store_dwordx4 v[16:17], v[0:3], off
	v_lshl_add_u64 v[16:17], v[6:7], 0, v[4:5]
	ds_read_b128 v[0:3], v14
	s_waitcnt lgkmcnt(0)
	v_lshlrev_b32_e32 v14, 16, v0
	v_and_b32_e32 v0, 0xffff0000, v0
	s_waitcnt vmcnt(7)
	v_mov_b32_e32 v6, v24
	v_mov_b32_e32 v7, v25
	v_mov_b32_e32 v8, v26
	v_mov_b32_e32 v9, v27
	v_lshlrev_b32_e32 v10, 16, v6
	v_and_b32_e32 v6, 0xffff0000, v6
	v_add_f32_e32 v10, v10, v14
	v_add_f32_e32 v0, v6, v0
	v_lshlrev_b32_e32 v6, 16, v7
	v_lshlrev_b32_e32 v14, 16, v1
	v_and_b32_e32 v7, 0xffff0000, v7
	v_and_b32_e32 v1, 0xffff0000, v1
	v_add_f32_e32 v6, v6, v14
	v_add_f32_e32 v1, v7, v1
	v_lshlrev_b32_e32 v7, 16, v8
	v_lshlrev_b32_e32 v14, 16, v2
	v_and_b32_e32 v8, 0xffff0000, v8
	v_and_b32_e32 v2, 0xffff0000, v2
	v_add_f32_e32 v7, v7, v14
	v_add_f32_e32 v2, v8, v2
	v_cvt_pk_bf16_f32 v1, v6, v1
	v_add_u32_e32 v6, s9, v11
	v_lshlrev_b32_e32 v8, 16, v9
	v_lshlrev_b32_e32 v14, 16, v3
	v_and_b32_e32 v9, 0xffff0000, v9
	v_and_b32_e32 v3, 0xffff0000, v3
	v_cvt_pk_bf16_f32 v2, v7, v2
	v_ashrrev_i32_e32 v7, 31, v6
	v_add_f32_e32 v8, v8, v14
	v_add_f32_e32 v3, v9, v3
	v_lshlrev_b64 v[6:7], 11, v[6:7]
	v_cvt_pk_bf16_f32 v0, v10, v0
	v_cvt_pk_bf16_f32 v3, v8, v3
	v_lshl_add_u64 v[6:7], s[62:63], 0, v[6:7]
	global_store_dwordx4 v[16:17], v[0:3], off
	v_lshl_add_u64 v[10:11], v[6:7], 0, v[4:5]
	ds_read_b128 v[0:3], v47
	s_waitcnt lgkmcnt(0)
	v_lshlrev_b32_e32 v16, 16, v0
	v_and_b32_e32 v0, 0xffff0000, v0
	s_waitcnt vmcnt(7)
	v_mov_b32_e32 v6, v32
	v_mov_b32_e32 v7, v33
	v_mov_b32_e32 v8, v34
	v_mov_b32_e32 v9, v35
	v_lshlrev_b32_e32 v14, 16, v6
	v_and_b32_e32 v6, 0xffff0000, v6
	v_add_f32_e32 v14, v14, v16
	v_add_f32_e32 v0, v6, v0
	v_lshlrev_b32_e32 v6, 16, v7
	v_lshlrev_b32_e32 v16, 16, v1
	v_and_b32_e32 v7, 0xffff0000, v7
	v_and_b32_e32 v1, 0xffff0000, v1
	v_add_f32_e32 v6, v6, v16
	v_add_f32_e32 v1, v7, v1
	v_lshlrev_b32_e32 v7, 16, v8
	v_lshlrev_b32_e32 v16, 16, v2
	v_and_b32_e32 v8, 0xffff0000, v8
	v_and_b32_e32 v2, 0xffff0000, v2
	v_add_f32_e32 v7, v7, v16
	v_add_f32_e32 v2, v8, v2
	v_cvt_pk_bf16_f32 v1, v6, v1
	v_add_u32_e32 v6, s9, v12
	v_lshlrev_b32_e32 v8, 16, v9
	v_lshlrev_b32_e32 v16, 16, v3
	v_and_b32_e32 v9, 0xffff0000, v9
	v_and_b32_e32 v3, 0xffff0000, v3
	v_cvt_pk_bf16_f32 v2, v7, v2
	v_ashrrev_i32_e32 v7, 31, v6
	v_add_f32_e32 v8, v8, v16
	v_add_f32_e32 v3, v9, v3
	v_lshlrev_b64 v[6:7], 11, v[6:7]
	v_cvt_pk_bf16_f32 v0, v14, v0
	v_cvt_pk_bf16_f32 v3, v8, v3
	v_lshl_add_u64 v[6:7], s[62:63], 0, v[6:7]
	global_store_dwordx4 v[10:11], v[0:3], off
	v_lshl_add_u64 v[10:11], v[6:7], 0, v[4:5]
	ds_read_b128 v[0:3], v30
	s_waitcnt lgkmcnt(0)
	v_lshlrev_b32_e32 v14, 16, v0
	v_and_b32_e32 v0, 0xffff0000, v0
	s_waitcnt vmcnt(7)
; DI float bflo(unsigned u) { return __uint_as_float(u << 16); }
; DI float bfhi(unsigned u) { return __uint_as_float(u & 0xffff0000u); }
; template <int EPI, bool RS>
; DI void gemm_epilogue(unsigned char* smem, f32x16 (&acc)[2][4], const float (&ssq)[4], int K, int m0, int nt256, const EpiArgs& ea, int wt, int wf, int r, int h) {
;     ...
; #pragma unroll
;       for (int i = 0; i < 8; ++i) {
;         const int c = tid + NTHR * i, row = c >> 5, kc = c & 31;
;         const u32x4 d = *(const u32x4*)(es + row * EP + kc * 16);
;         const size_t off = (size_t)(m0 + hf * 128 + row) * 1024 + nt256 * 256 + kc * 8;
;         const u32x4 xo = *(const u32x4*)(ea.XB + off);
;         float xn[8];
; #pragma unroll
;         for (int j = 0; j < 4; ++j) { xn[2 * j] = bflo(xo[j]) + bflo(d[j]); xn[2 * j + 1] = bfhi(xo[j]) + bfhi(d[j]); }
;         if (ea.X) {
;           f32x4 o0 = {xn[0], xn[1], xn[2], xn[3]}, o1 = {xn[4], xn[5], xn[6], xn[7]};
;           __builtin_nontemporal_store(o0, (f32x4*)(ea.X + off)); __builtin_nontemporal_store(o1, (f32x4*)(ea.X + off + 4));
;         } else {
;           u32x4 w;
; #pragma unroll
;           for (int j = 0; j < 4; ++j) w[j] = pk2(xn[2 * j], xn[2 * j + 1]);
;           *(u32x4*)(ea.XB + off) = w;
;         }
;       }
;       __syncthreads();
	v_mov_b32_e32 v6, v36
	v_mov_b32_e32 v7, v37
	v_mov_b32_e32 v8, v38
	v_mov_b32_e32 v9, v39
	v_lshlrev_b32_e32 v12, 16, v6
	v_and_b32_e32 v6, 0xffff0000, v6
	v_add_f32_e32 v12, v12, v14
	v_add_f32_e32 v0, v6, v0
	v_lshlrev_b32_e32 v6, 16, v7
	v_lshlrev_b32_e32 v14, 16, v1
	v_and_b32_e32 v7, 0xffff0000, v7
	v_and_b32_e32 v1, 0xffff0000, v1
	v_add_f32_e32 v6, v6, v14
	v_add_f32_e32 v1, v7, v1
	v_lshlrev_b32_e32 v7, 16, v8
	v_lshlrev_b32_e32 v14, 16, v2
	v_and_b32_e32 v8, 0xffff0000, v8
	v_and_b32_e32 v2, 0xffff0000, v2
	v_add_f32_e32 v7, v7, v14
	v_add_f32_e32 v2, v8, v2
	v_cvt_pk_bf16_f32 v1, v6, v1
	v_add_u32_e32 v6, s9, v13
	v_lshlrev_b32_e32 v8, 16, v9
	v_lshlrev_b32_e32 v14, 16, v3
	v_and_b32_e32 v9, 0xffff0000, v9
	v_and_b32_e32 v3, 0xffff0000, v3
	v_cvt_pk_bf16_f32 v2, v7, v2
	v_ashrrev_i32_e32 v7, 31, v6
	v_add_f32_e32 v8, v8, v14
	v_add_f32_e32 v3, v9, v3
	v_lshlrev_b64 v[6:7], 11, v[6:7]
	v_cvt_pk_bf16_f32 v0, v12, v0
	v_cvt_pk_bf16_f32 v3, v8, v3
	v_lshl_add_u64 v[6:7], s[62:63], 0, v[6:7]
	global_store_dwordx4 v[10:11], v[0:3], off
	v_lshl_add_u64 v[10:11], v[6:7], 0, v[4:5]
	ds_read_b128 v[0:3], v49
	s_waitcnt lgkmcnt(0)
	v_lshlrev_b32_e32 v13, 16, v0
	v_and_b32_e32 v0, 0xffff0000, v0
	s_waitcnt vmcnt(7)
	v_mov_b32_e32 v6, v40
	v_mov_b32_e32 v7, v41
	v_mov_b32_e32 v8, v42
	v_mov_b32_e32 v9, v43
	v_lshlrev_b32_e32 v12, 16, v6
	v_and_b32_e32 v6, 0xffff0000, v6
	v_add_f32_e32 v12, v12, v13
	v_add_f32_e32 v0, v6, v0
	v_lshlrev_b32_e32 v6, 16, v7
	v_lshlrev_b32_e32 v13, 16, v1
	v_and_b32_e32 v7, 0xffff0000, v7
	v_and_b32_e32 v1, 0xffff0000, v1
	v_add_f32_e32 v6, v6, v13
	v_add_f32_e32 v1, v7, v1
	v_lshlrev_b32_e32 v7, 16, v8
	v_lshlrev_b32_e32 v13, 16, v2
	v_and_b32_e32 v8, 0xffff0000, v8
	v_and_b32_e32 v2, 0xffff0000, v2
	v_add_f32_e32 v7, v7, v13
	v_add_f32_e32 v2, v8, v2
	v_cvt_pk_bf16_f32 v1, v6, v1
	v_add_u32_e32 v6, s9, v15
	v_lshlrev_b32_e32 v8, 16, v9
	v_lshlrev_b32_e32 v13, 16, v3
	v_and_b32_e32 v9, 0xffff0000, v9
	v_and_b32_e32 v3, 0xffff0000, v3
	v_cvt_pk_bf16_f32 v2, v7, v2
	v_ashrrev_i32_e32 v7, 31, v6
	v_add_f32_e32 v8, v8, v13
	v_add_f32_e32 v3, v9, v3
	v_lshlrev_b64 v[6:7], 11, v[6:7]
	v_cvt_pk_bf16_f32 v0, v12, v0
	v_cvt_pk_bf16_f32 v3, v8, v3
	v_lshl_add_u64 v[6:7], s[62:63], 0, v[6:7]
	global_store_dwordx4 v[10:11], v[0:3], off
	v_lshl_add_u64 v[10:11], v[6:7], 0, v[4:5]
	ds_read_b128 v[0:3], v48
	s_waitcnt lgkmcnt(0)
	v_lshlrev_b32_e32 v13, 16, v0
	v_and_b32_e32 v0, 0xffff0000, v0
	s_waitcnt vmcnt(7)
	v_mov_b32_e32 v6, v52
	v_mov_b32_e32 v7, v53
	v_mov_b32_e32 v8, v54
	v_mov_b32_e32 v9, v55
	v_lshlrev_b32_e32 v12, 16, v6
	v_and_b32_e32 v6, 0xffff0000, v6
	v_add_f32_e32 v12, v12, v13
	v_add_f32_e32 v0, v6, v0
	v_lshlrev_b32_e32 v6, 16, v7
	v_lshlrev_b32_e32 v13, 16, v1
	v_and_b32_e32 v7, 0xffff0000, v7
	v_and_b32_e32 v1, 0xffff0000, v1
	v_add_f32_e32 v6, v6, v13
	v_add_f32_e32 v1, v7, v1
	v_lshlrev_b32_e32 v7, 16, v8
	v_lshlrev_b32_e32 v13, 16, v2
	v_and_b32_e32 v8, 0xffff0000, v8
	v_and_b32_e32 v2, 0xffff0000, v2
	v_add_f32_e32 v7, v7, v13
	v_add_f32_e32 v2, v8, v2
	v_cvt_pk_bf16_f32 v1, v6, v1
	v_add_u32_e32 v6, s9, v31
	v_lshlrev_b32_e32 v8, 16, v9
	v_lshlrev_b32_e32 v13, 16, v3
	v_and_b32_e32 v9, 0xffff0000, v9
	v_and_b32_e32 v3, 0xffff0000, v3
	v_cvt_pk_bf16_f32 v2, v7, v2
	v_ashrrev_i32_e32 v7, 31, v6
	v_add_f32_e32 v8, v8, v13
	v_add_f32_e32 v3, v9, v3
	v_lshlrev_b64 v[6:7], 11, v[6:7]
	v_cvt_pk_bf16_f32 v0, v12, v0
	v_cvt_pk_bf16_f32 v3, v8, v3
	v_lshl_add_u64 v[6:7], s[62:63], 0, v[6:7]
	global_store_dwordx4 v[10:11], v[0:3], off
	v_lshl_add_u64 v[10:11], v[6:7], 0, v[4:5]
	ds_read_b128 v[0:3], v51
	s_waitcnt lgkmcnt(0)
	v_lshlrev_b32_e32 v13, 16, v0
	v_and_b32_e32 v0, 0xffff0000, v0
	s_waitcnt vmcnt(7)
	v_mov_b32_e32 v6, v56
	v_mov_b32_e32 v7, v57
	v_mov_b32_e32 v8, v58
	v_mov_b32_e32 v9, v59
	v_lshlrev_b32_e32 v12, 16, v6
	v_and_b32_e32 v6, 0xffff0000, v6
	v_add_f32_e32 v12, v12, v13
	v_add_f32_e32 v0, v6, v0
	v_lshlrev_b32_e32 v6, 16, v7
	v_lshlrev_b32_e32 v13, 16, v1
	v_and_b32_e32 v7, 0xffff0000, v7
	v_and_b32_e32 v1, 0xffff0000, v1
	v_add_f32_e32 v6, v6, v13
	v_add_f32_e32 v1, v7, v1
	v_lshlrev_b32_e32 v7, 16, v8
	v_lshlrev_b32_e32 v13, 16, v2
	v_and_b32_e32 v8, 0xffff0000, v8
	v_and_b32_e32 v2, 0xffff0000, v2
	v_add_f32_e32 v7, v7, v13
	v_add_f32_e32 v2, v8, v2
	v_cvt_pk_bf16_f32 v1, v6, v1
	v_add_u32_e32 v6, s9, v46
	v_lshlrev_b32_e32 v8, 16, v9
	v_lshlrev_b32_e32 v13, 16, v3
	v_and_b32_e32 v9, 0xffff0000, v9
	v_and_b32_e32 v3, 0xffff0000, v3
	v_cvt_pk_bf16_f32 v2, v7, v2
	v_ashrrev_i32_e32 v7, 31, v6
	v_add_f32_e32 v8, v8, v13
	v_add_f32_e32 v3, v9, v3
	v_lshlrev_b64 v[6:7], 11, v[6:7]
	v_cvt_pk_bf16_f32 v0, v12, v0
	v_cvt_pk_bf16_f32 v3, v8, v3
	v_lshl_add_u64 v[6:7], s[62:63], 0, v[6:7]
	global_store_dwordx4 v[10:11], v[0:3], off
	v_lshl_add_u64 v[8:9], v[6:7], 0, v[4:5]
	ds_read_b128 v[0:3], v50
	s_waitcnt lgkmcnt(0)
	v_lshlrev_b32_e32 v11, 16, v0
	v_and_b32_e32 v0, 0xffff0000, v0
	s_waitcnt vmcnt(7)
	v_mov_b32_e32 v4, v60
	v_mov_b32_e32 v5, v61
	v_mov_b32_e32 v6, v62
	v_mov_b32_e32 v7, v63
	v_lshlrev_b32_e32 v10, 16, v4
	v_and_b32_e32 v4, 0xffff0000, v4
	v_add_f32_e32 v10, v10, v11
	v_add_f32_e32 v0, v4, v0
	v_lshlrev_b32_e32 v4, 16, v5
	v_lshlrev_b32_e32 v11, 16, v1
	v_and_b32_e32 v5, 0xffff0000, v5
	v_and_b32_e32 v1, 0xffff0000, v1
	v_add_f32_e32 v4, v4, v11
	v_add_f32_e32 v1, v5, v1
	v_lshlrev_b32_e32 v5, 16, v6
	v_lshlrev_b32_e32 v11, 16, v2
	v_and_b32_e32 v6, 0xffff0000, v6
	v_and_b32_e32 v2, 0xffff0000, v2
	v_add_f32_e32 v5, v5, v11
	v_add_f32_e32 v2, v6, v2
	v_lshlrev_b32_e32 v6, 16, v7
	v_lshlrev_b32_e32 v11, 16, v3
	v_and_b32_e32 v7, 0xffff0000, v7
	v_and_b32_e32 v3, 0xffff0000, v3
	v_add_f32_e32 v6, v6, v11
	v_add_f32_e32 v3, v7, v3
	v_cvt_pk_bf16_f32 v0, v10, v0
	v_cvt_pk_bf16_f32 v1, v4, v1
	v_cvt_pk_bf16_f32 v2, v5, v2
	v_cvt_pk_bf16_f32 v3, v6, v3
	global_store_dwordx4 v[8:9], v[0:3], off
	s_barrier
	s_cbranch_vccnz .LBB0_305

; DI float bflo(unsigned u) { return __uint_as_float(u << 16); }
; DI float bfhi(unsigned u) { return __uint_as_float(u & 0xffff0000u); }
; template <int EPI, bool RS>
; DI void gemm_epilogue(unsigned char* smem, f32x16 (&acc)[2][4], const float (&ssq)[4], int K, int m0, int nt256, const EpiArgs& ea, int wt, int wf, int r, int h) {
;     ...
;       __syncthreads();
; #pragma unroll
;       for (int i = 0; i < 8; ++i) {
;         const int c = tid + NTHR * i, row = c >> 5, kc = c & 31;
;         const u32x4 d = *(const u32x4*)(es + row * EP + kc * 16);
;         const size_t off = (size_t)(m0 + hf * 128 + row) * 1024 + nt256 * 256 + kc * 8;
;         const u32x4 xo = *(const u32x4*)(ea.XB + off);
;         float xn[8];
; #pragma unroll
;         for (int j = 0; j < 4; ++j) { xn[2 * j] = bflo(xo[j]) + bflo(d[j]); xn[2 * j + 1] = bfhi(xo[j]) + bfhi(d[j]); }
;         if (ea.X) {
;           f32x4 o0 = {xn[0], xn[1], xn[2], xn[3]}, o1 = {xn[4], xn[5], xn[6], xn[7]};
;           __builtin_nontemporal_store(o0, (f32x4*)(ea.X + off)); __builtin_nontemporal_store(o1, (f32x4*)(ea.X + off + 4));
;         } else {
;           u32x4 w;
; #pragma unroll
;           for (int j = 0; j < 4; ++j) w[j] = pk2(xn[2 * j], xn[2 * j + 1]);
;           *(u32x4*)(ea.XB + off) = w;
;         }
;       }
;       __syncthreads();
.LBB0_303:
	s_or_b64 exec, exec, s[16:17]
	v_add_u32_e32 v4, v223, v234
	v_lshl_add_u32 v7, v4, 5, v233
	v_ashrrev_i32_e32 v8, 5, v7
	s_lshl_b32 s0, s33, 8
	v_add_u32_e32 v14, s50, v8
	v_and_b32_e32 v4, 31, v233
	s_ashr_i32 s1, s0, 31
	v_ashrrev_i32_e32 v15, 31, v14
	v_lshl_add_u32 v6, v4, 4, s35
	v_lshl_or_b32 v4, v4, 3, s0
	v_mov_b32_e32 v5, s1
	v_lshlrev_b64 v[14:15], 11, v[14:15]
	v_lshl_add_u64 v[14:15], s[62:63], 0, v[14:15]
	v_lshlrev_b64 v[4:5], 1, v[4:5]
	v_lshl_add_u64 v[14:15], v[14:15], 0, v[4:5]
	s_mov_b64 s[100:101], 0x8000
	global_load_dwordx4 v[80:83], v[14:15], off
	v_lshl_add_u64 v[62:63], v[14:15], 0, s[100:101]
	global_load_dwordx4 v[84:87], v[62:63], off
	v_lshl_add_u64 v[62:63], v[62:63], 0, s[100:101]
	global_load_dwordx4 v[88:91], v[62:63], off
	v_lshl_add_u64 v[62:63], v[62:63], 0, s[100:101]
	global_load_dwordx4 v[92:95], v[62:63], off
	v_lshl_add_u64 v[62:63], v[62:63], 0, s[100:101]
	global_load_dwordx4 v[96:99], v[62:63], off
	v_lshl_add_u64 v[62:63], v[62:63], 0, s[100:101]
	global_load_dwordx4 v[100:103], v[62:63], off
	v_lshl_add_u64 v[62:63], v[62:63], 0, s[100:101]
	global_load_dwordx4 v[104:107], v[62:63], off
	v_lshl_add_u64 v[62:63], v[62:63], 0, s[100:101]
	global_load_dwordx4 v[108:111], v[62:63], off
	s_waitcnt lgkmcnt(0)
	s_barrier
	v_mul_lo_u32 v9, v8, s29
	v_add_u32_e32 v9, v6, v9
	ds_read_b128 v[10:13], v9
	s_waitcnt lgkmcnt(0)
	v_lshlrev_b32_e32 v31, 16, v10
	v_and_b32_e32 v10, 0xffff0000, v10
	s_waitcnt vmcnt(7)
	v_mov_b32_e32 v46, v80
	v_mov_b32_e32 v47, v81
	v_mov_b32_e32 v48, v82
	v_mov_b32_e32 v49, v83
	v_lshlrev_b32_e32 v30, 16, v46
	v_add_f32_e32 v30, v30, v31
	v_and_b32_e32 v31, 0xffff0000, v46
	v_add_f32_e32 v10, v31, v10
	v_lshlrev_b32_e32 v31, 16, v47
	v_lshlrev_b32_e32 v46, 16, v11
	v_add_f32_e32 v31, v31, v46
	v_and_b32_e32 v46, 0xffff0000, v47
	v_and_b32_e32 v11, 0xffff0000, v11
	v_add_f32_e32 v11, v46, v11
	v_lshlrev_b32_e32 v46, 16, v48
	v_lshlrev_b32_e32 v47, 16, v12
	v_add_f32_e32 v46, v46, v47
	v_and_b32_e32 v47, 0xffff0000, v48
	v_and_b32_e32 v12, 0xffff0000, v12
	v_add_f32_e32 v12, v47, v12
	v_lshlrev_b32_e32 v47, 16, v49
	v_lshlrev_b32_e32 v48, 16, v13
	v_add_f32_e32 v47, v47, v48
	v_and_b32_e32 v48, 0xffff0000, v49
	v_and_b32_e32 v13, 0xffff0000, v13
	v_add_f32_e32 v13, v48, v13
	v_cvt_pk_bf16_f32 v10, v30, v10
	v_cvt_pk_bf16_f32 v11, v31, v11
	v_cvt_pk_bf16_f32 v12, v46, v12
	v_cvt_pk_bf16_f32 v13, v47, v13
	global_store_dwordx4 v[14:15], v[10:13], off
	s_nop 1
	v_add_u32_e32 v10, 0x200, v7
	v_ashrrev_i32_e32 v10, 5, v10
	v_add_u32_e32 v12, s50, v10
	v_ashrrev_i32_e32 v13, 31, v12
	v_lshlrev_b64 v[12:13], 11, v[12:13]
	v_lshl_add_u64 v[12:13], s[62:63], 0, v[12:13]
	v_lshl_add_u64 v[12:13], v[12:13], 0, v[4:5]
	v_mul_lo_u32 v11, v10, s29
	v_add_u32_e32 v14, v6, v11
	ds_read_b128 v[46:49], v14
	s_waitcnt lgkmcnt(0)
	v_lshlrev_b32_e32 v15, 16, v46
	v_and_b32_e32 v30, 0xffff0000, v46
	v_lshlrev_b32_e32 v31, 16, v47
	v_and_b32_e32 v46, 0xffff0000, v47
	v_lshlrev_b32_e32 v47, 16, v48
	s_waitcnt vmcnt(7)
	v_mov_b32_e32 v50, v84
	v_mov_b32_e32 v51, v85
	v_mov_b32_e32 v52, v86
	v_mov_b32_e32 v53, v87
	v_lshlrev_b32_e32 v11, 16, v50
	v_add_f32_e32 v11, v11, v15
	v_and_b32_e32 v15, 0xffff0000, v50
	v_add_f32_e32 v15, v15, v30
	v_lshlrev_b32_e32 v30, 16, v51
	v_add_f32_e32 v30, v30, v31
	v_and_b32_e32 v31, 0xffff0000, v51
	v_add_f32_e32 v31, v31, v46
	v_lshlrev_b32_e32 v46, 16, v52
	v_add_f32_e32 v50, v46, v47
	v_and_b32_e32 v46, 0xffff0000, v52
	v_and_b32_e32 v47, 0xffff0000, v48
	v_add_f32_e32 v48, v46, v47
	v_lshlrev_b32_e32 v46, 16, v53
	v_lshlrev_b32_e32 v47, 16, v49
	v_add_f32_e32 v51, v46, v47
	v_and_b32_e32 v46, 0xffff0000, v53
	v_and_b32_e32 v47, 0xffff0000, v49
	v_add_f32_e32 v49, v46, v47
	v_cvt_pk_bf16_f32 v46, v11, v15
	v_add_u32_e32 v11, 0x400, v7
	v_cvt_pk_bf16_f32 v47, v30, v31
	v_cvt_pk_bf16_f32 v48, v50, v48
	v_cvt_pk_bf16_f32 v49, v51, v49
	v_ashrrev_i32_e32 v11, 5, v11
	global_store_dwordx4 v[12:13], v[46:49], off
	v_mul_lo_u32 v12, v11, s29
	s_nop 0
	v_add_u32_e32 v47, v6, v12
	v_add_u32_e32 v12, s50, v11
	v_ashrrev_i32_e32 v13, 31, v12
	v_lshlrev_b64 v[12:13], 11, v[12:13]
	v_lshl_add_u64 v[12:13], s[62:63], 0, v[12:13]
	v_lshl_add_u64 v[12:13], v[12:13], 0, v[4:5]
	ds_read_b128 v[48:51], v47
	s_waitcnt lgkmcnt(0)
	v_lshlrev_b32_e32 v30, 16, v48
	v_and_b32_e32 v31, 0xffff0000, v48
	v_lshlrev_b32_e32 v46, 16, v49
	v_and_b32_e32 v48, 0xffff0000, v49
	v_lshlrev_b32_e32 v49, 16, v50
	s_waitcnt vmcnt(7)
	v_mov_b32_e32 v52, v88
	v_mov_b32_e32 v53, v89
	v_mov_b32_e32 v54, v90
	v_mov_b32_e32 v55, v91
	v_lshlrev_b32_e32 v15, 16, v52
	v_add_f32_e32 v15, v15, v30
	v_and_b32_e32 v30, 0xffff0000, v52
	v_add_f32_e32 v30, v30, v31
	v_lshlrev_b32_e32 v31, 16, v53
	v_add_f32_e32 v31, v31, v46
	v_and_b32_e32 v46, 0xffff0000, v53
	v_add_f32_e32 v46, v46, v48
	v_lshlrev_b32_e32 v48, 16, v54
	v_add_f32_e32 v52, v48, v49
	v_and_b32_e32 v48, 0xffff0000, v54
	v_and_b32_e32 v49, 0xffff0000, v50
	v_add_f32_e32 v50, v48, v49
	v_lshlrev_b32_e32 v48, 16, v55
	v_lshlrev_b32_e32 v49, 16, v51
	v_add_f32_e32 v53, v48, v49
	v_and_b32_e32 v48, 0xffff0000, v55
	v_and_b32_e32 v49, 0xffff0000, v51
	v_add_f32_e32 v51, v48, v49
	v_cvt_pk_bf16_f32 v48, v15, v30
	v_cvt_pk_bf16_f32 v49, v31, v46
	v_cvt_pk_bf16_f32 v50, v52, v50
	v_cvt_pk_bf16_f32 v51, v53, v51
	global_store_dwordx4 v[12:13], v[48:51], off
	v_add_u32_e32 v12, 0x600, v7
	v_ashrrev_i32_e32 v12, 5, v12
	v_add_u32_e32 v52, s50, v12
	v_ashrrev_i32_e32 v53, 31, v52
	v_lshlrev_b64 v[52:53], 11, v[52:53]
	v_lshl_add_u64 v[52:53], s[62:63], 0, v[52:53]
	v_lshl_add_u64 v[56:57], v[52:53], 0, v[4:5]
	v_mul_lo_u32 v13, v12, s29
	v_add_u32_e32 v30, v6, v13
	ds_read_b128 v[48:51], v30
	s_waitcnt lgkmcnt(0)
; DI float bflo(unsigned u) { return __uint_as_float(u << 16); }
; DI float bfhi(unsigned u) { return __uint_as_float(u & 0xffff0000u); }
; template <int EPI, bool RS>
; DI void gemm_epilogue(unsigned char* smem, f32x16 (&acc)[2][4], const float (&ssq)[4], int K, int m0, int nt256, const EpiArgs& ea, int wt, int wf, int r, int h) {
;     ...
; #pragma unroll
;       for (int i = 0; i < 8; ++i) {
;         const int c = tid + NTHR * i, row = c >> 5, kc = c & 31;
;         const u32x4 d = *(const u32x4*)(es + row * EP + kc * 16);
;         const size_t off = (size_t)(m0 + hf * 128 + row) * 1024 + nt256 * 256 + kc * 8;
;         const u32x4 xo = *(const u32x4*)(ea.XB + off);
;         float xn[8];
; #pragma unroll
;         for (int j = 0; j < 4; ++j) { xn[2 * j] = bflo(xo[j]) + bflo(d[j]); xn[2 * j + 1] = bfhi(xo[j]) + bfhi(d[j]); }
;         if (ea.X) {
;           f32x4 o0 = {xn[0], xn[1], xn[2], xn[3]}, o1 = {xn[4], xn[5], xn[6], xn[7]};
;           __builtin_nontemporal_store(o0, (f32x4*)(ea.X + off)); __builtin_nontemporal_store(o1, (f32x4*)(ea.X + off + 4));
;         } else {
;           u32x4 w;
; #pragma unroll
;           for (int j = 0; j < 4; ++j) w[j] = pk2(xn[2 * j], xn[2 * j + 1]);
;           *(u32x4*)(ea.XB + off) = w;
;         }
;       }
;       __syncthreads();
	v_lshlrev_b32_e32 v15, 16, v48
	v_and_b32_e32 v31, 0xffff0000, v48
	v_lshlrev_b32_e32 v46, 16, v49
	v_and_b32_e32 v48, 0xffff0000, v49
	v_lshlrev_b32_e32 v49, 16, v50
	s_waitcnt vmcnt(7)
	v_mov_b32_e32 v52, v92
	v_mov_b32_e32 v53, v93
	v_mov_b32_e32 v54, v94
	v_mov_b32_e32 v55, v95
	v_lshlrev_b32_e32 v13, 16, v52
	v_add_f32_e32 v13, v13, v15
	v_and_b32_e32 v15, 0xffff0000, v52
	v_add_f32_e32 v15, v15, v31
	v_lshlrev_b32_e32 v31, 16, v53
	v_add_f32_e32 v31, v31, v46
	v_and_b32_e32 v46, 0xffff0000, v53
	v_add_f32_e32 v46, v46, v48
	v_lshlrev_b32_e32 v48, 16, v54
	v_add_f32_e32 v52, v48, v49
	v_and_b32_e32 v48, 0xffff0000, v54
	v_and_b32_e32 v49, 0xffff0000, v50
	v_add_f32_e32 v50, v48, v49
	v_lshlrev_b32_e32 v48, 16, v55
	v_lshlrev_b32_e32 v49, 16, v51
	v_add_f32_e32 v53, v48, v49
	v_and_b32_e32 v48, 0xffff0000, v55
	v_and_b32_e32 v49, 0xffff0000, v51
	v_add_f32_e32 v51, v48, v49
	v_cvt_pk_bf16_f32 v48, v13, v15
	v_add_u32_e32 v13, 0x800, v7
	v_ashrrev_i32_e32 v13, 5, v13
	v_add_u32_e32 v54, s50, v13
	v_ashrrev_i32_e32 v55, 31, v54
	v_lshlrev_b64 v[54:55], 11, v[54:55]
	v_cvt_pk_bf16_f32 v49, v31, v46
	v_cvt_pk_bf16_f32 v50, v52, v50
	v_cvt_pk_bf16_f32 v51, v53, v51
	v_lshl_add_u64 v[54:55], s[62:63], 0, v[54:55]
	global_store_dwordx4 v[56:57], v[48:51], off
	v_lshl_add_u64 v[58:59], v[54:55], 0, v[4:5]
	v_mul_lo_u32 v15, v13, s29
	v_add_u32_e32 v49, v6, v15
	ds_read_b128 v[50:53], v49
	s_waitcnt lgkmcnt(0)
	v_lshlrev_b32_e32 v31, 16, v50
	v_and_b32_e32 v46, 0xffff0000, v50
	v_lshlrev_b32_e32 v48, 16, v51
	v_and_b32_e32 v50, 0xffff0000, v51
	v_lshlrev_b32_e32 v51, 16, v52
	s_waitcnt vmcnt(7)
	v_mov_b32_e32 v54, v96
	v_mov_b32_e32 v55, v97
	v_mov_b32_e32 v56, v98
	v_mov_b32_e32 v57, v99
	v_lshlrev_b32_e32 v15, 16, v54
	v_add_f32_e32 v15, v15, v31
	v_and_b32_e32 v31, 0xffff0000, v54
	v_add_f32_e32 v31, v31, v46
	v_lshlrev_b32_e32 v46, 16, v55
	v_add_f32_e32 v46, v46, v48
	v_and_b32_e32 v48, 0xffff0000, v55
	v_add_f32_e32 v48, v48, v50
	v_lshlrev_b32_e32 v50, 16, v56
	v_add_f32_e32 v54, v50, v51
	v_and_b32_e32 v50, 0xffff0000, v56
	v_and_b32_e32 v51, 0xffff0000, v52
	v_add_f32_e32 v52, v50, v51
	v_lshlrev_b32_e32 v50, 16, v57
	v_lshlrev_b32_e32 v51, 16, v53
	v_add_f32_e32 v55, v50, v51
	v_and_b32_e32 v50, 0xffff0000, v57
	v_and_b32_e32 v51, 0xffff0000, v53
	v_add_f32_e32 v53, v50, v51
	v_cvt_pk_bf16_f32 v50, v15, v31
	v_add_u32_e32 v15, 0xa00, v7
	v_ashrrev_i32_e32 v15, 5, v15
	v_cvt_pk_bf16_f32 v52, v54, v52
	v_add_u32_e32 v54, s50, v15
	v_cvt_pk_bf16_f32 v53, v55, v53
	v_ashrrev_i32_e32 v55, 31, v54
	v_lshlrev_b64 v[54:55], 11, v[54:55]
	v_cvt_pk_bf16_f32 v51, v46, v48
	v_lshl_add_u64 v[54:55], s[62:63], 0, v[54:55]
	global_store_dwordx4 v[58:59], v[50:53], off
	v_lshl_add_u64 v[58:59], v[54:55], 0, v[4:5]
	v_mul_lo_u32 v31, v15, s29
	v_add_u32_e32 v48, v6, v31
	ds_read_b128 v[50:53], v48
	s_waitcnt lgkmcnt(0)
	v_lshlrev_b32_e32 v46, 16, v50
	v_and_b32_e32 v50, 0xffff0000, v50
	s_waitcnt vmcnt(7)
	v_mov_b32_e32 v54, v100
	v_mov_b32_e32 v55, v101
	v_mov_b32_e32 v56, v102
	v_mov_b32_e32 v57, v103
	v_lshlrev_b32_e32 v31, 16, v54
	v_add_f32_e32 v31, v31, v46
	v_and_b32_e32 v46, 0xffff0000, v54
	v_add_f32_e32 v46, v46, v50
	v_lshlrev_b32_e32 v50, 16, v55
	v_lshlrev_b32_e32 v54, 16, v51
	v_add_f32_e32 v54, v50, v54
	v_and_b32_e32 v50, 0xffff0000, v55
	v_and_b32_e32 v51, 0xffff0000, v51
	v_add_f32_e32 v51, v50, v51
	v_lshlrev_b32_e32 v50, 16, v56
	v_lshlrev_b32_e32 v55, 16, v52
	v_add_f32_e32 v55, v50, v55
	v_and_b32_e32 v50, 0xffff0000, v56
	v_and_b32_e32 v52, 0xffff0000, v52
	v_add_f32_e32 v52, v50, v52
	v_lshlrev_b32_e32 v50, 16, v57
	v_lshlrev_b32_e32 v56, 16, v53
	v_add_f32_e32 v56, v50, v56
	v_and_b32_e32 v50, 0xffff0000, v57
	v_and_b32_e32 v53, 0xffff0000, v53
	v_add_f32_e32 v53, v50, v53
	v_cvt_pk_bf16_f32 v50, v31, v46
	v_add_u32_e32 v31, 0xc00, v7
	v_ashrrev_i32_e32 v31, 5, v31
	v_cvt_pk_bf16_f32 v53, v56, v53
	v_add_u32_e32 v56, s50, v31
	v_ashrrev_i32_e32 v57, 31, v56
	v_lshlrev_b64 v[56:57], 11, v[56:57]
	v_cvt_pk_bf16_f32 v51, v54, v51
	v_cvt_pk_bf16_f32 v52, v55, v52
	v_lshl_add_u64 v[56:57], s[62:63], 0, v[56:57]
	global_store_dwordx4 v[58:59], v[50:53], off
	v_lshl_add_u64 v[60:61], v[56:57], 0, v[4:5]
	v_mul_lo_u32 v46, v31, s29
	v_add_u32_e32 v51, v6, v46
	ds_read_b128 v[52:55], v51
	v_add_u32_e32 v7, 0xe00, v7
	s_waitcnt lgkmcnt(0)
	v_lshlrev_b32_e32 v50, 16, v52
	v_and_b32_e32 v52, 0xffff0000, v52
	s_waitcnt vmcnt(7)
	v_mov_b32_e32 v56, v104
	v_mov_b32_e32 v57, v105
	v_mov_b32_e32 v58, v106
	v_mov_b32_e32 v59, v107
	v_lshlrev_b32_e32 v46, 16, v56
	v_add_f32_e32 v46, v46, v50
	v_and_b32_e32 v50, 0xffff0000, v56
	v_add_f32_e32 v50, v50, v52
	v_lshlrev_b32_e32 v52, 16, v57
	v_lshlrev_b32_e32 v56, 16, v53
	v_add_f32_e32 v56, v52, v56
	v_and_b32_e32 v52, 0xffff0000, v57
	v_and_b32_e32 v53, 0xffff0000, v53
	v_add_f32_e32 v53, v52, v53
	v_lshlrev_b32_e32 v52, 16, v58
	v_lshlrev_b32_e32 v57, 16, v54
	v_add_f32_e32 v57, v52, v57
	v_and_b32_e32 v52, 0xffff0000, v58
	v_and_b32_e32 v54, 0xffff0000, v54
	v_add_f32_e32 v54, v52, v54
	v_lshlrev_b32_e32 v52, 16, v59
	v_lshlrev_b32_e32 v58, 16, v55
	v_add_f32_e32 v58, v52, v58
	v_and_b32_e32 v52, 0xffff0000, v59
	v_and_b32_e32 v55, 0xffff0000, v55
	v_add_f32_e32 v55, v52, v55
	v_cvt_pk_bf16_f32 v52, v46, v50
	v_ashrrev_i32_e32 v46, 5, v7
	v_mul_lo_u32 v7, v46, s29
	v_add_u32_e32 v50, v6, v7
	v_add_u32_e32 v6, s50, v46
	v_ashrrev_i32_e32 v7, 31, v6
	v_lshlrev_b64 v[6:7], 11, v[6:7]
	v_cvt_pk_bf16_f32 v53, v56, v53
	v_cvt_pk_bf16_f32 v54, v57, v54
	v_cvt_pk_bf16_f32 v55, v58, v55
	v_lshl_add_u64 v[6:7], s[62:63], 0, v[6:7]
	global_store_dwordx4 v[60:61], v[52:55], off
	v_lshl_add_u64 v[6:7], v[6:7], 0, v[4:5]
	ds_read_b128 v[52:55], v50
	s_waitcnt lgkmcnt(0)
	v_lshlrev_b32_e32 v61, 16, v52
	v_and_b32_e32 v52, 0xffff0000, v52
	s_waitcnt vmcnt(7)
	v_mov_b32_e32 v56, v108
	v_mov_b32_e32 v57, v109
	v_mov_b32_e32 v58, v110
	v_mov_b32_e32 v59, v111
	v_lshlrev_b32_e32 v60, 16, v56
	v_and_b32_e32 v56, 0xffff0000, v56
	v_add_f32_e32 v60, v60, v61
	v_add_f32_e32 v52, v56, v52
	v_lshlrev_b32_e32 v56, 16, v57
	v_lshlrev_b32_e32 v61, 16, v53
	v_and_b32_e32 v57, 0xffff0000, v57
	v_and_b32_e32 v53, 0xffff0000, v53
	v_add_f32_e32 v56, v56, v61
	v_add_f32_e32 v53, v57, v53
	v_lshlrev_b32_e32 v57, 16, v58
	v_lshlrev_b32_e32 v61, 16, v54
	v_and_b32_e32 v58, 0xffff0000, v58
	v_and_b32_e32 v54, 0xffff0000, v54
	v_add_f32_e32 v57, v57, v61
	v_add_f32_e32 v54, v58, v54
	v_lshlrev_b32_e32 v58, 16, v59
	v_lshlrev_b32_e32 v61, 16, v55
	v_and_b32_e32 v59, 0xffff0000, v59
	v_and_b32_e32 v55, 0xffff0000, v55
	v_add_f32_e32 v58, v58, v61
	v_add_f32_e32 v55, v59, v55
	v_cvt_pk_bf16_f32 v52, v60, v52
	v_cvt_pk_bf16_f32 v53, v56, v53
	v_cvt_pk_bf16_f32 v54, v57, v54
	v_cvt_pk_bf16_f32 v55, v58, v55
	global_store_dwordx4 v[6:7], v[52:55], off
	s_barrier
; template <int EPI, bool RS>
; DI void gemm_epilogue(unsigned char* smem, f32x16 (&acc)[2][4], const float (&ssq)[4], int K, int m0, int nt256, const EpiArgs& ea, int wt, int wf, int r, int h) {
;     ...
;       if (wt == hf) {
; #pragma unroll
;         for (int tb = 0; tb < 4; ++tb)
; #pragma unroll
;           for (int fb = 0; fb < 2; ++fb)
; #pragma unroll
;             for (int g4 = 0; g4 < 4; ++g4) {
;               u32x2 w; w[0] = pk2(acc[fb][tb][4 * g4], acc[fb][tb][4 * g4 + 1]); w[1] = pk2(acc[fb][tb][4 * g4 + 2], acc[fb][tb][4 * g4 + 3]);
;               *(u32x2*)(es + (tb * 32 + r) * EP + (wf * 64 + fb * 32 + g4 * 8 + 4 * h) * 2) = w;
;             }
;       }
;       __syncthreads();
	s_and_saveexec_b64 s[16:17], s[4:5]
	s_cbranch_execz .LBB0_294
	v_mad_u64_u32 v[6:7], s[0:1], v233, s29, v[228:229]
	v_add_u32_e32 v7, 0x4000, v6
	ds_write2_b64 v6, v[224:225], v[226:227] offset1:2
	ds_write2_b64 v6, v[118:119], v[122:123] offset0:4 offset1:6
	ds_write2_b64 v6, v[114:115], v[120:121] offset0:8 offset1:10
	ds_write2_b64 v6, v[112:113], v[116:117] offset0:12 offset1:14
	ds_write2_b64 v7, v[74:75], v[78:79] offset0:64 offset1:66
	ds_write2_b64 v7, v[70:71], v[76:77] offset0:68 offset1:70
	ds_write2_b64 v7, v[66:67], v[72:73] offset0:72 offset1:74
	ds_write2_b64 v7, v[64:65], v[68:69] offset0:76 offset1:78
	v_add_u32_e32 v7, 0x8000, v6
	v_add_u32_e32 v6, 0xc000, v6
	ds_write2_b64 v7, v[40:41], v[44:45] offset0:128 offset1:130
	ds_write2_b64 v7, v[36:37], v[42:43] offset0:132 offset1:134
	ds_write2_b64 v7, v[34:35], v[38:39] offset0:136 offset1:138
	ds_write2_b64 v7, v[32:33], v[28:29] offset0:140 offset1:142
	ds_write2_b64 v6, v[22:23], v[26:27] offset0:192 offset1:194
	ds_write2_b64 v6, v[18:19], v[24:25] offset0:196 offset1:198
	ds_write2_b64 v6, v[16:17], v[20:21] offset0:200 offset1:202
	ds_write2_b64 v6, v[0:1], v[2:3] offset0:204 offset1:206
	s_branch .LBB0_294

; DI float bflo(unsigned u) { return __uint_as_float(u << 16); }
; DI float bfhi(unsigned u) { return __uint_as_float(u & 0xffff0000u); }
; template <int EPI, bool RS>
; DI void gemm_epilogue(unsigned char* smem, f32x16 (&acc)[2][4], const float (&ssq)[4], int K, int m0, int nt256, const EpiArgs& ea, int wt, int wf, int r, int h) {
;     ...
; #pragma unroll
;       for (int i = 0; i < 8; ++i) {
;         const int c = tid + NTHR * i, row = c >> 5, kc = c & 31;
;         const u32x4 d = *(const u32x4*)(es + row * EP + kc * 16);
;         const size_t off = (size_t)(m0 + hf * 128 + row) * 1024 + nt256 * 256 + kc * 8;
;         const u32x4 xo = *(const u32x4*)(ea.XB + off);
;         float xn[8];
; #pragma unroll
;         for (int j = 0; j < 4; ++j) { xn[2 * j] = bflo(xo[j]) + bflo(d[j]); xn[2 * j + 1] = bfhi(xo[j]) + bfhi(d[j]); }
;         if (ea.X) {
;           f32x4 o0 = {xn[0], xn[1], xn[2], xn[3]}, o1 = {xn[4], xn[5], xn[6], xn[7]};
;           __builtin_nontemporal_store(o0, (f32x4*)(ea.X + off)); __builtin_nontemporal_store(o1, (f32x4*)(ea.X + off + 4));
;         } else {
;           u32x4 w;
; #pragma unroll
;           for (int j = 0; j < 4; ++j) w[j] = pk2(xn[2 * j], xn[2 * j + 1]);
;           *(u32x4*)(ea.XB + off) = w;
;         }
;       }
;       __syncthreads();
.LBB0_423:
	s_or_b64 exec, exec, s[16:17]
	s_add_i32 s7, s53, 0x80
	v_add_u32_e32 v6, s7, v8
	v_ashrrev_i32_e32 v7, 31, v6
	v_lshlrev_b64 v[6:7], 11, v[6:7]
	v_lshl_add_u64 v[6:7], s[62:63], 0, v[6:7]
	v_lshl_add_u64 v[16:17], v[6:7], 0, v[4:5]
	s_mov_b64 s[100:101], 0x8000
	global_load_dwordx4 v[20:23], v[16:17], off
	v_lshl_add_u64 v[28:29], v[16:17], 0, s[100:101]
	global_load_dwordx4 v[24:27], v[28:29], off
	v_lshl_add_u64 v[28:29], v[28:29], 0, s[100:101]
	global_load_dwordx4 v[32:35], v[28:29], off
	v_lshl_add_u64 v[28:29], v[28:29], 0, s[100:101]
	global_load_dwordx4 v[36:39], v[28:29], off
	v_lshl_add_u64 v[28:29], v[28:29], 0, s[100:101]
	global_load_dwordx4 v[40:43], v[28:29], off
	v_lshl_add_u64 v[28:29], v[28:29], 0, s[100:101]
	global_load_dwordx4 v[52:55], v[28:29], off
	v_lshl_add_u64 v[28:29], v[28:29], 0, s[100:101]
	global_load_dwordx4 v[56:59], v[28:29], off
	v_lshl_add_u64 v[28:29], v[28:29], 0, s[100:101]
	global_load_dwordx4 v[60:63], v[28:29], off
	s_waitcnt lgkmcnt(0)
	s_barrier
	ds_read_b128 v[0:3], v9
	s_mov_b64 s[36:37], 0
	s_and_b64 vcc, exec, s[10:11]
	s_mov_b32 s33, s52
	s_waitcnt lgkmcnt(0)
	v_lshlrev_b32_e32 v19, 16, v0
	v_and_b32_e32 v0, 0xffff0000, v0
	s_mov_b64 s[20:21], s[14:15]
	s_mov_b64 s[16:17], s[12:13]
	s_mov_b32 s53, s6
	s_waitcnt vmcnt(7)
	v_mov_b32_e32 v6, v20
	v_mov_b32_e32 v7, v21
	v_mov_b32_e32 v8, v22
	v_mov_b32_e32 v9, v23
	v_lshlrev_b32_e32 v18, 16, v6
	v_and_b32_e32 v6, 0xffff0000, v6
	v_add_f32_e32 v18, v18, v19
	v_add_f32_e32 v0, v6, v0
	v_lshlrev_b32_e32 v6, 16, v7
	v_lshlrev_b32_e32 v19, 16, v1
	v_and_b32_e32 v7, 0xffff0000, v7
	v_and_b32_e32 v1, 0xffff0000, v1
	v_add_f32_e32 v6, v6, v19
	v_add_f32_e32 v1, v7, v1
	v_lshlrev_b32_e32 v7, 16, v8
	v_lshlrev_b32_e32 v19, 16, v2
	v_and_b32_e32 v8, 0xffff0000, v8
	v_and_b32_e32 v2, 0xffff0000, v2
	v_add_f32_e32 v7, v7, v19
	v_add_f32_e32 v2, v8, v2
	v_cvt_pk_bf16_f32 v1, v6, v1
	v_add_u32_e32 v6, s7, v10
	v_lshlrev_b32_e32 v8, 16, v9
	v_lshlrev_b32_e32 v19, 16, v3
	v_and_b32_e32 v9, 0xffff0000, v9
	v_and_b32_e32 v3, 0xffff0000, v3
	v_cvt_pk_bf16_f32 v2, v7, v2
	v_ashrrev_i32_e32 v7, 31, v6
	v_add_f32_e32 v8, v8, v19
	v_add_f32_e32 v3, v9, v3
	v_lshlrev_b64 v[6:7], 11, v[6:7]
	v_cvt_pk_bf16_f32 v0, v18, v0
	v_cvt_pk_bf16_f32 v3, v8, v3
	v_lshl_add_u64 v[6:7], s[62:63], 0, v[6:7]
	global_store_dwordx4 v[16:17], v[0:3], off
	v_lshl_add_u64 v[16:17], v[6:7], 0, v[4:5]
	ds_read_b128 v[0:3], v14
	s_waitcnt lgkmcnt(0)
	v_lshlrev_b32_e32 v14, 16, v0
	v_and_b32_e32 v0, 0xffff0000, v0
	s_waitcnt vmcnt(7)
	v_mov_b32_e32 v6, v24
	v_mov_b32_e32 v7, v25
	v_mov_b32_e32 v8, v26
	v_mov_b32_e32 v9, v27
	v_lshlrev_b32_e32 v10, 16, v6
	v_and_b32_e32 v6, 0xffff0000, v6
	v_add_f32_e32 v10, v10, v14
	v_add_f32_e32 v0, v6, v0
	v_lshlrev_b32_e32 v6, 16, v7
	v_lshlrev_b32_e32 v14, 16, v1
	v_and_b32_e32 v7, 0xffff0000, v7
	v_and_b32_e32 v1, 0xffff0000, v1
	v_add_f32_e32 v6, v6, v14
	v_add_f32_e32 v1, v7, v1
	v_lshlrev_b32_e32 v7, 16, v8
	v_lshlrev_b32_e32 v14, 16, v2
	v_and_b32_e32 v8, 0xffff0000, v8
	v_and_b32_e32 v2, 0xffff0000, v2
	v_add_f32_e32 v7, v7, v14
	v_add_f32_e32 v2, v8, v2
	v_cvt_pk_bf16_f32 v1, v6, v1
	v_add_u32_e32 v6, s7, v11
	v_lshlrev_b32_e32 v8, 16, v9
	v_lshlrev_b32_e32 v14, 16, v3
	v_and_b32_e32 v9, 0xffff0000, v9
	v_and_b32_e32 v3, 0xffff0000, v3
	v_cvt_pk_bf16_f32 v2, v7, v2
	v_ashrrev_i32_e32 v7, 31, v6
	v_add_f32_e32 v8, v8, v14
	v_add_f32_e32 v3, v9, v3
	v_lshlrev_b64 v[6:7], 11, v[6:7]
	v_cvt_pk_bf16_f32 v0, v10, v0
	v_cvt_pk_bf16_f32 v3, v8, v3
	v_lshl_add_u64 v[6:7], s[62:63], 0, v[6:7]
	global_store_dwordx4 v[16:17], v[0:3], off
	v_lshl_add_u64 v[10:11], v[6:7], 0, v[4:5]
	ds_read_b128 v[0:3], v47
	s_waitcnt lgkmcnt(0)
	v_lshlrev_b32_e32 v16, 16, v0
	v_and_b32_e32 v0, 0xffff0000, v0
	s_waitcnt vmcnt(7)
	v_mov_b32_e32 v6, v32
	v_mov_b32_e32 v7, v33
	v_mov_b32_e32 v8, v34
	v_mov_b32_e32 v9, v35
	v_lshlrev_b32_e32 v14, 16, v6
	v_and_b32_e32 v6, 0xffff0000, v6
	v_add_f32_e32 v14, v14, v16
	v_add_f32_e32 v0, v6, v0
	v_lshlrev_b32_e32 v6, 16, v7
	v_lshlrev_b32_e32 v16, 16, v1
	v_and_b32_e32 v7, 0xffff0000, v7
	v_and_b32_e32 v1, 0xffff0000, v1
	v_add_f32_e32 v6, v6, v16
	v_add_f32_e32 v1, v7, v1
	v_lshlrev_b32_e32 v7, 16, v8
	v_lshlrev_b32_e32 v16, 16, v2
	v_and_b32_e32 v8, 0xffff0000, v8
	v_and_b32_e32 v2, 0xffff0000, v2
	v_add_f32_e32 v7, v7, v16
	v_add_f32_e32 v2, v8, v2
	v_cvt_pk_bf16_f32 v1, v6, v1
	v_add_u32_e32 v6, s7, v12
	v_lshlrev_b32_e32 v8, 16, v9
	v_lshlrev_b32_e32 v16, 16, v3
	v_and_b32_e32 v9, 0xffff0000, v9
	v_and_b32_e32 v3, 0xffff0000, v3
	v_cvt_pk_bf16_f32 v2, v7, v2
	v_ashrrev_i32_e32 v7, 31, v6
	v_add_f32_e32 v8, v8, v16
	v_add_f32_e32 v3, v9, v3
	v_lshlrev_b64 v[6:7], 11, v[6:7]
	v_cvt_pk_bf16_f32 v0, v14, v0
	v_cvt_pk_bf16_f32 v3, v8, v3
	v_lshl_add_u64 v[6:7], s[62:63], 0, v[6:7]
	global_store_dwordx4 v[10:11], v[0:3], off
	v_lshl_add_u64 v[10:11], v[6:7], 0, v[4:5]
	ds_read_b128 v[0:3], v30
	s_waitcnt lgkmcnt(0)
	v_lshlrev_b32_e32 v14, 16, v0
	v_and_b32_e32 v0, 0xffff0000, v0
	s_waitcnt vmcnt(7)
; DI float bflo(unsigned u) { return __uint_as_float(u << 16); }
; DI float bfhi(unsigned u) { return __uint_as_float(u & 0xffff0000u); }
; template <int EPI, bool RS>
; DI void gemm_epilogue(unsigned char* smem, f32x16 (&acc)[2][4], const float (&ssq)[4], int K, int m0, int nt256, const EpiArgs& ea, int wt, int wf, int r, int h) {
;     ...
; #pragma unroll
;       for (int i = 0; i < 8; ++i) {
;         const int c = tid + NTHR * i, row = c >> 5, kc = c & 31;
;         const u32x4 d = *(const u32x4*)(es + row * EP + kc * 16);
;         const size_t off = (size_t)(m0 + hf * 128 + row) * 1024 + nt256 * 256 + kc * 8;
;         const u32x4 xo = *(const u32x4*)(ea.XB + off);
;         float xn[8];
; #pragma unroll
;         for (int j = 0; j < 4; ++j) { xn[2 * j] = bflo(xo[j]) + bflo(d[j]); xn[2 * j + 1] = bfhi(xo[j]) + bfhi(d[j]); }
;         if (ea.X) {
;           f32x4 o0 = {xn[0], xn[1], xn[2], xn[3]}, o1 = {xn[4], xn[5], xn[6], xn[7]};
;           __builtin_nontemporal_store(o0, (f32x4*)(ea.X + off)); __builtin_nontemporal_store(o1, (f32x4*)(ea.X + off + 4));
;         } else {
;           u32x4 w;
; #pragma unroll
;           for (int j = 0; j < 4; ++j) w[j] = pk2(xn[2 * j], xn[2 * j + 1]);
;           *(u32x4*)(ea.XB + off) = w;
;         }
;       }
;       __syncthreads();
	v_mov_b32_e32 v6, v36
	v_mov_b32_e32 v7, v37
	v_mov_b32_e32 v8, v38
	v_mov_b32_e32 v9, v39
	v_lshlrev_b32_e32 v12, 16, v6
	v_and_b32_e32 v6, 0xffff0000, v6
	v_add_f32_e32 v12, v12, v14
	v_add_f32_e32 v0, v6, v0
	v_lshlrev_b32_e32 v6, 16, v7
	v_lshlrev_b32_e32 v14, 16, v1
	v_and_b32_e32 v7, 0xffff0000, v7
	v_and_b32_e32 v1, 0xffff0000, v1
	v_add_f32_e32 v6, v6, v14
	v_add_f32_e32 v1, v7, v1
	v_lshlrev_b32_e32 v7, 16, v8
	v_lshlrev_b32_e32 v14, 16, v2
	v_and_b32_e32 v8, 0xffff0000, v8
	v_and_b32_e32 v2, 0xffff0000, v2
	v_add_f32_e32 v7, v7, v14
	v_add_f32_e32 v2, v8, v2
	v_cvt_pk_bf16_f32 v1, v6, v1
	v_add_u32_e32 v6, s7, v13
	v_lshlrev_b32_e32 v8, 16, v9
	v_lshlrev_b32_e32 v14, 16, v3
	v_and_b32_e32 v9, 0xffff0000, v9
	v_and_b32_e32 v3, 0xffff0000, v3
	v_cvt_pk_bf16_f32 v2, v7, v2
	v_ashrrev_i32_e32 v7, 31, v6
	v_add_f32_e32 v8, v8, v14
	v_add_f32_e32 v3, v9, v3
	v_lshlrev_b64 v[6:7], 11, v[6:7]
	v_cvt_pk_bf16_f32 v0, v12, v0
	v_cvt_pk_bf16_f32 v3, v8, v3
	v_lshl_add_u64 v[6:7], s[62:63], 0, v[6:7]
	global_store_dwordx4 v[10:11], v[0:3], off
	v_lshl_add_u64 v[10:11], v[6:7], 0, v[4:5]
	ds_read_b128 v[0:3], v49
	s_waitcnt lgkmcnt(0)
	v_lshlrev_b32_e32 v13, 16, v0
	v_and_b32_e32 v0, 0xffff0000, v0
	s_waitcnt vmcnt(7)
	v_mov_b32_e32 v6, v40
	v_mov_b32_e32 v7, v41
	v_mov_b32_e32 v8, v42
	v_mov_b32_e32 v9, v43
	v_lshlrev_b32_e32 v12, 16, v6
	v_and_b32_e32 v6, 0xffff0000, v6
	v_add_f32_e32 v12, v12, v13
	v_add_f32_e32 v0, v6, v0
	v_lshlrev_b32_e32 v6, 16, v7
	v_lshlrev_b32_e32 v13, 16, v1
	v_and_b32_e32 v7, 0xffff0000, v7
	v_and_b32_e32 v1, 0xffff0000, v1
	v_add_f32_e32 v6, v6, v13
	v_add_f32_e32 v1, v7, v1
	v_lshlrev_b32_e32 v7, 16, v8
	v_lshlrev_b32_e32 v13, 16, v2
	v_and_b32_e32 v8, 0xffff0000, v8
	v_and_b32_e32 v2, 0xffff0000, v2
	v_add_f32_e32 v7, v7, v13
	v_add_f32_e32 v2, v8, v2
	v_cvt_pk_bf16_f32 v1, v6, v1
	v_add_u32_e32 v6, s7, v15
	v_lshlrev_b32_e32 v8, 16, v9
	v_lshlrev_b32_e32 v13, 16, v3
	v_and_b32_e32 v9, 0xffff0000, v9
	v_and_b32_e32 v3, 0xffff0000, v3
	v_cvt_pk_bf16_f32 v2, v7, v2
	v_ashrrev_i32_e32 v7, 31, v6
	v_add_f32_e32 v8, v8, v13
	v_add_f32_e32 v3, v9, v3
	v_lshlrev_b64 v[6:7], 11, v[6:7]
	v_cvt_pk_bf16_f32 v0, v12, v0
	v_cvt_pk_bf16_f32 v3, v8, v3
	v_lshl_add_u64 v[6:7], s[62:63], 0, v[6:7]
	global_store_dwordx4 v[10:11], v[0:3], off
	v_lshl_add_u64 v[10:11], v[6:7], 0, v[4:5]
	ds_read_b128 v[0:3], v48
	s_waitcnt lgkmcnt(0)
	v_lshlrev_b32_e32 v13, 16, v0
	v_and_b32_e32 v0, 0xffff0000, v0
	s_waitcnt vmcnt(7)
	v_mov_b32_e32 v6, v52
	v_mov_b32_e32 v7, v53
	v_mov_b32_e32 v8, v54
	v_mov_b32_e32 v9, v55
	v_lshlrev_b32_e32 v12, 16, v6
	v_and_b32_e32 v6, 0xffff0000, v6
	v_add_f32_e32 v12, v12, v13
	v_add_f32_e32 v0, v6, v0
	v_lshlrev_b32_e32 v6, 16, v7
	v_lshlrev_b32_e32 v13, 16, v1
	v_and_b32_e32 v7, 0xffff0000, v7
	v_and_b32_e32 v1, 0xffff0000, v1
	v_add_f32_e32 v6, v6, v13
	v_add_f32_e32 v1, v7, v1
	v_lshlrev_b32_e32 v7, 16, v8
	v_lshlrev_b32_e32 v13, 16, v2
	v_and_b32_e32 v8, 0xffff0000, v8
	v_and_b32_e32 v2, 0xffff0000, v2
	v_add_f32_e32 v7, v7, v13
	v_add_f32_e32 v2, v8, v2
	v_cvt_pk_bf16_f32 v1, v6, v1
	v_add_u32_e32 v6, s7, v31
	v_lshlrev_b32_e32 v8, 16, v9
	v_lshlrev_b32_e32 v13, 16, v3
	v_and_b32_e32 v9, 0xffff0000, v9
	v_and_b32_e32 v3, 0xffff0000, v3
	v_cvt_pk_bf16_f32 v2, v7, v2
	v_ashrrev_i32_e32 v7, 31, v6
	v_add_f32_e32 v8, v8, v13
	v_add_f32_e32 v3, v9, v3
	v_lshlrev_b64 v[6:7], 11, v[6:7]
	v_cvt_pk_bf16_f32 v0, v12, v0
	v_cvt_pk_bf16_f32 v3, v8, v3
	v_lshl_add_u64 v[6:7], s[62:63], 0, v[6:7]
	global_store_dwordx4 v[10:11], v[0:3], off
	v_lshl_add_u64 v[10:11], v[6:7], 0, v[4:5]
	ds_read_b128 v[0:3], v51
	s_waitcnt lgkmcnt(0)
	v_lshlrev_b32_e32 v13, 16, v0
	v_and_b32_e32 v0, 0xffff0000, v0
	s_waitcnt vmcnt(7)
	v_mov_b32_e32 v6, v56
	v_mov_b32_e32 v7, v57
	v_mov_b32_e32 v8, v58
	v_mov_b32_e32 v9, v59
	v_lshlrev_b32_e32 v12, 16, v6
	v_and_b32_e32 v6, 0xffff0000, v6
	v_add_f32_e32 v12, v12, v13
	v_add_f32_e32 v0, v6, v0
	v_lshlrev_b32_e32 v6, 16, v7
	v_lshlrev_b32_e32 v13, 16, v1
	v_and_b32_e32 v7, 0xffff0000, v7
	v_and_b32_e32 v1, 0xffff0000, v1
	v_add_f32_e32 v6, v6, v13
	v_add_f32_e32 v1, v7, v1
	v_lshlrev_b32_e32 v7, 16, v8
	v_lshlrev_b32_e32 v13, 16, v2
	v_and_b32_e32 v8, 0xffff0000, v8
	v_and_b32_e32 v2, 0xffff0000, v2
	v_add_f32_e32 v7, v7, v13
	v_add_f32_e32 v2, v8, v2
	v_cvt_pk_bf16_f32 v1, v6, v1
	v_add_u32_e32 v6, s7, v46
	v_lshlrev_b32_e32 v8, 16, v9
	v_lshlrev_b32_e32 v13, 16, v3
	v_and_b32_e32 v9, 0xffff0000, v9
	v_and_b32_e32 v3, 0xffff0000, v3
	v_cvt_pk_bf16_f32 v2, v7, v2
	v_ashrrev_i32_e32 v7, 31, v6
	v_add_f32_e32 v8, v8, v13
	v_add_f32_e32 v3, v9, v3
	v_lshlrev_b64 v[6:7], 11, v[6:7]
	v_cvt_pk_bf16_f32 v0, v12, v0
	v_cvt_pk_bf16_f32 v3, v8, v3
	v_lshl_add_u64 v[6:7], s[62:63], 0, v[6:7]
	global_store_dwordx4 v[10:11], v[0:3], off
	v_lshl_add_u64 v[8:9], v[6:7], 0, v[4:5]
	ds_read_b128 v[0:3], v50
	s_waitcnt lgkmcnt(0)
	v_lshlrev_b32_e32 v11, 16, v0
	v_and_b32_e32 v0, 0xffff0000, v0
	s_waitcnt vmcnt(7)
	v_mov_b32_e32 v4, v60
	v_mov_b32_e32 v5, v61
	v_mov_b32_e32 v6, v62
	v_mov_b32_e32 v7, v63
	v_lshlrev_b32_e32 v10, 16, v4
	v_and_b32_e32 v4, 0xffff0000, v4
	v_add_f32_e32 v10, v10, v11
	v_add_f32_e32 v0, v4, v0
	v_lshlrev_b32_e32 v4, 16, v5
	v_lshlrev_b32_e32 v11, 16, v1
	v_and_b32_e32 v5, 0xffff0000, v5
	v_and_b32_e32 v1, 0xffff0000, v1
	v_add_f32_e32 v4, v4, v11
	v_add_f32_e32 v1, v5, v1
	v_lshlrev_b32_e32 v5, 16, v6
	v_lshlrev_b32_e32 v11, 16, v2
	v_and_b32_e32 v6, 0xffff0000, v6
	v_and_b32_e32 v2, 0xffff0000, v2
	v_add_f32_e32 v5, v5, v11
	v_add_f32_e32 v2, v6, v2
	v_lshlrev_b32_e32 v6, 16, v7
	v_lshlrev_b32_e32 v11, 16, v3
	v_and_b32_e32 v7, 0xffff0000, v7
	v_and_b32_e32 v3, 0xffff0000, v3
	v_add_f32_e32 v6, v6, v11
	v_add_f32_e32 v3, v7, v3
	v_cvt_pk_bf16_f32 v0, v10, v0
	v_cvt_pk_bf16_f32 v1, v4, v1
	v_cvt_pk_bf16_f32 v2, v5, v2
	v_cvt_pk_bf16_f32 v3, v6, v3
	global_store_dwordx4 v[8:9], v[0:3], off
	s_barrier
	s_cbranch_vccnz .LBB0_434

; DI float bflo(unsigned u) { return __uint_as_float(u << 16); }
; DI float bfhi(unsigned u) { return __uint_as_float(u & 0xffff0000u); }
; template <int EPI, bool RS>
; DI void gemm_epilogue(unsigned char* smem, f32x16 (&acc)[2][4], const float (&ssq)[4], int K, int m0, int nt256, const EpiArgs& ea, int wt, int wf, int r, int h) {
;     ...
;       __syncthreads();
; #pragma unroll
;       for (int i = 0; i < 8; ++i) {
;         const int c = tid + NTHR * i, row = c >> 5, kc = c & 31;
;         const u32x4 d = *(const u32x4*)(es + row * EP + kc * 16);
;         const size_t off = (size_t)(m0 + hf * 128 + row) * 1024 + nt256 * 256 + kc * 8;
;         const u32x4 xo = *(const u32x4*)(ea.XB + off);
;         float xn[8];
; #pragma unroll
;         for (int j = 0; j < 4; ++j) { xn[2 * j] = bflo(xo[j]) + bflo(d[j]); xn[2 * j + 1] = bfhi(xo[j]) + bfhi(d[j]); }
;         if (ea.X) {
;           f32x4 o0 = {xn[0], xn[1], xn[2], xn[3]}, o1 = {xn[4], xn[5], xn[6], xn[7]};
;           __builtin_nontemporal_store(o0, (f32x4*)(ea.X + off)); __builtin_nontemporal_store(o1, (f32x4*)(ea.X + off + 4));
;         } else {
;           u32x4 w;
; #pragma unroll
;           for (int j = 0; j < 4; ++j) w[j] = pk2(xn[2 * j], xn[2 * j + 1]);
;           *(u32x4*)(ea.XB + off) = w;
;         }
;       }
;       __syncthreads();
.LBB0_432:
	s_or_b64 exec, exec, s[16:17]
	v_add_u32_e32 v4, v223, v234
	v_lshl_add_u32 v7, v4, 5, v233
	v_ashrrev_i32_e32 v8, 5, v7
	s_lshl_b32 s0, s33, 8
	v_add_u32_e32 v14, s53, v8
	v_and_b32_e32 v4, 31, v233
	s_ashr_i32 s1, s0, 31
	v_ashrrev_i32_e32 v15, 31, v14
	v_lshl_add_u32 v6, v4, 4, s35
	v_lshl_or_b32 v4, v4, 3, s0
	v_mov_b32_e32 v5, s1
	v_lshlrev_b64 v[14:15], 11, v[14:15]
	v_lshl_add_u64 v[14:15], s[62:63], 0, v[14:15]
	v_lshlrev_b64 v[4:5], 1, v[4:5]
	v_lshl_add_u64 v[14:15], v[14:15], 0, v[4:5]
	s_mov_b64 s[100:101], 0x8000
	global_load_dwordx4 v[80:83], v[14:15], off
	v_lshl_add_u64 v[62:63], v[14:15], 0, s[100:101]
	global_load_dwordx4 v[84:87], v[62:63], off
	v_lshl_add_u64 v[62:63], v[62:63], 0, s[100:101]
	global_load_dwordx4 v[88:91], v[62:63], off
	v_lshl_add_u64 v[62:63], v[62:63], 0, s[100:101]
	global_load_dwordx4 v[92:95], v[62:63], off
	v_lshl_add_u64 v[62:63], v[62:63], 0, s[100:101]
	global_load_dwordx4 v[96:99], v[62:63], off
	v_lshl_add_u64 v[62:63], v[62:63], 0, s[100:101]
	global_load_dwordx4 v[100:103], v[62:63], off
	v_lshl_add_u64 v[62:63], v[62:63], 0, s[100:101]
	global_load_dwordx4 v[104:107], v[62:63], off
	v_lshl_add_u64 v[62:63], v[62:63], 0, s[100:101]
	global_load_dwordx4 v[108:111], v[62:63], off
	s_waitcnt lgkmcnt(0)
	s_barrier
	v_mul_lo_u32 v9, v8, s29
	v_add_u32_e32 v9, v6, v9
	ds_read_b128 v[10:13], v9
	s_waitcnt lgkmcnt(0)
	v_lshlrev_b32_e32 v31, 16, v10
	v_and_b32_e32 v10, 0xffff0000, v10
	s_waitcnt vmcnt(7)
	v_mov_b32_e32 v46, v80
	v_mov_b32_e32 v47, v81
	v_mov_b32_e32 v48, v82
	v_mov_b32_e32 v49, v83
	v_lshlrev_b32_e32 v30, 16, v46
	v_add_f32_e32 v30, v30, v31
	v_and_b32_e32 v31, 0xffff0000, v46
	v_add_f32_e32 v10, v31, v10
	v_lshlrev_b32_e32 v31, 16, v47
	v_lshlrev_b32_e32 v46, 16, v11
	v_add_f32_e32 v31, v31, v46
	v_and_b32_e32 v46, 0xffff0000, v47
	v_and_b32_e32 v11, 0xffff0000, v11
	v_add_f32_e32 v11, v46, v11
	v_lshlrev_b32_e32 v46, 16, v48
	v_lshlrev_b32_e32 v47, 16, v12
	v_add_f32_e32 v46, v46, v47
	v_and_b32_e32 v47, 0xffff0000, v48
	v_and_b32_e32 v12, 0xffff0000, v12
	v_add_f32_e32 v12, v47, v12
	v_lshlrev_b32_e32 v47, 16, v49
	v_lshlrev_b32_e32 v48, 16, v13
	v_add_f32_e32 v47, v47, v48
	v_and_b32_e32 v48, 0xffff0000, v49
	v_and_b32_e32 v13, 0xffff0000, v13
	v_add_f32_e32 v13, v48, v13
	v_cvt_pk_bf16_f32 v10, v30, v10
	v_cvt_pk_bf16_f32 v11, v31, v11
	v_cvt_pk_bf16_f32 v12, v46, v12
	v_cvt_pk_bf16_f32 v13, v47, v13
	global_store_dwordx4 v[14:15], v[10:13], off
	s_nop 1
	v_add_u32_e32 v10, 0x200, v7
	v_ashrrev_i32_e32 v10, 5, v10
	v_add_u32_e32 v12, s53, v10
	v_ashrrev_i32_e32 v13, 31, v12
	v_lshlrev_b64 v[12:13], 11, v[12:13]
	v_lshl_add_u64 v[12:13], s[62:63], 0, v[12:13]
	v_lshl_add_u64 v[12:13], v[12:13], 0, v[4:5]
	v_mul_lo_u32 v11, v10, s29
	v_add_u32_e32 v14, v6, v11
	ds_read_b128 v[46:49], v14
	s_waitcnt lgkmcnt(0)
	v_lshlrev_b32_e32 v15, 16, v46
	v_and_b32_e32 v30, 0xffff0000, v46
	v_lshlrev_b32_e32 v31, 16, v47
	v_and_b32_e32 v46, 0xffff0000, v47
	v_lshlrev_b32_e32 v47, 16, v48
	s_waitcnt vmcnt(7)
	v_mov_b32_e32 v50, v84
	v_mov_b32_e32 v51, v85
	v_mov_b32_e32 v52, v86
	v_mov_b32_e32 v53, v87
	v_lshlrev_b32_e32 v11, 16, v50
	v_add_f32_e32 v11, v11, v15
	v_and_b32_e32 v15, 0xffff0000, v50
	v_add_f32_e32 v15, v15, v30
	v_lshlrev_b32_e32 v30, 16, v51
	v_add_f32_e32 v30, v30, v31
	v_and_b32_e32 v31, 0xffff0000, v51
	v_add_f32_e32 v31, v31, v46
	v_lshlrev_b32_e32 v46, 16, v52
	v_add_f32_e32 v50, v46, v47
	v_and_b32_e32 v46, 0xffff0000, v52
	v_and_b32_e32 v47, 0xffff0000, v48
	v_add_f32_e32 v48, v46, v47
	v_lshlrev_b32_e32 v46, 16, v53
	v_lshlrev_b32_e32 v47, 16, v49
	v_add_f32_e32 v51, v46, v47
	v_and_b32_e32 v46, 0xffff0000, v53
	v_and_b32_e32 v47, 0xffff0000, v49
	v_add_f32_e32 v49, v46, v47
	v_cvt_pk_bf16_f32 v46, v11, v15
	v_add_u32_e32 v11, 0x400, v7
	v_cvt_pk_bf16_f32 v47, v30, v31
	v_cvt_pk_bf16_f32 v48, v50, v48
	v_cvt_pk_bf16_f32 v49, v51, v49
	v_ashrrev_i32_e32 v11, 5, v11
	global_store_dwordx4 v[12:13], v[46:49], off
	v_mul_lo_u32 v12, v11, s29
	s_nop 0
	v_add_u32_e32 v47, v6, v12
	v_add_u32_e32 v12, s53, v11
	v_ashrrev_i32_e32 v13, 31, v12
	v_lshlrev_b64 v[12:13], 11, v[12:13]
	v_lshl_add_u64 v[12:13], s[62:63], 0, v[12:13]
	v_lshl_add_u64 v[12:13], v[12:13], 0, v[4:5]
	ds_read_b128 v[48:51], v47
	s_waitcnt lgkmcnt(0)
	v_lshlrev_b32_e32 v30, 16, v48
	v_and_b32_e32 v31, 0xffff0000, v48
	v_lshlrev_b32_e32 v46, 16, v49
	v_and_b32_e32 v48, 0xffff0000, v49
	v_lshlrev_b32_e32 v49, 16, v50
	s_waitcnt vmcnt(7)
	v_mov_b32_e32 v52, v88
	v_mov_b32_e32 v53, v89
	v_mov_b32_e32 v54, v90
	v_mov_b32_e32 v55, v91
	v_lshlrev_b32_e32 v15, 16, v52
	v_add_f32_e32 v15, v15, v30
	v_and_b32_e32 v30, 0xffff0000, v52
	v_add_f32_e32 v30, v30, v31
	v_lshlrev_b32_e32 v31, 16, v53
	v_add_f32_e32 v31, v31, v46
	v_and_b32_e32 v46, 0xffff0000, v53
	v_add_f32_e32 v46, v46, v48
	v_lshlrev_b32_e32 v48, 16, v54
	v_add_f32_e32 v52, v48, v49
	v_and_b32_e32 v48, 0xffff0000, v54
	v_and_b32_e32 v49, 0xffff0000, v50
	v_add_f32_e32 v50, v48, v49
	v_lshlrev_b32_e32 v48, 16, v55
	v_lshlrev_b32_e32 v49, 16, v51
	v_add_f32_e32 v53, v48, v49
	v_and_b32_e32 v48, 0xffff0000, v55
	v_and_b32_e32 v49, 0xffff0000, v51
	v_add_f32_e32 v51, v48, v49
	v_cvt_pk_bf16_f32 v48, v15, v30
	v_cvt_pk_bf16_f32 v49, v31, v46
	v_cvt_pk_bf16_f32 v50, v52, v50
	v_cvt_pk_bf16_f32 v51, v53, v51
	global_store_dwordx4 v[12:13], v[48:51], off
	v_add_u32_e32 v12, 0x600, v7
	v_ashrrev_i32_e32 v12, 5, v12
	v_add_u32_e32 v52, s53, v12
	v_ashrrev_i32_e32 v53, 31, v52
	v_lshlrev_b64 v[52:53], 11, v[52:53]
	v_lshl_add_u64 v[52:53], s[62:63], 0, v[52:53]
	v_lshl_add_u64 v[56:57], v[52:53], 0, v[4:5]
	v_mul_lo_u32 v13, v12, s29
	v_add_u32_e32 v30, v6, v13
	ds_read_b128 v[48:51], v30
	s_waitcnt lgkmcnt(0)
; DI float bflo(unsigned u) { return __uint_as_float(u << 16); }
; DI float bfhi(unsigned u) { return __uint_as_float(u & 0xffff0000u); }
; template <int EPI, bool RS>
; DI void gemm_epilogue(unsigned char* smem, f32x16 (&acc)[2][4], const float (&ssq)[4], int K, int m0, int nt256, const EpiArgs& ea, int wt, int wf, int r, int h) {
;     ...
; #pragma unroll
;       for (int i = 0; i < 8; ++i) {
;         const int c = tid + NTHR * i, row = c >> 5, kc = c & 31;
;         const u32x4 d = *(const u32x4*)(es + row * EP + kc * 16);
;         const size_t off = (size_t)(m0 + hf * 128 + row) * 1024 + nt256 * 256 + kc * 8;
;         const u32x4 xo = *(const u32x4*)(ea.XB + off);
;         float xn[8];
; #pragma unroll
;         for (int j = 0; j < 4; ++j) { xn[2 * j] = bflo(xo[j]) + bflo(d[j]); xn[2 * j + 1] = bfhi(xo[j]) + bfhi(d[j]); }
;         if (ea.X) {
;           f32x4 o0 = {xn[0], xn[1], xn[2], xn[3]}, o1 = {xn[4], xn[5], xn[6], xn[7]};
;           __builtin_nontemporal_store(o0, (f32x4*)(ea.X + off)); __builtin_nontemporal_store(o1, (f32x4*)(ea.X + off + 4));
;         } else {
;           u32x4 w;
; #pragma unroll
;           for (int j = 0; j < 4; ++j) w[j] = pk2(xn[2 * j], xn[2 * j + 1]);
;           *(u32x4*)(ea.XB + off) = w;
;         }
;       }
;       __syncthreads();
	v_lshlrev_b32_e32 v15, 16, v48
	v_and_b32_e32 v31, 0xffff0000, v48
	v_lshlrev_b32_e32 v46, 16, v49
	v_and_b32_e32 v48, 0xffff0000, v49
	v_lshlrev_b32_e32 v49, 16, v50
	s_waitcnt vmcnt(7)
	v_mov_b32_e32 v52, v92
	v_mov_b32_e32 v53, v93
	v_mov_b32_e32 v54, v94
	v_mov_b32_e32 v55, v95
	v_lshlrev_b32_e32 v13, 16, v52
	v_add_f32_e32 v13, v13, v15
	v_and_b32_e32 v15, 0xffff0000, v52
	v_add_f32_e32 v15, v15, v31
	v_lshlrev_b32_e32 v31, 16, v53
	v_add_f32_e32 v31, v31, v46
	v_and_b32_e32 v46, 0xffff0000, v53
	v_add_f32_e32 v46, v46, v48
	v_lshlrev_b32_e32 v48, 16, v54
	v_add_f32_e32 v52, v48, v49
	v_and_b32_e32 v48, 0xffff0000, v54
	v_and_b32_e32 v49, 0xffff0000, v50
	v_add_f32_e32 v50, v48, v49
	v_lshlrev_b32_e32 v48, 16, v55
	v_lshlrev_b32_e32 v49, 16, v51
	v_add_f32_e32 v53, v48, v49
	v_and_b32_e32 v48, 0xffff0000, v55
	v_and_b32_e32 v49, 0xffff0000, v51
	v_add_f32_e32 v51, v48, v49
	v_cvt_pk_bf16_f32 v48, v13, v15
	v_add_u32_e32 v13, 0x800, v7
	v_ashrrev_i32_e32 v13, 5, v13
	v_add_u32_e32 v54, s53, v13
	v_ashrrev_i32_e32 v55, 31, v54
	v_lshlrev_b64 v[54:55], 11, v[54:55]
	v_cvt_pk_bf16_f32 v49, v31, v46
	v_cvt_pk_bf16_f32 v50, v52, v50
	v_cvt_pk_bf16_f32 v51, v53, v51
	v_lshl_add_u64 v[54:55], s[62:63], 0, v[54:55]
	global_store_dwordx4 v[56:57], v[48:51], off
	v_lshl_add_u64 v[58:59], v[54:55], 0, v[4:5]
	v_mul_lo_u32 v15, v13, s29
	v_add_u32_e32 v49, v6, v15
	ds_read_b128 v[50:53], v49
	s_waitcnt lgkmcnt(0)
	v_lshlrev_b32_e32 v31, 16, v50
	v_and_b32_e32 v46, 0xffff0000, v50
	v_lshlrev_b32_e32 v48, 16, v51
	v_and_b32_e32 v50, 0xffff0000, v51
	v_lshlrev_b32_e32 v51, 16, v52
	s_waitcnt vmcnt(7)
	v_mov_b32_e32 v54, v96
	v_mov_b32_e32 v55, v97
	v_mov_b32_e32 v56, v98
	v_mov_b32_e32 v57, v99
	v_lshlrev_b32_e32 v15, 16, v54
	v_add_f32_e32 v15, v15, v31
	v_and_b32_e32 v31, 0xffff0000, v54
	v_add_f32_e32 v31, v31, v46
	v_lshlrev_b32_e32 v46, 16, v55
	v_add_f32_e32 v46, v46, v48
	v_and_b32_e32 v48, 0xffff0000, v55
	v_add_f32_e32 v48, v48, v50
	v_lshlrev_b32_e32 v50, 16, v56
	v_add_f32_e32 v54, v50, v51
	v_and_b32_e32 v50, 0xffff0000, v56
	v_and_b32_e32 v51, 0xffff0000, v52
	v_add_f32_e32 v52, v50, v51
	v_lshlrev_b32_e32 v50, 16, v57
	v_lshlrev_b32_e32 v51, 16, v53
	v_add_f32_e32 v55, v50, v51
	v_and_b32_e32 v50, 0xffff0000, v57
	v_and_b32_e32 v51, 0xffff0000, v53
	v_add_f32_e32 v53, v50, v51
	v_cvt_pk_bf16_f32 v50, v15, v31
	v_add_u32_e32 v15, 0xa00, v7
	v_ashrrev_i32_e32 v15, 5, v15
	v_cvt_pk_bf16_f32 v52, v54, v52
	v_add_u32_e32 v54, s53, v15
	v_cvt_pk_bf16_f32 v53, v55, v53
	v_ashrrev_i32_e32 v55, 31, v54
	v_lshlrev_b64 v[54:55], 11, v[54:55]
	v_cvt_pk_bf16_f32 v51, v46, v48
	v_lshl_add_u64 v[54:55], s[62:63], 0, v[54:55]
	global_store_dwordx4 v[58:59], v[50:53], off
	v_lshl_add_u64 v[58:59], v[54:55], 0, v[4:5]
	v_mul_lo_u32 v31, v15, s29
	v_add_u32_e32 v48, v6, v31
	ds_read_b128 v[50:53], v48
	s_waitcnt lgkmcnt(0)
	v_lshlrev_b32_e32 v46, 16, v50
	v_and_b32_e32 v50, 0xffff0000, v50
	s_waitcnt vmcnt(7)
	v_mov_b32_e32 v54, v100
	v_mov_b32_e32 v55, v101
	v_mov_b32_e32 v56, v102
	v_mov_b32_e32 v57, v103
	v_lshlrev_b32_e32 v31, 16, v54
	v_add_f32_e32 v31, v31, v46
	v_and_b32_e32 v46, 0xffff0000, v54
	v_add_f32_e32 v46, v46, v50
	v_lshlrev_b32_e32 v50, 16, v55
	v_lshlrev_b32_e32 v54, 16, v51
	v_add_f32_e32 v54, v50, v54
	v_and_b32_e32 v50, 0xffff0000, v55
	v_and_b32_e32 v51, 0xffff0000, v51
	v_add_f32_e32 v51, v50, v51
	v_lshlrev_b32_e32 v50, 16, v56
	v_lshlrev_b32_e32 v55, 16, v52
	v_add_f32_e32 v55, v50, v55
	v_and_b32_e32 v50, 0xffff0000, v56
	v_and_b32_e32 v52, 0xffff0000, v52
	v_add_f32_e32 v52, v50, v52
	v_lshlrev_b32_e32 v50, 16, v57
	v_lshlrev_b32_e32 v56, 16, v53
	v_add_f32_e32 v56, v50, v56
	v_and_b32_e32 v50, 0xffff0000, v57
	v_and_b32_e32 v53, 0xffff0000, v53
	v_add_f32_e32 v53, v50, v53
	v_cvt_pk_bf16_f32 v50, v31, v46
	v_add_u32_e32 v31, 0xc00, v7
	v_ashrrev_i32_e32 v31, 5, v31
	v_cvt_pk_bf16_f32 v53, v56, v53
	v_add_u32_e32 v56, s53, v31
	v_ashrrev_i32_e32 v57, 31, v56
	v_lshlrev_b64 v[56:57], 11, v[56:57]
	v_cvt_pk_bf16_f32 v51, v54, v51
	v_cvt_pk_bf16_f32 v52, v55, v52
	v_lshl_add_u64 v[56:57], s[62:63], 0, v[56:57]
	global_store_dwordx4 v[58:59], v[50:53], off
	v_lshl_add_u64 v[60:61], v[56:57], 0, v[4:5]
	v_mul_lo_u32 v46, v31, s29
	v_add_u32_e32 v51, v6, v46
	ds_read_b128 v[52:55], v51
	v_add_u32_e32 v7, 0xe00, v7
	s_waitcnt lgkmcnt(0)
	v_lshlrev_b32_e32 v50, 16, v52
	v_and_b32_e32 v52, 0xffff0000, v52
	s_waitcnt vmcnt(7)
	v_mov_b32_e32 v56, v104
	v_mov_b32_e32 v57, v105
	v_mov_b32_e32 v58, v106
	v_mov_b32_e32 v59, v107
	v_lshlrev_b32_e32 v46, 16, v56
	v_add_f32_e32 v46, v46, v50
	v_and_b32_e32 v50, 0xffff0000, v56
	v_add_f32_e32 v50, v50, v52
	v_lshlrev_b32_e32 v52, 16, v57
	v_lshlrev_b32_e32 v56, 16, v53
	v_add_f32_e32 v56, v52, v56
	v_and_b32_e32 v52, 0xffff0000, v57
	v_and_b32_e32 v53, 0xffff0000, v53
	v_add_f32_e32 v53, v52, v53
	v_lshlrev_b32_e32 v52, 16, v58
	v_lshlrev_b32_e32 v57, 16, v54
	v_add_f32_e32 v57, v52, v57
	v_and_b32_e32 v52, 0xffff0000, v58
	v_and_b32_e32 v54, 0xffff0000, v54
	v_add_f32_e32 v54, v52, v54
	v_lshlrev_b32_e32 v52, 16, v59
	v_lshlrev_b32_e32 v58, 16, v55
	v_add_f32_e32 v58, v52, v58
	v_and_b32_e32 v52, 0xffff0000, v59
	v_and_b32_e32 v55, 0xffff0000, v55
	v_add_f32_e32 v55, v52, v55
	v_cvt_pk_bf16_f32 v52, v46, v50
	v_ashrrev_i32_e32 v46, 5, v7
	v_mul_lo_u32 v7, v46, s29
	v_add_u32_e32 v50, v6, v7
	v_add_u32_e32 v6, s53, v46
	v_ashrrev_i32_e32 v7, 31, v6
	v_lshlrev_b64 v[6:7], 11, v[6:7]
	v_cvt_pk_bf16_f32 v53, v56, v53
	v_cvt_pk_bf16_f32 v54, v57, v54
	v_cvt_pk_bf16_f32 v55, v58, v55
	v_lshl_add_u64 v[6:7], s[62:63], 0, v[6:7]
	global_store_dwordx4 v[60:61], v[52:55], off
	v_lshl_add_u64 v[6:7], v[6:7], 0, v[4:5]
	ds_read_b128 v[52:55], v50
	s_waitcnt lgkmcnt(0)
	v_lshlrev_b32_e32 v61, 16, v52
	v_and_b32_e32 v52, 0xffff0000, v52
	s_waitcnt vmcnt(7)
	v_mov_b32_e32 v56, v108
	v_mov_b32_e32 v57, v109
	v_mov_b32_e32 v58, v110
	v_mov_b32_e32 v59, v111
	v_lshlrev_b32_e32 v60, 16, v56
	v_and_b32_e32 v56, 0xffff0000, v56
	v_add_f32_e32 v60, v60, v61
	v_add_f32_e32 v52, v56, v52
	v_lshlrev_b32_e32 v56, 16, v57
	v_lshlrev_b32_e32 v61, 16, v53
	v_and_b32_e32 v57, 0xffff0000, v57
	v_and_b32_e32 v53, 0xffff0000, v53
	v_add_f32_e32 v56, v56, v61
	v_add_f32_e32 v53, v57, v53
	v_lshlrev_b32_e32 v57, 16, v58
	v_lshlrev_b32_e32 v61, 16, v54
	v_and_b32_e32 v58, 0xffff0000, v58
	v_and_b32_e32 v54, 0xffff0000, v54
	v_add_f32_e32 v57, v57, v61
	v_add_f32_e32 v54, v58, v54
	v_lshlrev_b32_e32 v58, 16, v59
	v_lshlrev_b32_e32 v61, 16, v55
	v_and_b32_e32 v59, 0xffff0000, v59
	v_and_b32_e32 v55, 0xffff0000, v55
	v_add_f32_e32 v58, v58, v61
	v_add_f32_e32 v55, v59, v55
	v_cvt_pk_bf16_f32 v52, v60, v52
	v_cvt_pk_bf16_f32 v53, v56, v53
	v_cvt_pk_bf16_f32 v54, v57, v54
	v_cvt_pk_bf16_f32 v55, v58, v55
	global_store_dwordx4 v[6:7], v[52:55], off
	s_barrier
; template <int EPI, bool RS>
; DI void gemm_epilogue(unsigned char* smem, f32x16 (&acc)[2][4], const float (&ssq)[4], int K, int m0, int nt256, const EpiArgs& ea, int wt, int wf, int r, int h) {
;     ...
;       if (wt == hf) {
; #pragma unroll
;         for (int tb = 0; tb < 4; ++tb)
; #pragma unroll
;           for (int fb = 0; fb < 2; ++fb)
; #pragma unroll
;             for (int g4 = 0; g4 < 4; ++g4) {
;               u32x2 w; w[0] = pk2(acc[fb][tb][4 * g4], acc[fb][tb][4 * g4 + 1]); w[1] = pk2(acc[fb][tb][4 * g4 + 2], acc[fb][tb][4 * g4 + 3]);
;               *(u32x2*)(es + (tb * 32 + r) * EP + (wf * 64 + fb * 32 + g4 * 8 + 4 * h) * 2) = w;
;             }
;       }
;       __syncthreads();
	s_and_saveexec_b64 s[16:17], s[4:5]
	s_cbranch_execz .LBB0_423
	v_mad_u64_u32 v[6:7], s[0:1], v233, s29, v[228:229]
	v_add_u32_e32 v7, 0x4000, v6
	ds_write2_b64 v6, v[224:225], v[226:227] offset1:2
	ds_write2_b64 v6, v[118:119], v[122:123] offset0:4 offset1:6
	ds_write2_b64 v6, v[114:115], v[120:121] offset0:8 offset1:10
	ds_write2_b64 v6, v[112:113], v[116:117] offset0:12 offset1:14
	ds_write2_b64 v7, v[74:75], v[78:79] offset0:64 offset1:66
	ds_write2_b64 v7, v[70:71], v[76:77] offset0:68 offset1:70
	ds_write2_b64 v7, v[66:67], v[72:73] offset0:72 offset1:74
	ds_write2_b64 v7, v[64:65], v[68:69] offset0:76 offset1:78
	v_add_u32_e32 v7, 0x8000, v6
	v_add_u32_e32 v6, 0xc000, v6
	ds_write2_b64 v7, v[40:41], v[44:45] offset0:128 offset1:130
	ds_write2_b64 v7, v[36:37], v[42:43] offset0:132 offset1:134
	ds_write2_b64 v7, v[34:35], v[38:39] offset0:136 offset1:138
	ds_write2_b64 v7, v[32:33], v[28:29] offset0:140 offset1:142
	ds_write2_b64 v6, v[22:23], v[26:27] offset0:192 offset1:194
	ds_write2_b64 v6, v[18:19], v[24:25] offset0:196 offset1:198
	ds_write2_b64 v6, v[16:17], v[20:21] offset0:200 offset1:202
	ds_write2_b64 v6, v[0:1], v[2:3] offset0:204 offset1:206
	s_branch .LBB0_423

; DI float bflo(unsigned u) { return __uint_as_float(u << 16); }
; DI float bfhi(unsigned u) { return __uint_as_float(u & 0xffff0000u); }
; template <int EPI, bool RS>
; DI void gemm_epilogue(unsigned char* smem, f32x16 (&acc)[2][4], const float (&ssq)[4], int K, int m0, int nt256, const EpiArgs& ea, int wt, int wf, int r, int h) {
;     ...
; #pragma unroll
;       for (int i = 0; i < 8; ++i) {
;         const int c = tid + NTHR * i, row = c >> 5, kc = c & 31;
;         const u32x4 d = *(const u32x4*)(es + row * EP + kc * 16);
;         const size_t off = (size_t)(m0 + hf * 128 + row) * 1024 + nt256 * 256 + kc * 8;
;         const u32x4 xo = *(const u32x4*)(ea.XB + off);
;         float xn[8];
; #pragma unroll
;         for (int j = 0; j < 4; ++j) { xn[2 * j] = bflo(xo[j]) + bflo(d[j]); xn[2 * j + 1] = bfhi(xo[j]) + bfhi(d[j]); }
;         if (ea.X) {
;           f32x4 o0 = {xn[0], xn[1], xn[2], xn[3]}, o1 = {xn[4], xn[5], xn[6], xn[7]};
;           __builtin_nontemporal_store(o0, (f32x4*)(ea.X + off)); __builtin_nontemporal_store(o1, (f32x4*)(ea.X + off + 4));
;         } else {
;           u32x4 w;
; #pragma unroll
;           for (int j = 0; j < 4; ++j) w[j] = pk2(xn[2 * j], xn[2 * j + 1]);
;           *(u32x4*)(ea.XB + off) = w;
;         }
;       }
.LBB0_585:
	s_or_b64 exec, exec, s[12:13]
	s_add_i32 s1, s46, 0x80
	v_add_u32_e32 v6, s1, v8
	v_ashrrev_i32_e32 v7, 31, v6
	v_lshlrev_b64 v[6:7], 11, v[6:7]
	v_lshl_add_u64 v[6:7], s[62:63], 0, v[6:7]
	v_lshl_add_u64 v[16:17], v[6:7], 0, v[4:5]
	s_mov_b64 s[100:101], 0x8000
	global_load_dwordx4 v[20:23], v[16:17], off
	v_lshl_add_u64 v[28:29], v[16:17], 0, s[100:101]
	global_load_dwordx4 v[24:27], v[28:29], off
	v_lshl_add_u64 v[28:29], v[28:29], 0, s[100:101]
	global_load_dwordx4 v[32:35], v[28:29], off
	v_lshl_add_u64 v[28:29], v[28:29], 0, s[100:101]
	global_load_dwordx4 v[36:39], v[28:29], off
	v_lshl_add_u64 v[28:29], v[28:29], 0, s[100:101]
	global_load_dwordx4 v[40:43], v[28:29], off
	v_lshl_add_u64 v[28:29], v[28:29], 0, s[100:101]
	global_load_dwordx4 v[52:55], v[28:29], off
	v_lshl_add_u64 v[28:29], v[28:29], 0, s[100:101]
	global_load_dwordx4 v[56:59], v[28:29], off
	v_lshl_add_u64 v[28:29], v[28:29], 0, s[100:101]
	global_load_dwordx4 v[60:63], v[28:29], off
	s_waitcnt lgkmcnt(0)
	s_barrier
	ds_read_b128 v[0:3], v9
	s_mov_b64 s[16:17], 0
	s_and_b64 vcc, exec, s[6:7]
	s_mov_b32 s33, s37
	s_waitcnt lgkmcnt(0)
	v_lshlrev_b32_e32 v19, 16, v0
	v_and_b32_e32 v0, 0xffff0000, v0
	s_mov_b64 s[14:15], s[10:11]
	s_mov_b64 s[12:13], s[8:9]
	s_mov_b32 s46, s0
	s_waitcnt vmcnt(7)
	v_mov_b32_e32 v6, v20
	v_mov_b32_e32 v7, v21
	v_mov_b32_e32 v8, v22
	v_mov_b32_e32 v9, v23
	v_lshlrev_b32_e32 v18, 16, v6
	v_and_b32_e32 v6, 0xffff0000, v6
	v_add_f32_e32 v18, v18, v19
	v_add_f32_e32 v0, v6, v0
	v_lshlrev_b32_e32 v6, 16, v7
	v_lshlrev_b32_e32 v19, 16, v1
	v_and_b32_e32 v7, 0xffff0000, v7
	v_and_b32_e32 v1, 0xffff0000, v1
	v_add_f32_e32 v6, v6, v19
	v_add_f32_e32 v1, v7, v1
	v_lshlrev_b32_e32 v7, 16, v8
	v_lshlrev_b32_e32 v19, 16, v2
	v_and_b32_e32 v8, 0xffff0000, v8
	v_and_b32_e32 v2, 0xffff0000, v2
	v_add_f32_e32 v7, v7, v19
	v_add_f32_e32 v2, v8, v2
	v_cvt_pk_bf16_f32 v1, v6, v1
	v_add_u32_e32 v6, s1, v10
	v_lshlrev_b32_e32 v8, 16, v9
	v_lshlrev_b32_e32 v19, 16, v3
	v_and_b32_e32 v9, 0xffff0000, v9
	v_and_b32_e32 v3, 0xffff0000, v3
	v_cvt_pk_bf16_f32 v2, v7, v2
	v_ashrrev_i32_e32 v7, 31, v6
	v_add_f32_e32 v8, v8, v19
	v_add_f32_e32 v3, v9, v3
	v_lshlrev_b64 v[6:7], 11, v[6:7]
	v_cvt_pk_bf16_f32 v0, v18, v0
	v_cvt_pk_bf16_f32 v3, v8, v3
	v_lshl_add_u64 v[6:7], s[62:63], 0, v[6:7]
	global_store_dwordx4 v[16:17], v[0:3], off
	v_lshl_add_u64 v[16:17], v[6:7], 0, v[4:5]
	ds_read_b128 v[0:3], v14
	s_waitcnt lgkmcnt(0)
	v_lshlrev_b32_e32 v14, 16, v0
	v_and_b32_e32 v0, 0xffff0000, v0
	s_waitcnt vmcnt(7)
	v_mov_b32_e32 v6, v24
	v_mov_b32_e32 v7, v25
	v_mov_b32_e32 v8, v26
	v_mov_b32_e32 v9, v27
	v_lshlrev_b32_e32 v10, 16, v6
	v_and_b32_e32 v6, 0xffff0000, v6
	v_add_f32_e32 v10, v10, v14
	v_add_f32_e32 v0, v6, v0
	v_lshlrev_b32_e32 v6, 16, v7
	v_lshlrev_b32_e32 v14, 16, v1
	v_and_b32_e32 v7, 0xffff0000, v7
	v_and_b32_e32 v1, 0xffff0000, v1
	v_add_f32_e32 v6, v6, v14
	v_add_f32_e32 v1, v7, v1
	v_lshlrev_b32_e32 v7, 16, v8
	v_lshlrev_b32_e32 v14, 16, v2
	v_and_b32_e32 v8, 0xffff0000, v8
	v_and_b32_e32 v2, 0xffff0000, v2
	v_add_f32_e32 v7, v7, v14
	v_add_f32_e32 v2, v8, v2
	v_cvt_pk_bf16_f32 v1, v6, v1
	v_add_u32_e32 v6, s1, v11
	v_lshlrev_b32_e32 v8, 16, v9
	v_lshlrev_b32_e32 v14, 16, v3
	v_and_b32_e32 v9, 0xffff0000, v9
	v_and_b32_e32 v3, 0xffff0000, v3
	v_cvt_pk_bf16_f32 v2, v7, v2
	v_ashrrev_i32_e32 v7, 31, v6
	v_add_f32_e32 v8, v8, v14
	v_add_f32_e32 v3, v9, v3
	v_lshlrev_b64 v[6:7], 11, v[6:7]
	v_cvt_pk_bf16_f32 v0, v10, v0
	v_cvt_pk_bf16_f32 v3, v8, v3
	v_lshl_add_u64 v[6:7], s[62:63], 0, v[6:7]
	global_store_dwordx4 v[16:17], v[0:3], off
	v_lshl_add_u64 v[10:11], v[6:7], 0, v[4:5]
	ds_read_b128 v[0:3], v47
	s_waitcnt lgkmcnt(0)
	v_lshlrev_b32_e32 v16, 16, v0
	v_and_b32_e32 v0, 0xffff0000, v0
	s_waitcnt vmcnt(7)
	v_mov_b32_e32 v6, v32
	v_mov_b32_e32 v7, v33
	v_mov_b32_e32 v8, v34
	v_mov_b32_e32 v9, v35
	v_lshlrev_b32_e32 v14, 16, v6
	v_and_b32_e32 v6, 0xffff0000, v6
	v_add_f32_e32 v14, v14, v16
	v_add_f32_e32 v0, v6, v0
	v_lshlrev_b32_e32 v6, 16, v7
	v_lshlrev_b32_e32 v16, 16, v1
	v_and_b32_e32 v7, 0xffff0000, v7
	v_and_b32_e32 v1, 0xffff0000, v1
	v_add_f32_e32 v6, v6, v16
	v_add_f32_e32 v1, v7, v1
	v_lshlrev_b32_e32 v7, 16, v8
	v_lshlrev_b32_e32 v16, 16, v2
	v_and_b32_e32 v8, 0xffff0000, v8
	v_and_b32_e32 v2, 0xffff0000, v2
	v_add_f32_e32 v7, v7, v16
	v_add_f32_e32 v2, v8, v2
	v_cvt_pk_bf16_f32 v1, v6, v1
	v_add_u32_e32 v6, s1, v12
	v_lshlrev_b32_e32 v8, 16, v9
	v_lshlrev_b32_e32 v16, 16, v3
	v_and_b32_e32 v9, 0xffff0000, v9
	v_and_b32_e32 v3, 0xffff0000, v3
	v_cvt_pk_bf16_f32 v2, v7, v2
	v_ashrrev_i32_e32 v7, 31, v6
	v_add_f32_e32 v8, v8, v16
	v_add_f32_e32 v3, v9, v3
	v_lshlrev_b64 v[6:7], 11, v[6:7]
	v_cvt_pk_bf16_f32 v0, v14, v0
	v_cvt_pk_bf16_f32 v3, v8, v3
	v_lshl_add_u64 v[6:7], s[62:63], 0, v[6:7]
	global_store_dwordx4 v[10:11], v[0:3], off
	v_lshl_add_u64 v[10:11], v[6:7], 0, v[4:5]
	ds_read_b128 v[0:3], v30
	s_waitcnt lgkmcnt(0)
	v_lshlrev_b32_e32 v14, 16, v0
	v_and_b32_e32 v0, 0xffff0000, v0
	s_waitcnt vmcnt(7)
; DI float bflo(unsigned u) { return __uint_as_float(u << 16); }
; DI float bfhi(unsigned u) { return __uint_as_float(u & 0xffff0000u); }
; template <int EPI, bool RS>
; DI void gemm_epilogue(unsigned char* smem, f32x16 (&acc)[2][4], const float (&ssq)[4], int K, int m0, int nt256, const EpiArgs& ea, int wt, int wf, int r, int h) {
;     ...
; #pragma unroll
;       for (int i = 0; i < 8; ++i) {
;         const int c = tid + NTHR * i, row = c >> 5, kc = c & 31;
;         const u32x4 d = *(const u32x4*)(es + row * EP + kc * 16);
;         const size_t off = (size_t)(m0 + hf * 128 + row) * 1024 + nt256 * 256 + kc * 8;
;         const u32x4 xo = *(const u32x4*)(ea.XB + off);
;         float xn[8];
; #pragma unroll
;         for (int j = 0; j < 4; ++j) { xn[2 * j] = bflo(xo[j]) + bflo(d[j]); xn[2 * j + 1] = bfhi(xo[j]) + bfhi(d[j]); }
;         if (ea.X) {
;           f32x4 o0 = {xn[0], xn[1], xn[2], xn[3]}, o1 = {xn[4], xn[5], xn[6], xn[7]};
;           __builtin_nontemporal_store(o0, (f32x4*)(ea.X + off)); __builtin_nontemporal_store(o1, (f32x4*)(ea.X + off + 4));
;         } else {
;           u32x4 w;
; #pragma unroll
;           for (int j = 0; j < 4; ++j) w[j] = pk2(xn[2 * j], xn[2 * j + 1]);
;           *(u32x4*)(ea.XB + off) = w;
;         }
;       }
	v_mov_b32_e32 v6, v36
	v_mov_b32_e32 v7, v37
	v_mov_b32_e32 v8, v38
	v_mov_b32_e32 v9, v39
	v_lshlrev_b32_e32 v12, 16, v6
	v_and_b32_e32 v6, 0xffff0000, v6
	v_add_f32_e32 v12, v12, v14
	v_add_f32_e32 v0, v6, v0
	v_lshlrev_b32_e32 v6, 16, v7
	v_lshlrev_b32_e32 v14, 16, v1
	v_and_b32_e32 v7, 0xffff0000, v7
	v_and_b32_e32 v1, 0xffff0000, v1
	v_add_f32_e32 v6, v6, v14
	v_add_f32_e32 v1, v7, v1
	v_lshlrev_b32_e32 v7, 16, v8
	v_lshlrev_b32_e32 v14, 16, v2
	v_and_b32_e32 v8, 0xffff0000, v8
	v_and_b32_e32 v2, 0xffff0000, v2
	v_add_f32_e32 v7, v7, v14
	v_add_f32_e32 v2, v8, v2
	v_cvt_pk_bf16_f32 v1, v6, v1
	v_add_u32_e32 v6, s1, v13
	v_lshlrev_b32_e32 v8, 16, v9
	v_lshlrev_b32_e32 v14, 16, v3
	v_and_b32_e32 v9, 0xffff0000, v9
	v_and_b32_e32 v3, 0xffff0000, v3
	v_cvt_pk_bf16_f32 v2, v7, v2
	v_ashrrev_i32_e32 v7, 31, v6
	v_add_f32_e32 v8, v8, v14
	v_add_f32_e32 v3, v9, v3
	v_lshlrev_b64 v[6:7], 11, v[6:7]
	v_cvt_pk_bf16_f32 v0, v12, v0
	v_cvt_pk_bf16_f32 v3, v8, v3
	v_lshl_add_u64 v[6:7], s[62:63], 0, v[6:7]
	global_store_dwordx4 v[10:11], v[0:3], off
	v_lshl_add_u64 v[10:11], v[6:7], 0, v[4:5]
	ds_read_b128 v[0:3], v49
	s_waitcnt lgkmcnt(0)
	v_lshlrev_b32_e32 v13, 16, v0
	v_and_b32_e32 v0, 0xffff0000, v0
	s_waitcnt vmcnt(7)
	v_mov_b32_e32 v6, v40
	v_mov_b32_e32 v7, v41
	v_mov_b32_e32 v8, v42
	v_mov_b32_e32 v9, v43
	v_lshlrev_b32_e32 v12, 16, v6
	v_and_b32_e32 v6, 0xffff0000, v6
	v_add_f32_e32 v12, v12, v13
	v_add_f32_e32 v0, v6, v0
	v_lshlrev_b32_e32 v6, 16, v7
	v_lshlrev_b32_e32 v13, 16, v1
	v_and_b32_e32 v7, 0xffff0000, v7
	v_and_b32_e32 v1, 0xffff0000, v1
	v_add_f32_e32 v6, v6, v13
	v_add_f32_e32 v1, v7, v1
	v_lshlrev_b32_e32 v7, 16, v8
	v_lshlrev_b32_e32 v13, 16, v2
	v_and_b32_e32 v8, 0xffff0000, v8
	v_and_b32_e32 v2, 0xffff0000, v2
	v_add_f32_e32 v7, v7, v13
	v_add_f32_e32 v2, v8, v2
	v_cvt_pk_bf16_f32 v1, v6, v1
	v_add_u32_e32 v6, s1, v15
	v_lshlrev_b32_e32 v8, 16, v9
	v_lshlrev_b32_e32 v13, 16, v3
	v_and_b32_e32 v9, 0xffff0000, v9
	v_and_b32_e32 v3, 0xffff0000, v3
	v_cvt_pk_bf16_f32 v2, v7, v2
	v_ashrrev_i32_e32 v7, 31, v6
	v_add_f32_e32 v8, v8, v13
	v_add_f32_e32 v3, v9, v3
	v_lshlrev_b64 v[6:7], 11, v[6:7]
	v_cvt_pk_bf16_f32 v0, v12, v0
	v_cvt_pk_bf16_f32 v3, v8, v3
	v_lshl_add_u64 v[6:7], s[62:63], 0, v[6:7]
	global_store_dwordx4 v[10:11], v[0:3], off
	v_lshl_add_u64 v[10:11], v[6:7], 0, v[4:5]
	ds_read_b128 v[0:3], v48
	s_waitcnt lgkmcnt(0)
	v_lshlrev_b32_e32 v13, 16, v0
	v_and_b32_e32 v0, 0xffff0000, v0
	s_waitcnt vmcnt(7)
	v_mov_b32_e32 v6, v52
	v_mov_b32_e32 v7, v53
	v_mov_b32_e32 v8, v54
	v_mov_b32_e32 v9, v55
	v_lshlrev_b32_e32 v12, 16, v6
	v_and_b32_e32 v6, 0xffff0000, v6
	v_add_f32_e32 v12, v12, v13
	v_add_f32_e32 v0, v6, v0
	v_lshlrev_b32_e32 v6, 16, v7
	v_lshlrev_b32_e32 v13, 16, v1
	v_and_b32_e32 v7, 0xffff0000, v7
	v_and_b32_e32 v1, 0xffff0000, v1
	v_add_f32_e32 v6, v6, v13
	v_add_f32_e32 v1, v7, v1
	v_lshlrev_b32_e32 v7, 16, v8
	v_lshlrev_b32_e32 v13, 16, v2
	v_and_b32_e32 v8, 0xffff0000, v8
	v_and_b32_e32 v2, 0xffff0000, v2
	v_add_f32_e32 v7, v7, v13
	v_add_f32_e32 v2, v8, v2
	v_cvt_pk_bf16_f32 v1, v6, v1
	v_add_u32_e32 v6, s1, v31
	v_lshlrev_b32_e32 v8, 16, v9
	v_lshlrev_b32_e32 v13, 16, v3
	v_and_b32_e32 v9, 0xffff0000, v9
	v_and_b32_e32 v3, 0xffff0000, v3
	v_cvt_pk_bf16_f32 v2, v7, v2
	v_ashrrev_i32_e32 v7, 31, v6
	v_add_f32_e32 v8, v8, v13
	v_add_f32_e32 v3, v9, v3
	v_lshlrev_b64 v[6:7], 11, v[6:7]
	v_cvt_pk_bf16_f32 v0, v12, v0
	v_cvt_pk_bf16_f32 v3, v8, v3
	v_lshl_add_u64 v[6:7], s[62:63], 0, v[6:7]
	global_store_dwordx4 v[10:11], v[0:3], off
	v_lshl_add_u64 v[10:11], v[6:7], 0, v[4:5]
	ds_read_b128 v[0:3], v51
	s_waitcnt lgkmcnt(0)
	v_lshlrev_b32_e32 v13, 16, v0
	v_and_b32_e32 v0, 0xffff0000, v0
	s_waitcnt vmcnt(7)
	v_mov_b32_e32 v6, v56
	v_mov_b32_e32 v7, v57
	v_mov_b32_e32 v8, v58
	v_mov_b32_e32 v9, v59
	v_lshlrev_b32_e32 v12, 16, v6
	v_and_b32_e32 v6, 0xffff0000, v6
	v_add_f32_e32 v12, v12, v13
	v_add_f32_e32 v0, v6, v0
	v_lshlrev_b32_e32 v6, 16, v7
	v_lshlrev_b32_e32 v13, 16, v1
	v_and_b32_e32 v7, 0xffff0000, v7
	v_and_b32_e32 v1, 0xffff0000, v1
	v_add_f32_e32 v6, v6, v13
	v_add_f32_e32 v1, v7, v1
	v_lshlrev_b32_e32 v7, 16, v8
	v_lshlrev_b32_e32 v13, 16, v2
	v_and_b32_e32 v8, 0xffff0000, v8
	v_and_b32_e32 v2, 0xffff0000, v2
	v_add_f32_e32 v7, v7, v13
	v_add_f32_e32 v2, v8, v2
	v_cvt_pk_bf16_f32 v1, v6, v1
	v_add_u32_e32 v6, s1, v46
	v_lshlrev_b32_e32 v8, 16, v9
	v_lshlrev_b32_e32 v13, 16, v3
	v_and_b32_e32 v9, 0xffff0000, v9
	v_and_b32_e32 v3, 0xffff0000, v3
	v_cvt_pk_bf16_f32 v2, v7, v2
	v_ashrrev_i32_e32 v7, 31, v6
	v_add_f32_e32 v8, v8, v13
	v_add_f32_e32 v3, v9, v3
	v_lshlrev_b64 v[6:7], 11, v[6:7]
	v_cvt_pk_bf16_f32 v0, v12, v0
	v_cvt_pk_bf16_f32 v3, v8, v3
	v_lshl_add_u64 v[6:7], s[62:63], 0, v[6:7]
	global_store_dwordx4 v[10:11], v[0:3], off
	v_lshl_add_u64 v[8:9], v[6:7], 0, v[4:5]
	ds_read_b128 v[0:3], v50
	s_waitcnt lgkmcnt(0)
	v_lshlrev_b32_e32 v11, 16, v0
	v_and_b32_e32 v0, 0xffff0000, v0
	s_waitcnt vmcnt(7)
	v_mov_b32_e32 v4, v60
	v_mov_b32_e32 v5, v61
	v_mov_b32_e32 v6, v62
	v_mov_b32_e32 v7, v63
	v_lshlrev_b32_e32 v10, 16, v4
	v_and_b32_e32 v4, 0xffff0000, v4
	v_add_f32_e32 v10, v10, v11
	v_add_f32_e32 v0, v4, v0
	v_lshlrev_b32_e32 v4, 16, v5
	v_lshlrev_b32_e32 v11, 16, v1
	v_and_b32_e32 v5, 0xffff0000, v5
	v_and_b32_e32 v1, 0xffff0000, v1
	v_add_f32_e32 v4, v4, v11
	v_add_f32_e32 v1, v5, v1
	v_lshlrev_b32_e32 v5, 16, v6
	v_lshlrev_b32_e32 v11, 16, v2
	v_and_b32_e32 v6, 0xffff0000, v6
	v_and_b32_e32 v2, 0xffff0000, v2
	v_add_f32_e32 v5, v5, v11
	v_add_f32_e32 v2, v6, v2
	v_lshlrev_b32_e32 v6, 16, v7
	v_lshlrev_b32_e32 v11, 16, v3
	v_and_b32_e32 v7, 0xffff0000, v7
	v_and_b32_e32 v3, 0xffff0000, v3
	v_add_f32_e32 v6, v6, v11
	v_add_f32_e32 v3, v7, v3
	v_cvt_pk_bf16_f32 v0, v10, v0
	v_cvt_pk_bf16_f32 v1, v4, v1
	v_cvt_pk_bf16_f32 v2, v5, v2
	v_cvt_pk_bf16_f32 v3, v6, v3
	global_store_dwordx4 v[8:9], v[0:3], off
	s_barrier
	s_cbranch_vccnz .LBB0_596

; DI float bflo(unsigned u) { return __uint_as_float(u << 16); }
; DI float bfhi(unsigned u) { return __uint_as_float(u & 0xffff0000u); }
; template <int EPI, bool RS>
; DI void gemm_epilogue(unsigned char* smem, f32x16 (&acc)[2][4], const float (&ssq)[4], int K, int m0, int nt256, const EpiArgs& ea, int wt, int wf, int r, int h) {
;     ...
; #pragma unroll
;       for (int i = 0; i < 8; ++i) {
;         const int c = tid + NTHR * i, row = c >> 5, kc = c & 31;
;         const u32x4 d = *(const u32x4*)(es + row * EP + kc * 16);
;         const size_t off = (size_t)(m0 + hf * 128 + row) * 1024 + nt256 * 256 + kc * 8;
;         const u32x4 xo = *(const u32x4*)(ea.XB + off);
;         float xn[8];
; #pragma unroll
;         for (int j = 0; j < 4; ++j) { xn[2 * j] = bflo(xo[j]) + bflo(d[j]); xn[2 * j + 1] = bfhi(xo[j]) + bfhi(d[j]); }
;         if (ea.X) {
;           f32x4 o0 = {xn[0], xn[1], xn[2], xn[3]}, o1 = {xn[4], xn[5], xn[6], xn[7]};
;           __builtin_nontemporal_store(o0, (f32x4*)(ea.X + off)); __builtin_nontemporal_store(o1, (f32x4*)(ea.X + off + 4));
;         } else {
;           u32x4 w;
; #pragma unroll
;           for (int j = 0; j < 4; ++j) w[j] = pk2(xn[2 * j], xn[2 * j + 1]);
;           *(u32x4*)(ea.XB + off) = w;
;         }
;       }
.LBB0_594:
	s_or_b64 exec, exec, s[12:13]
	v_add_u32_e32 v4, v223, v234
	v_lshl_add_u32 v7, v4, 5, v233
	v_ashrrev_i32_e32 v8, 5, v7
	s_lshl_b32 s1, s33, 8
	v_add_u32_e32 v14, s46, v8
	v_and_b32_e32 v4, 31, v233
	s_ashr_i32 s12, s1, 31
	v_ashrrev_i32_e32 v15, 31, v14
	v_lshl_add_u32 v6, v4, 4, s35
	v_lshl_or_b32 v4, v4, 3, s1
	v_mov_b32_e32 v5, s12
	v_lshlrev_b64 v[14:15], 11, v[14:15]
	v_lshl_add_u64 v[14:15], s[62:63], 0, v[14:15]
	v_lshlrev_b64 v[4:5], 1, v[4:5]
	v_lshl_add_u64 v[14:15], v[14:15], 0, v[4:5]
	s_mov_b64 s[100:101], 0x8000
	global_load_dwordx4 v[80:83], v[14:15], off
	v_lshl_add_u64 v[62:63], v[14:15], 0, s[100:101]
	global_load_dwordx4 v[84:87], v[62:63], off
	v_lshl_add_u64 v[62:63], v[62:63], 0, s[100:101]
	global_load_dwordx4 v[88:91], v[62:63], off
	v_lshl_add_u64 v[62:63], v[62:63], 0, s[100:101]
	global_load_dwordx4 v[92:95], v[62:63], off
	v_lshl_add_u64 v[62:63], v[62:63], 0, s[100:101]
	global_load_dwordx4 v[96:99], v[62:63], off
	v_lshl_add_u64 v[62:63], v[62:63], 0, s[100:101]
	global_load_dwordx4 v[100:103], v[62:63], off
	v_lshl_add_u64 v[62:63], v[62:63], 0, s[100:101]
	global_load_dwordx4 v[104:107], v[62:63], off
	v_lshl_add_u64 v[62:63], v[62:63], 0, s[100:101]
	global_load_dwordx4 v[108:111], v[62:63], off
	s_waitcnt lgkmcnt(0)
	s_barrier
	v_mul_lo_u32 v9, v8, s29
	v_add_u32_e32 v9, v6, v9
	ds_read_b128 v[10:13], v9
	s_waitcnt lgkmcnt(0)
	v_lshlrev_b32_e32 v31, 16, v10
	v_and_b32_e32 v10, 0xffff0000, v10
	s_waitcnt vmcnt(7)
	v_mov_b32_e32 v46, v80
	v_mov_b32_e32 v47, v81
	v_mov_b32_e32 v48, v82
	v_mov_b32_e32 v49, v83
	v_lshlrev_b32_e32 v30, 16, v46
	v_add_f32_e32 v30, v30, v31
	v_and_b32_e32 v31, 0xffff0000, v46
	v_add_f32_e32 v10, v31, v10
	v_lshlrev_b32_e32 v31, 16, v47
	v_lshlrev_b32_e32 v46, 16, v11
	v_add_f32_e32 v31, v31, v46
	v_and_b32_e32 v46, 0xffff0000, v47
	v_and_b32_e32 v11, 0xffff0000, v11
	v_add_f32_e32 v11, v46, v11
	v_lshlrev_b32_e32 v46, 16, v48
	v_lshlrev_b32_e32 v47, 16, v12
	v_add_f32_e32 v46, v46, v47
	v_and_b32_e32 v47, 0xffff0000, v48
	v_and_b32_e32 v12, 0xffff0000, v12
	v_add_f32_e32 v12, v47, v12
	v_lshlrev_b32_e32 v47, 16, v49
	v_lshlrev_b32_e32 v48, 16, v13
	v_add_f32_e32 v47, v47, v48
	v_and_b32_e32 v48, 0xffff0000, v49
	v_and_b32_e32 v13, 0xffff0000, v13
	v_add_f32_e32 v13, v48, v13
	v_cvt_pk_bf16_f32 v10, v30, v10
	v_cvt_pk_bf16_f32 v11, v31, v11
	v_cvt_pk_bf16_f32 v12, v46, v12
	v_cvt_pk_bf16_f32 v13, v47, v13
	global_store_dwordx4 v[14:15], v[10:13], off
	s_nop 1
	v_add_u32_e32 v10, 0x200, v7
	v_ashrrev_i32_e32 v10, 5, v10
	v_add_u32_e32 v12, s46, v10
	v_ashrrev_i32_e32 v13, 31, v12
	v_lshlrev_b64 v[12:13], 11, v[12:13]
	v_lshl_add_u64 v[12:13], s[62:63], 0, v[12:13]
	v_lshl_add_u64 v[12:13], v[12:13], 0, v[4:5]
	v_mul_lo_u32 v11, v10, s29
	v_add_u32_e32 v14, v6, v11
	ds_read_b128 v[46:49], v14
	s_waitcnt lgkmcnt(0)
	v_lshlrev_b32_e32 v15, 16, v46
	v_and_b32_e32 v30, 0xffff0000, v46
	v_lshlrev_b32_e32 v31, 16, v47
	v_and_b32_e32 v46, 0xffff0000, v47
	v_lshlrev_b32_e32 v47, 16, v48
	s_waitcnt vmcnt(7)
	v_mov_b32_e32 v50, v84
	v_mov_b32_e32 v51, v85
	v_mov_b32_e32 v52, v86
	v_mov_b32_e32 v53, v87
	v_lshlrev_b32_e32 v11, 16, v50
	v_add_f32_e32 v11, v11, v15
	v_and_b32_e32 v15, 0xffff0000, v50
	v_add_f32_e32 v15, v15, v30
	v_lshlrev_b32_e32 v30, 16, v51
	v_add_f32_e32 v30, v30, v31
	v_and_b32_e32 v31, 0xffff0000, v51
	v_add_f32_e32 v31, v31, v46
	v_lshlrev_b32_e32 v46, 16, v52
	v_add_f32_e32 v50, v46, v47
	v_and_b32_e32 v46, 0xffff0000, v52
	v_and_b32_e32 v47, 0xffff0000, v48
	v_add_f32_e32 v48, v46, v47
	v_lshlrev_b32_e32 v46, 16, v53
	v_lshlrev_b32_e32 v47, 16, v49
	v_add_f32_e32 v51, v46, v47
	v_and_b32_e32 v46, 0xffff0000, v53
	v_and_b32_e32 v47, 0xffff0000, v49
	v_add_f32_e32 v49, v46, v47
	v_cvt_pk_bf16_f32 v46, v11, v15
	v_add_u32_e32 v11, 0x400, v7
	v_cvt_pk_bf16_f32 v47, v30, v31
	v_cvt_pk_bf16_f32 v48, v50, v48
	v_cvt_pk_bf16_f32 v49, v51, v49
	v_ashrrev_i32_e32 v11, 5, v11
	global_store_dwordx4 v[12:13], v[46:49], off
	v_mul_lo_u32 v12, v11, s29
	s_nop 0
	v_add_u32_e32 v47, v6, v12
	v_add_u32_e32 v12, s46, v11
	v_ashrrev_i32_e32 v13, 31, v12
	v_lshlrev_b64 v[12:13], 11, v[12:13]
	v_lshl_add_u64 v[12:13], s[62:63], 0, v[12:13]
	v_lshl_add_u64 v[12:13], v[12:13], 0, v[4:5]
	ds_read_b128 v[48:51], v47
	s_waitcnt lgkmcnt(0)
	v_lshlrev_b32_e32 v30, 16, v48
	v_and_b32_e32 v31, 0xffff0000, v48
	v_lshlrev_b32_e32 v46, 16, v49
	v_and_b32_e32 v48, 0xffff0000, v49
	v_lshlrev_b32_e32 v49, 16, v50
	s_waitcnt vmcnt(7)
	v_mov_b32_e32 v52, v88
	v_mov_b32_e32 v53, v89
	v_mov_b32_e32 v54, v90
	v_mov_b32_e32 v55, v91
	v_lshlrev_b32_e32 v15, 16, v52
	v_add_f32_e32 v15, v15, v30
	v_and_b32_e32 v30, 0xffff0000, v52
	v_add_f32_e32 v30, v30, v31
	v_lshlrev_b32_e32 v31, 16, v53
	v_add_f32_e32 v31, v31, v46
	v_and_b32_e32 v46, 0xffff0000, v53
	v_add_f32_e32 v46, v46, v48
	v_lshlrev_b32_e32 v48, 16, v54
	v_add_f32_e32 v52, v48, v49
	v_and_b32_e32 v48, 0xffff0000, v54
	v_and_b32_e32 v49, 0xffff0000, v50
	v_add_f32_e32 v50, v48, v49
	v_lshlrev_b32_e32 v48, 16, v55
	v_lshlrev_b32_e32 v49, 16, v51
	v_add_f32_e32 v53, v48, v49
	v_and_b32_e32 v48, 0xffff0000, v55
	v_and_b32_e32 v49, 0xffff0000, v51
	v_add_f32_e32 v51, v48, v49
	v_cvt_pk_bf16_f32 v48, v15, v30
	v_cvt_pk_bf16_f32 v49, v31, v46
	v_cvt_pk_bf16_f32 v50, v52, v50
	v_cvt_pk_bf16_f32 v51, v53, v51
	global_store_dwordx4 v[12:13], v[48:51], off
	v_add_u32_e32 v12, 0x600, v7
	v_ashrrev_i32_e32 v12, 5, v12
	v_add_u32_e32 v52, s46, v12
	v_ashrrev_i32_e32 v53, 31, v52
	v_lshlrev_b64 v[52:53], 11, v[52:53]
	v_lshl_add_u64 v[52:53], s[62:63], 0, v[52:53]
	v_lshl_add_u64 v[56:57], v[52:53], 0, v[4:5]
	v_mul_lo_u32 v13, v12, s29
	v_add_u32_e32 v30, v6, v13
	ds_read_b128 v[48:51], v30
	s_waitcnt lgkmcnt(0)
; DI float bflo(unsigned u) { return __uint_as_float(u << 16); }
; DI float bfhi(unsigned u) { return __uint_as_float(u & 0xffff0000u); }
; template <int EPI, bool RS>
; DI void gemm_epilogue(unsigned char* smem, f32x16 (&acc)[2][4], const float (&ssq)[4], int K, int m0, int nt256, const EpiArgs& ea, int wt, int wf, int r, int h) {
;     ...
; #pragma unroll
;       for (int i = 0; i < 8; ++i) {
;         const int c = tid + NTHR * i, row = c >> 5, kc = c & 31;
;         const u32x4 d = *(const u32x4*)(es + row * EP + kc * 16);
;         const size_t off = (size_t)(m0 + hf * 128 + row) * 1024 + nt256 * 256 + kc * 8;
;         const u32x4 xo = *(const u32x4*)(ea.XB + off);
;         float xn[8];
; #pragma unroll
;         for (int j = 0; j < 4; ++j) { xn[2 * j] = bflo(xo[j]) + bflo(d[j]); xn[2 * j + 1] = bfhi(xo[j]) + bfhi(d[j]); }
;         if (ea.X) {
;           f32x4 o0 = {xn[0], xn[1], xn[2], xn[3]}, o1 = {xn[4], xn[5], xn[6], xn[7]};
;           __builtin_nontemporal_store(o0, (f32x4*)(ea.X + off)); __builtin_nontemporal_store(o1, (f32x4*)(ea.X + off + 4));
;         } else {
;           u32x4 w;
; #pragma unroll
;           for (int j = 0; j < 4; ++j) w[j] = pk2(xn[2 * j], xn[2 * j + 1]);
;           *(u32x4*)(ea.XB + off) = w;
;         }
;       }
	v_lshlrev_b32_e32 v15, 16, v48
	v_and_b32_e32 v31, 0xffff0000, v48
	v_lshlrev_b32_e32 v46, 16, v49
	v_and_b32_e32 v48, 0xffff0000, v49
	v_lshlrev_b32_e32 v49, 16, v50
	s_waitcnt vmcnt(7)
	v_mov_b32_e32 v52, v92
	v_mov_b32_e32 v53, v93
	v_mov_b32_e32 v54, v94
	v_mov_b32_e32 v55, v95
	v_lshlrev_b32_e32 v13, 16, v52
	v_add_f32_e32 v13, v13, v15
	v_and_b32_e32 v15, 0xffff0000, v52
	v_add_f32_e32 v15, v15, v31
	v_lshlrev_b32_e32 v31, 16, v53
	v_add_f32_e32 v31, v31, v46
	v_and_b32_e32 v46, 0xffff0000, v53
	v_add_f32_e32 v46, v46, v48
	v_lshlrev_b32_e32 v48, 16, v54
	v_add_f32_e32 v52, v48, v49
	v_and_b32_e32 v48, 0xffff0000, v54
	v_and_b32_e32 v49, 0xffff0000, v50
	v_add_f32_e32 v50, v48, v49
	v_lshlrev_b32_e32 v48, 16, v55
	v_lshlrev_b32_e32 v49, 16, v51
	v_add_f32_e32 v53, v48, v49
	v_and_b32_e32 v48, 0xffff0000, v55
	v_and_b32_e32 v49, 0xffff0000, v51
	v_add_f32_e32 v51, v48, v49
	v_cvt_pk_bf16_f32 v48, v13, v15
	v_add_u32_e32 v13, 0x800, v7
	v_ashrrev_i32_e32 v13, 5, v13
	v_add_u32_e32 v54, s46, v13
	v_ashrrev_i32_e32 v55, 31, v54
	v_lshlrev_b64 v[54:55], 11, v[54:55]
	v_cvt_pk_bf16_f32 v49, v31, v46
	v_cvt_pk_bf16_f32 v50, v52, v50
	v_cvt_pk_bf16_f32 v51, v53, v51
	v_lshl_add_u64 v[54:55], s[62:63], 0, v[54:55]
	global_store_dwordx4 v[56:57], v[48:51], off
	v_lshl_add_u64 v[58:59], v[54:55], 0, v[4:5]
	v_mul_lo_u32 v15, v13, s29
	v_add_u32_e32 v49, v6, v15
	ds_read_b128 v[50:53], v49
	s_waitcnt lgkmcnt(0)
	v_lshlrev_b32_e32 v31, 16, v50
	v_and_b32_e32 v46, 0xffff0000, v50
	v_lshlrev_b32_e32 v48, 16, v51
	v_and_b32_e32 v50, 0xffff0000, v51
	v_lshlrev_b32_e32 v51, 16, v52
	s_waitcnt vmcnt(7)
	v_mov_b32_e32 v54, v96
	v_mov_b32_e32 v55, v97
	v_mov_b32_e32 v56, v98
	v_mov_b32_e32 v57, v99
	v_lshlrev_b32_e32 v15, 16, v54
	v_add_f32_e32 v15, v15, v31
	v_and_b32_e32 v31, 0xffff0000, v54
	v_add_f32_e32 v31, v31, v46
	v_lshlrev_b32_e32 v46, 16, v55
	v_add_f32_e32 v46, v46, v48
	v_and_b32_e32 v48, 0xffff0000, v55
	v_add_f32_e32 v48, v48, v50
	v_lshlrev_b32_e32 v50, 16, v56
	v_add_f32_e32 v54, v50, v51
	v_and_b32_e32 v50, 0xffff0000, v56
	v_and_b32_e32 v51, 0xffff0000, v52
	v_add_f32_e32 v52, v50, v51
	v_lshlrev_b32_e32 v50, 16, v57
	v_lshlrev_b32_e32 v51, 16, v53
	v_add_f32_e32 v55, v50, v51
	v_and_b32_e32 v50, 0xffff0000, v57
	v_and_b32_e32 v51, 0xffff0000, v53
	v_add_f32_e32 v53, v50, v51
	v_cvt_pk_bf16_f32 v50, v15, v31
	v_add_u32_e32 v15, 0xa00, v7
	v_ashrrev_i32_e32 v15, 5, v15
	v_cvt_pk_bf16_f32 v52, v54, v52
	v_add_u32_e32 v54, s46, v15
	v_cvt_pk_bf16_f32 v53, v55, v53
	v_ashrrev_i32_e32 v55, 31, v54
	v_lshlrev_b64 v[54:55], 11, v[54:55]
	v_cvt_pk_bf16_f32 v51, v46, v48
	v_lshl_add_u64 v[54:55], s[62:63], 0, v[54:55]
	global_store_dwordx4 v[58:59], v[50:53], off
	v_lshl_add_u64 v[58:59], v[54:55], 0, v[4:5]
	v_mul_lo_u32 v31, v15, s29
	v_add_u32_e32 v48, v6, v31
	ds_read_b128 v[50:53], v48
	s_waitcnt lgkmcnt(0)
	v_lshlrev_b32_e32 v46, 16, v50
	v_and_b32_e32 v50, 0xffff0000, v50
	s_waitcnt vmcnt(7)
	v_mov_b32_e32 v54, v100
	v_mov_b32_e32 v55, v101
	v_mov_b32_e32 v56, v102
	v_mov_b32_e32 v57, v103
	v_lshlrev_b32_e32 v31, 16, v54
	v_add_f32_e32 v31, v31, v46
	v_and_b32_e32 v46, 0xffff0000, v54
	v_add_f32_e32 v46, v46, v50
	v_lshlrev_b32_e32 v50, 16, v55
	v_lshlrev_b32_e32 v54, 16, v51
	v_add_f32_e32 v54, v50, v54
	v_and_b32_e32 v50, 0xffff0000, v55
	v_and_b32_e32 v51, 0xffff0000, v51
	v_add_f32_e32 v51, v50, v51
	v_lshlrev_b32_e32 v50, 16, v56
	v_lshlrev_b32_e32 v55, 16, v52
	v_add_f32_e32 v55, v50, v55
	v_and_b32_e32 v50, 0xffff0000, v56
	v_and_b32_e32 v52, 0xffff0000, v52
	v_add_f32_e32 v52, v50, v52
	v_lshlrev_b32_e32 v50, 16, v57
	v_lshlrev_b32_e32 v56, 16, v53
	v_add_f32_e32 v56, v50, v56
	v_and_b32_e32 v50, 0xffff0000, v57
	v_and_b32_e32 v53, 0xffff0000, v53
	v_add_f32_e32 v53, v50, v53
	v_cvt_pk_bf16_f32 v50, v31, v46
	v_add_u32_e32 v31, 0xc00, v7
	v_ashrrev_i32_e32 v31, 5, v31
	v_cvt_pk_bf16_f32 v53, v56, v53
	v_add_u32_e32 v56, s46, v31
	v_ashrrev_i32_e32 v57, 31, v56
	v_lshlrev_b64 v[56:57], 11, v[56:57]
	v_cvt_pk_bf16_f32 v51, v54, v51
	v_cvt_pk_bf16_f32 v52, v55, v52
	v_lshl_add_u64 v[56:57], s[62:63], 0, v[56:57]
	global_store_dwordx4 v[58:59], v[50:53], off
	v_lshl_add_u64 v[60:61], v[56:57], 0, v[4:5]
	v_mul_lo_u32 v46, v31, s29
	v_add_u32_e32 v51, v6, v46
	ds_read_b128 v[52:55], v51
	v_add_u32_e32 v7, 0xe00, v7
	s_waitcnt lgkmcnt(0)
	v_lshlrev_b32_e32 v50, 16, v52
	v_and_b32_e32 v52, 0xffff0000, v52
	s_waitcnt vmcnt(7)
	v_mov_b32_e32 v56, v104
	v_mov_b32_e32 v57, v105
	v_mov_b32_e32 v58, v106
	v_mov_b32_e32 v59, v107
	v_lshlrev_b32_e32 v46, 16, v56
	v_add_f32_e32 v46, v46, v50
	v_and_b32_e32 v50, 0xffff0000, v56
	v_add_f32_e32 v50, v50, v52
	v_lshlrev_b32_e32 v52, 16, v57
	v_lshlrev_b32_e32 v56, 16, v53
	v_add_f32_e32 v56, v52, v56
	v_and_b32_e32 v52, 0xffff0000, v57
	v_and_b32_e32 v53, 0xffff0000, v53
	v_add_f32_e32 v53, v52, v53
	v_lshlrev_b32_e32 v52, 16, v58
	v_lshlrev_b32_e32 v57, 16, v54
	v_add_f32_e32 v57, v52, v57
	v_and_b32_e32 v52, 0xffff0000, v58
	v_and_b32_e32 v54, 0xffff0000, v54
	v_add_f32_e32 v54, v52, v54
	v_lshlrev_b32_e32 v52, 16, v59
	v_lshlrev_b32_e32 v58, 16, v55
	v_add_f32_e32 v58, v52, v58
	v_and_b32_e32 v52, 0xffff0000, v59
	v_and_b32_e32 v55, 0xffff0000, v55
	v_add_f32_e32 v55, v52, v55
	v_cvt_pk_bf16_f32 v52, v46, v50
	v_ashrrev_i32_e32 v46, 5, v7
	v_mul_lo_u32 v7, v46, s29
	v_add_u32_e32 v50, v6, v7
	v_add_u32_e32 v6, s46, v46
	v_ashrrev_i32_e32 v7, 31, v6
	v_lshlrev_b64 v[6:7], 11, v[6:7]
	v_cvt_pk_bf16_f32 v53, v56, v53
	v_cvt_pk_bf16_f32 v54, v57, v54
	v_cvt_pk_bf16_f32 v55, v58, v55
	v_lshl_add_u64 v[6:7], s[62:63], 0, v[6:7]
	global_store_dwordx4 v[60:61], v[52:55], off
	v_lshl_add_u64 v[6:7], v[6:7], 0, v[4:5]
	ds_read_b128 v[52:55], v50
	s_waitcnt lgkmcnt(0)
	v_lshlrev_b32_e32 v61, 16, v52
	v_and_b32_e32 v52, 0xffff0000, v52
	s_waitcnt vmcnt(7)
	v_mov_b32_e32 v56, v108
	v_mov_b32_e32 v57, v109
	v_mov_b32_e32 v58, v110
	v_mov_b32_e32 v59, v111
	v_lshlrev_b32_e32 v60, 16, v56
	v_and_b32_e32 v56, 0xffff0000, v56
	v_add_f32_e32 v60, v60, v61
	v_add_f32_e32 v52, v56, v52
	v_lshlrev_b32_e32 v56, 16, v57
	v_lshlrev_b32_e32 v61, 16, v53
	v_and_b32_e32 v57, 0xffff0000, v57
	v_and_b32_e32 v53, 0xffff0000, v53
	v_add_f32_e32 v56, v56, v61
	v_add_f32_e32 v53, v57, v53
	v_lshlrev_b32_e32 v57, 16, v58
	v_lshlrev_b32_e32 v61, 16, v54
	v_and_b32_e32 v58, 0xffff0000, v58
	v_and_b32_e32 v54, 0xffff0000, v54
	v_add_f32_e32 v57, v57, v61
	v_add_f32_e32 v54, v58, v54
	v_lshlrev_b32_e32 v58, 16, v59
	v_lshlrev_b32_e32 v61, 16, v55
	v_and_b32_e32 v59, 0xffff0000, v59
	v_and_b32_e32 v55, 0xffff0000, v55
	v_add_f32_e32 v58, v58, v61
	v_add_f32_e32 v55, v59, v55
	v_cvt_pk_bf16_f32 v52, v60, v52
	v_cvt_pk_bf16_f32 v53, v56, v53
	v_cvt_pk_bf16_f32 v54, v57, v54
	v_cvt_pk_bf16_f32 v55, v58, v55
	global_store_dwordx4 v[6:7], v[52:55], off
	s_barrier
; template <int EPI, bool RS>
; DI void gemm_epilogue(unsigned char* smem, f32x16 (&acc)[2][4], const float (&ssq)[4], int K, int m0, int nt256, const EpiArgs& ea, int wt, int wf, int r, int h) {
;     ...
;       if (wt == hf) {
; #pragma unroll
;         for (int tb = 0; tb < 4; ++tb)
; #pragma unroll
;           for (int fb = 0; fb < 2; ++fb)
; #pragma unroll
;             for (int g4 = 0; g4 < 4; ++g4) {
;               u32x2 w; w[0] = pk2(acc[fb][tb][4 * g4], acc[fb][tb][4 * g4 + 1]); w[1] = pk2(acc[fb][tb][4 * g4 + 2], acc[fb][tb][4 * g4 + 3]);
;               *(u32x2*)(es + (tb * 32 + r) * EP + (wf * 64 + fb * 32 + g4 * 8 + 4 * h) * 2) = w;
;             }
	s_and_saveexec_b64 s[12:13], s[4:5]
	s_cbranch_execz .LBB0_585
	v_mad_u64_u32 v[6:7], s[14:15], v233, s29, v[228:229]
	v_add_u32_e32 v7, 0x4000, v6
	ds_write2_b64 v6, v[224:225], v[226:227] offset1:2
	ds_write2_b64 v6, v[118:119], v[122:123] offset0:4 offset1:6
	ds_write2_b64 v6, v[114:115], v[120:121] offset0:8 offset1:10
	ds_write2_b64 v6, v[112:113], v[116:117] offset0:12 offset1:14
	ds_write2_b64 v7, v[74:75], v[78:79] offset0:64 offset1:66
	ds_write2_b64 v7, v[70:71], v[76:77] offset0:68 offset1:70
	ds_write2_b64 v7, v[66:67], v[72:73] offset0:72 offset1:74
	ds_write2_b64 v7, v[64:65], v[68:69] offset0:76 offset1:78
	v_add_u32_e32 v7, 0x8000, v6
	v_add_u32_e32 v6, 0xc000, v6
	ds_write2_b64 v7, v[40:41], v[44:45] offset0:128 offset1:130
	ds_write2_b64 v7, v[36:37], v[42:43] offset0:132 offset1:134
	ds_write2_b64 v7, v[34:35], v[38:39] offset0:136 offset1:138
	ds_write2_b64 v7, v[32:33], v[28:29] offset0:140 offset1:142
	ds_write2_b64 v6, v[22:23], v[26:27] offset0:192 offset1:194
	ds_write2_b64 v6, v[18:19], v[24:25] offset0:196 offset1:198
	ds_write2_b64 v6, v[16:17], v[20:21] offset0:200 offset1:202
	ds_write2_b64 v6, v[0:1], v[2:3] offset0:204 offset1:206
	s_branch .LBB0_585

	.amdhsa_kernel _Z6k_mega1P
		.amdhsa_group_segment_fixed_size 8192
		.amdhsa_private_segment_fixed_size 0
		.amdhsa_kernarg_size 528
		.amdhsa_user_sgpr_count 2
		.amdhsa_user_sgpr_dispatch_ptr 0
		.amdhsa_user_sgpr_queue_ptr 0
		.amdhsa_user_sgpr_kernarg_segment_ptr 1
		.amdhsa_user_sgpr_dispatch_id 0
		.amdhsa_user_sgpr_kernarg_preload_length 0
		.amdhsa_user_sgpr_kernarg_preload_offset 0
		.amdhsa_user_sgpr_private_segment_size 0
		.amdhsa_uses_dynamic_stack 0
		.amdhsa_enable_private_segment 0
		.amdhsa_system_sgpr_workgroup_id_x 1
		.amdhsa_system_sgpr_workgroup_id_y 0
		.amdhsa_system_sgpr_workgroup_id_z 0
		.amdhsa_system_sgpr_workgroup_info 0
		.amdhsa_system_vgpr_workitem_id 2
		.amdhsa_next_free_vgpr 256
		.amdhsa_next_free_sgpr 102
		.amdhsa_accum_offset 256
		.amdhsa_reserve_vcc 1
		.amdhsa_float_round_mode_32 0
		.amdhsa_float_round_mode_16_64 0
		.amdhsa_float_denorm_mode_32 3
		.amdhsa_float_denorm_mode_16_64 3
		.amdhsa_dx10_clamp 1
		.amdhsa_ieee_mode 1
		.amdhsa_fp16_overflow 0
		.amdhsa_tg_split 0
		.amdhsa_exception_fp_ieee_invalid_op 0
		.amdhsa_exception_fp_denorm_src 0
		.amdhsa_exception_fp_ieee_div_zero 0
		.amdhsa_exception_fp_ieee_overflow 0
		.amdhsa_exception_fp_ieee_underflow 0
		.amdhsa_exception_fp_ieee_inexact 0
		.amdhsa_exception_int_div_zero 0
	.end_amdhsa_kernel

amdhsa.kernels:
  - .agpr_count:     0
    .args:
      - .offset:         0
        .size:           272
        .value_kind:     by_value
      - .offset:         272
        .size:           4
        .value_kind:     hidden_block_count_x
      - .offset:         276
        .size:           4
        .value_kind:     hidden_block_count_y
      - .offset:         280
        .size:           4
        .value_kind:     hidden_block_count_z
      - .offset:         284
        .size:           2
        .value_kind:     hidden_group_size_x
      - .offset:         286
        .size:           2
        .value_kind:     hidden_group_size_y
      - .offset:         288
        .size:           2
        .value_kind:     hidden_group_size_z
      - .offset:         290
        .size:           2
        .value_kind:     hidden_remainder_x
      - .offset:         292
        .size:           2
        .value_kind:     hidden_remainder_y
      - .offset:         294
        .size:           2
        .value_kind:     hidden_remainder_z
      - .offset:         312
        .size:           8
        .value_kind:     hidden_global_offset_x
      - .offset:         320
        .size:           8
        .value_kind:     hidden_global_offset_y
      - .offset:         328
        .size:           8
        .value_kind:     hidden_global_offset_z
      - .offset:         336
        .size:           2
        .value_kind:     hidden_grid_dims
      - .offset:         360
        .size:           8
        .value_kind:     hidden_multigrid_sync_arg
      - .offset:         392
        .size:           4
        .value_kind:     hidden_dynamic_lds_size
    .group_segment_fixed_size: 8192
    .kernarg_segment_align: 8
    .kernarg_segment_size: 528
    .language:       OpenCL C
    .language_version:
      - 2
      - 0
    .max_flat_workgroup_size: 512
    .name:           _Z6k_mega1P
    .private_segment_fixed_size: 0
    .sgpr_count:     106
    .sgpr_spill_count: 81
    .symbol:         _Z6k_mega1P.kd
    .uniform_work_group_size: 1
    .uses_dynamic_stack: false
    .vgpr_count:     256
    .vgpr_spill_count: 0
    .wavefront_size: 64
